# K-loops: post-MFMA barrier executed 3 MFMAs early (partner group release overlaps the MFMA tail); setprio flips + duplicate lgkmcnt removed
# baseline (speedup 1.0000x reference)
; #define PG8_STAGE(bufoff, gbase, voff) do { _Pragma("unroll") for (int _i = 0; _i < 2; ++_i) \
;         __builtin_amdgcn_global_load_lds((const unsigned*)((const char*)(gbase) + (voff)[_i]), (LAS unsigned*)(lds + (bufoff) + ldsw + _i * 8192), 16, 0, 0); } while (0)
; #define PG8_LDA(dst, b, h) do { _Pragma("unroll") for (int m = 0; m < 4; ++m) _Pragma("unroll") for (int k = 0; k < 2; ++k) dst[m][k] = *(const LAS bf16x8*)(lds + PG8_SA(b, h) + aoff + m * 2048 + k * 1024); } while (0)
; #define PG8_LDB(dst, b, h) do { _Pragma("unroll") for (int n = 0; n < 2; ++n) _Pragma("unroll") for (int k = 0; k < 2; ++k) dst[n][k] = *(const LAS bf16x8*)(lds + PG8_SB(b, h) + boff + n * 2048 + k * 1024); } while (0)
; #define PG8_MMA(ai, bj, At, Bt) do { __builtin_amdgcn_s_setprio(1); _Pragma("unroll") for (int m = 0; m < 4; ++m) _Pragma("unroll") for (int n = 0; n < 2; ++n) _Pragma("unroll") for (int k = 0; k < 2; ++k) \
;         acc[ai][bj][m][n] = __builtin_amdgcn_mfma_f32_16x16x32_bf16(Bt[n][k], At[m][k], acc[ai][bj][m][n], 0, 0, 0); __builtin_amdgcn_s_setprio(0); } while (0)
; #define PG8_WAIT_V(n) asm volatile("s_waitcnt vmcnt(" #n ")" ::: "memory")
; #define PG8_WAIT_L(n) asm volatile("s_waitcnt lgkmcnt(" #n ")" ::: "memory")
; #define PG8_BAR __builtin_amdgcn_s_barrier()
; template <int MODE, class EpiT, class Sched>
; __device__ __forceinline__ void gemm_phase(LAS unsigned char* lds, const Gemm g, const Sched& S, const EpiT& E) {
;     ...
;             const bool last = (t == nt - 2);
;             const char* a1 = cA + (size_t)(t + 1) * kstep;
;             const char* a2 = last ? nA : cA + (size_t)(t + 2) * kstep; const char* b2 = last ? nB : cB + (size_t)(t + 2) * kstep;
;             const char* a3 = a2 + kstep; const char* b3 = b2 + kstep;
;             PG8_LDB(B0, 0, 0); PG8_SCHED; PG8_LDA(At, 0, 0); PG8_STAGE(PG8_SA(1, 1), a1 + hstep, voffA);
;             PG8_WAIT_L(8); PG8_BAR; PG8_WAIT_L(0); PG8_MMA(0, 0, At, B0); PG8_BAR; PG8_SCHED;
;             PG8_LDB(B1, 0, 1); PG8_STAGE(PG8_SB(0, 0), b2, voffB);
;             PG8_BAR; PG8_WAIT_L(0); PG8_MMA(0, 1, At, B1); PG8_BAR;
;             PG8_LDA(At, 0, 1); PG8_STAGE(PG8_SA(0, 0), a2, voffA);
;             PG8_BAR; PG8_WAIT_L(0); PG8_MMA(1, 0, At, B0); PG8_BAR; PG8_SCHED;
;             PG8_STAGE(PG8_SB(0, 1), b2 + hstep, voffB);
;             PG8_WAIT_V(6); PG8_BAR; PG8_MMA(1, 1, At, B1); PG8_BAR;
.LBB0_115:
	s_add_i32 s58, s52, 2
	s_add_u32 s59, s44, 0x80
	s_addc_u32 s53, s45, 0
	s_add_i32 s91, 0, 0x10000
	v_add_u32_e32 v86, s91, v192
	ds_read_b128 v[70:73], v86
	ds_read_b128 v[74:77], v86 offset:1024
	ds_read_b128 v[82:85], v86 offset:2048
	ds_read_b128 v[86:89], v86 offset:3072
	s_cmp_eq_u32 s57, s52
	s_cselect_b32 s52, s4, s59
	s_cselect_b32 s53, s5, s53
	s_cselect_b32 s75, s47, vcc_hi
	s_cselect_b32 s74, s46, vcc_lo
	v_lshl_add_u64 v[188:189], s[44:45], 0, v[176:177]
	s_add_i32 m0, s20, 0xc000
	ds_read_b128 v[138:141], v194
	ds_read_b128 v[142:145], v194 offset:1024
	ds_read_b128 v[146:149], v194 offset:2048
	ds_read_b128 v[154:157], v194 offset:3072
	ds_read_b128 v[162:165], v194 offset:4096
	ds_read_b128 v[166:169], v194 offset:5120
	ds_read_b128 v[170:173], v194 offset:6144
	ds_read_b128 v[184:187], v194 offset:7168
	global_load_lds_dwordx4 v[188:189], off
	v_lshl_add_u64 v[188:189], s[44:45], 0, v[182:183]
	s_add_i32 m0, s20, 0xe000
	s_nop 0
	global_load_lds_dwordx4 v[188:189], off
	s_waitcnt lgkmcnt(8)
	s_barrier
	s_waitcnt lgkmcnt(0)
	v_mfma_f32_16x16x32_bf16 v[158:161], v[70:73], v[138:141], v[158:161]
	v_mfma_f32_16x16x32_bf16 v[150:153], v[82:85], v[138:141], v[150:153]
	v_mfma_f32_16x16x32_bf16 v[126:129], v[70:73], v[146:149], v[126:129]
	v_mfma_f32_16x16x32_bf16 v[122:125], v[82:85], v[146:149], v[122:125]
	v_mfma_f32_16x16x32_bf16 v[110:113], v[70:73], v[162:165], v[110:113]
	v_mfma_f32_16x16x32_bf16 v[106:109], v[82:85], v[162:165], v[106:109]
	v_mfma_f32_16x16x32_bf16 v[94:97], v[70:73], v[170:173], v[94:97]
	v_mfma_f32_16x16x32_bf16 v[90:93], v[82:85], v[170:173], v[90:93]
	v_mfma_f32_16x16x32_bf16 v[158:161], v[74:77], v[142:145], v[158:161]
	v_mfma_f32_16x16x32_bf16 v[150:153], v[86:89], v[142:145], v[150:153]
	v_mfma_f32_16x16x32_bf16 v[126:129], v[74:77], v[154:157], v[126:129]
	v_mfma_f32_16x16x32_bf16 v[122:125], v[86:89], v[154:157], v[122:125]
	v_mfma_f32_16x16x32_bf16 v[110:113], v[74:77], v[166:169], v[110:113]
	s_barrier
	v_mfma_f32_16x16x32_bf16 v[106:109], v[86:89], v[166:169], v[106:109]
	v_mfma_f32_16x16x32_bf16 v[94:97], v[74:77], v[184:187], v[94:97]
	v_mfma_f32_16x16x32_bf16 v[90:93], v[86:89], v[184:187], v[90:93]
	s_add_i32 s59, 0, 0x14000
	s_add_i32 s91, s91, s9
	v_add_u32_e32 v195, s59, v192
	v_lshl_add_u64 v[228:229], s[74:75], 0, v[0:1]
	s_mov_b32 m0, s91
	ds_read_b128 v[188:191], v195
	ds_read_b128 v[196:199], v195 offset:1024
	ds_read_b128 v[220:223], v195 offset:2048
	ds_read_b128 v[224:227], v195 offset:3072
	global_load_lds_dwordx4 v[228:229], off
	v_lshl_add_u64 v[230:231], s[74:75], 0, v[174:175]
	s_add_i32 m0, s91, 0x2000
	s_nop 0
	global_load_lds_dwordx4 v[230:231], off
	s_barrier
	s_waitcnt lgkmcnt(0)
	v_mfma_f32_16x16x32_bf16 v[134:137], v[188:191], v[138:141], v[134:137]
	v_mfma_f32_16x16x32_bf16 v[130:133], v[220:223], v[138:141], v[130:133]
	v_mfma_f32_16x16x32_bf16 v[118:121], v[188:191], v[146:149], v[118:121]
	v_mfma_f32_16x16x32_bf16 v[114:117], v[220:223], v[146:149], v[114:117]
	v_mfma_f32_16x16x32_bf16 v[102:105], v[188:191], v[162:165], v[102:105]
	v_mfma_f32_16x16x32_bf16 v[98:101], v[220:223], v[162:165], v[98:101]
	v_mfma_f32_16x16x32_bf16 v[78:81], v[188:191], v[170:173], v[78:81]
	v_mfma_f32_16x16x32_bf16 v[66:69], v[220:223], v[170:173], v[66:69]
	v_mfma_f32_16x16x32_bf16 v[134:137], v[196:199], v[142:145], v[134:137]
	v_mfma_f32_16x16x32_bf16 v[130:133], v[224:227], v[142:145], v[130:133]
	v_mfma_f32_16x16x32_bf16 v[118:121], v[196:199], v[154:157], v[118:121]
	v_mfma_f32_16x16x32_bf16 v[114:117], v[224:227], v[154:157], v[114:117]
	v_mfma_f32_16x16x32_bf16 v[102:105], v[196:199], v[166:169], v[102:105]
	s_barrier
	v_mfma_f32_16x16x32_bf16 v[98:101], v[224:227], v[166:169], v[98:101]
	v_mfma_f32_16x16x32_bf16 v[78:81], v[196:199], v[184:187], v[78:81]
	v_mfma_f32_16x16x32_bf16 v[66:69], v[224:227], v[184:187], v[66:69]
	s_mov_b32 m0, s20
	v_lshl_add_u64 v[232:233], s[52:53], 0, v[0:1]
	ds_read_b128 v[138:141], v194 offset:16384
	ds_read_b128 v[142:145], v194 offset:17408
	ds_read_b128 v[146:149], v194 offset:18432
	ds_read_b128 v[154:157], v194 offset:19456
	ds_read_b128 v[162:165], v194 offset:20480
	ds_read_b128 v[166:169], v194 offset:21504
	ds_read_b128 v[170:173], v194 offset:22528
	ds_read_b128 v[184:187], v194 offset:23552
	global_load_lds_dwordx4 v[232:233], off
	v_lshl_add_u64 v[234:235], s[52:53], 0, v[174:175]
	s_mov_b32 m0, s21
	s_nop 0
	global_load_lds_dwordx4 v[234:235], off
	s_barrier
	s_waitcnt lgkmcnt(0)
	v_mfma_f32_16x16x32_bf16 v[62:65], v[70:73], v[138:141], v[62:65]
	v_mfma_f32_16x16x32_bf16 v[58:61], v[82:85], v[138:141], v[58:61]
	v_mfma_f32_16x16x32_bf16 v[46:49], v[70:73], v[146:149], v[46:49]
	v_mfma_f32_16x16x32_bf16 v[42:45], v[82:85], v[146:149], v[42:45]
	v_mfma_f32_16x16x32_bf16 v[30:33], v[70:73], v[162:165], v[30:33]
	v_mfma_f32_16x16x32_bf16 v[26:29], v[82:85], v[162:165], v[26:29]
	v_mfma_f32_16x16x32_bf16 v[14:17], v[70:73], v[170:173], v[14:17]
	v_mfma_f32_16x16x32_bf16 v[10:13], v[82:85], v[170:173], v[10:13]
	v_mfma_f32_16x16x32_bf16 v[62:65], v[74:77], v[142:145], v[62:65]
	v_mfma_f32_16x16x32_bf16 v[58:61], v[86:89], v[142:145], v[58:61]
	v_mfma_f32_16x16x32_bf16 v[46:49], v[74:77], v[154:157], v[46:49]
	v_mfma_f32_16x16x32_bf16 v[42:45], v[86:89], v[154:157], v[42:45]
	v_mfma_f32_16x16x32_bf16 v[30:33], v[74:77], v[166:169], v[30:33]
	s_barrier
	v_mfma_f32_16x16x32_bf16 v[26:29], v[86:89], v[166:169], v[26:29]
	v_mfma_f32_16x16x32_bf16 v[14:17], v[74:77], v[184:187], v[14:17]
	v_mfma_f32_16x16x32_bf16 v[10:13], v[86:89], v[184:187], v[10:13]
	s_add_u32 s74, s74, s78
	s_addc_u32 s75, s75, 0
	s_add_i32 s59, s59, s9
	v_lshl_add_u64 v[236:237], s[74:75], 0, v[0:1]
	s_mov_b32 m0, s59
	v_lshl_add_u64 v[238:239], s[74:75], 0, v[174:175]
	global_load_lds_dwordx4 v[236:237], off
	s_add_i32 m0, s59, 0x2000
	s_nop 0
	global_load_lds_dwordx4 v[238:239], off
	s_waitcnt vmcnt(6)
	s_barrier
; #define PG8_STAGE(bufoff, gbase, voff) do { _Pragma("unroll") for (int _i = 0; _i < 2; ++_i) \
;         __builtin_amdgcn_global_load_lds((const unsigned*)((const char*)(gbase) + (voff)[_i]), (LAS unsigned*)(lds + (bufoff) + ldsw + _i * 8192), 16, 0, 0); } while (0)
; #define PG8_LDA(dst, b, h) do { _Pragma("unroll") for (int m = 0; m < 4; ++m) _Pragma("unroll") for (int k = 0; k < 2; ++k) dst[m][k] = *(const LAS bf16x8*)(lds + PG8_SA(b, h) + aoff + m * 2048 + k * 1024); } while (0)
; #define PG8_LDB(dst, b, h) do { _Pragma("unroll") for (int n = 0; n < 2; ++n) _Pragma("unroll") for (int k = 0; k < 2; ++k) dst[n][k] = *(const LAS bf16x8*)(lds + PG8_SB(b, h) + boff + n * 2048 + k * 1024); } while (0)
; #define PG8_MMA(ai, bj, At, Bt) do { __builtin_amdgcn_s_setprio(1); _Pragma("unroll") for (int m = 0; m < 4; ++m) _Pragma("unroll") for (int n = 0; n < 2; ++n) _Pragma("unroll") for (int k = 0; k < 2; ++k) \
;         acc[ai][bj][m][n] = __builtin_amdgcn_mfma_f32_16x16x32_bf16(Bt[n][k], At[m][k], acc[ai][bj][m][n], 0, 0, 0); __builtin_amdgcn_s_setprio(0); } while (0)
; #define PG8_WAIT_V(n) asm volatile("s_waitcnt vmcnt(" #n ")" ::: "memory")
; #define PG8_WAIT_L(n) asm volatile("s_waitcnt lgkmcnt(" #n ")" ::: "memory")
; #define PG8_BAR __builtin_amdgcn_s_barrier()
; #define PG8_SCHED __builtin_amdgcn_sched_barrier(0)
; template <int MODE, class EpiT, class Sched>
; __device__ __forceinline__ void gemm_phase(LAS unsigned char* lds, const Gemm g, const Sched& S, const EpiT& E) {
;     ...
;             PG8_WAIT_V(6); PG8_BAR; PG8_MMA(1, 1, At, B1); PG8_BAR;
;             PG8_LDB(B0, 1, 0); PG8_SCHED; PG8_LDA(At, 1, 0); PG8_STAGE(PG8_SA(0, 1), a2 + hstep, voffA);
;             PG8_WAIT_L(8); PG8_BAR; PG8_WAIT_L(0); PG8_MMA(0, 0, At, B0); PG8_BAR; PG8_SCHED;
;             PG8_LDB(B1, 1, 1); PG8_STAGE(PG8_SB(1, 0), b3, voffB);
;             PG8_BAR; PG8_WAIT_L(0); PG8_MMA(0, 1, At, B1); PG8_BAR;
	v_mfma_f32_16x16x32_bf16 v[54:57], v[188:191], v[138:141], v[54:57]
	v_mfma_f32_16x16x32_bf16 v[50:53], v[220:223], v[138:141], v[50:53]
	v_mfma_f32_16x16x32_bf16 v[38:41], v[188:191], v[146:149], v[38:41]
	v_mfma_f32_16x16x32_bf16 v[34:37], v[220:223], v[146:149], v[34:37]
	v_mfma_f32_16x16x32_bf16 v[22:25], v[188:191], v[162:165], v[22:25]
	v_mfma_f32_16x16x32_bf16 v[18:21], v[220:223], v[162:165], v[18:21]
	v_mfma_f32_16x16x32_bf16 v[6:9], v[188:191], v[170:173], v[6:9]
	v_mfma_f32_16x16x32_bf16 v[2:5], v[220:223], v[170:173], v[2:5]
	v_mfma_f32_16x16x32_bf16 v[54:57], v[196:199], v[142:145], v[54:57]
	v_mfma_f32_16x16x32_bf16 v[50:53], v[224:227], v[142:145], v[50:53]
	v_mfma_f32_16x16x32_bf16 v[38:41], v[196:199], v[154:157], v[38:41]
	v_mfma_f32_16x16x32_bf16 v[34:37], v[224:227], v[154:157], v[34:37]
	v_mfma_f32_16x16x32_bf16 v[22:25], v[196:199], v[166:169], v[22:25]
	s_barrier
	v_mfma_f32_16x16x32_bf16 v[18:21], v[224:227], v[166:169], v[18:21]
	v_mfma_f32_16x16x32_bf16 v[6:9], v[196:199], v[184:187], v[6:9]
	v_mfma_f32_16x16x32_bf16 v[2:5], v[224:227], v[184:187], v[2:5]
	s_add_i32 s59, 0, 0x18000
	v_add_u32_e32 v86, s59, v192
	ds_read_b128 v[70:73], v86
	ds_read_b128 v[74:77], v86 offset:1024
	ds_read_b128 v[82:85], v86 offset:2048
	ds_read_b128 v[86:89], v86 offset:3072
	s_add_u32 s52, s52, s78
	s_addc_u32 s53, s53, 0
	s_mov_b32 m0, s22
	v_lshl_add_u64 v[188:189], s[52:53], 0, v[0:1]
	ds_read_b128 v[138:141], v194 offset:32768
	ds_read_b128 v[142:145], v194 offset:33792
	ds_read_b128 v[146:149], v194 offset:34816
	ds_read_b128 v[154:157], v194 offset:35840
	ds_read_b128 v[162:165], v194 offset:36864
	ds_read_b128 v[166:169], v194 offset:37888
	ds_read_b128 v[170:173], v194 offset:38912
	ds_read_b128 v[184:187], v194 offset:39936
	global_load_lds_dwordx4 v[188:189], off
	v_lshl_add_u64 v[188:189], s[52:53], 0, v[174:175]
	s_mov_b32 m0, s23
	s_nop 0
	global_load_lds_dwordx4 v[188:189], off
	s_waitcnt lgkmcnt(8)
	s_barrier
	s_waitcnt lgkmcnt(0)
	v_mfma_f32_16x16x32_bf16 v[158:161], v[70:73], v[138:141], v[158:161]
	v_mfma_f32_16x16x32_bf16 v[150:153], v[82:85], v[138:141], v[150:153]
	v_mfma_f32_16x16x32_bf16 v[126:129], v[70:73], v[146:149], v[126:129]
	v_mfma_f32_16x16x32_bf16 v[122:125], v[82:85], v[146:149], v[122:125]
	v_mfma_f32_16x16x32_bf16 v[110:113], v[70:73], v[162:165], v[110:113]
	v_mfma_f32_16x16x32_bf16 v[106:109], v[82:85], v[162:165], v[106:109]
	v_mfma_f32_16x16x32_bf16 v[94:97], v[70:73], v[170:173], v[94:97]
	v_mfma_f32_16x16x32_bf16 v[90:93], v[82:85], v[170:173], v[90:93]
	v_mfma_f32_16x16x32_bf16 v[158:161], v[74:77], v[142:145], v[158:161]
	v_mfma_f32_16x16x32_bf16 v[150:153], v[86:89], v[142:145], v[150:153]
	v_mfma_f32_16x16x32_bf16 v[126:129], v[74:77], v[154:157], v[126:129]
	v_mfma_f32_16x16x32_bf16 v[122:125], v[86:89], v[154:157], v[122:125]
	v_mfma_f32_16x16x32_bf16 v[110:113], v[74:77], v[166:169], v[110:113]
	s_barrier
	v_mfma_f32_16x16x32_bf16 v[106:109], v[86:89], v[166:169], v[106:109]
	v_mfma_f32_16x16x32_bf16 v[94:97], v[74:77], v[184:187], v[94:97]
	v_mfma_f32_16x16x32_bf16 v[90:93], v[86:89], v[184:187], v[90:93]
	s_add_i32 s52, 0, 0x1c000
	s_add_i32 s53, s59, s9
	v_add_u32_e32 v195, s52, v192
	v_lshl_add_u64 v[228:229], v[228:229], 0, s[76:77]
	s_mov_b32 m0, s53
	ds_read_b128 v[188:191], v195
	ds_read_b128 v[196:199], v195 offset:1024
	ds_read_b128 v[220:223], v195 offset:2048
	ds_read_b128 v[224:227], v195 offset:3072
	global_load_lds_dwordx4 v[228:229], off
	v_lshl_add_u64 v[228:229], v[230:231], 0, s[76:77]
	s_add_i32 m0, s53, 0x2000
	s_nop 0
	global_load_lds_dwordx4 v[228:229], off
	s_barrier
	s_waitcnt lgkmcnt(0)
	v_mfma_f32_16x16x32_bf16 v[134:137], v[188:191], v[138:141], v[134:137]
	v_mfma_f32_16x16x32_bf16 v[130:133], v[220:223], v[138:141], v[130:133]
	v_mfma_f32_16x16x32_bf16 v[118:121], v[188:191], v[146:149], v[118:121]
	v_mfma_f32_16x16x32_bf16 v[114:117], v[220:223], v[146:149], v[114:117]
	v_mfma_f32_16x16x32_bf16 v[102:105], v[188:191], v[162:165], v[102:105]
	v_mfma_f32_16x16x32_bf16 v[98:101], v[220:223], v[162:165], v[98:101]
	v_mfma_f32_16x16x32_bf16 v[78:81], v[188:191], v[170:173], v[78:81]
	v_mfma_f32_16x16x32_bf16 v[66:69], v[220:223], v[170:173], v[66:69]
	v_mfma_f32_16x16x32_bf16 v[134:137], v[196:199], v[142:145], v[134:137]
	v_mfma_f32_16x16x32_bf16 v[130:133], v[224:227], v[142:145], v[130:133]
	v_mfma_f32_16x16x32_bf16 v[118:121], v[196:199], v[154:157], v[118:121]
	v_mfma_f32_16x16x32_bf16 v[114:117], v[224:227], v[154:157], v[114:117]
	v_mfma_f32_16x16x32_bf16 v[102:105], v[196:199], v[166:169], v[102:105]
	s_barrier
; #define PG8_STAGE(bufoff, gbase, voff) do { _Pragma("unroll") for (int _i = 0; _i < 2; ++_i) \
;         __builtin_amdgcn_global_load_lds((const unsigned*)((const char*)(gbase) + (voff)[_i]), (LAS unsigned*)(lds + (bufoff) + ldsw + _i * 8192), 16, 0, 0); } while (0)
; #define PG8_LDA(dst, b, h) do { _Pragma("unroll") for (int m = 0; m < 4; ++m) _Pragma("unroll") for (int k = 0; k < 2; ++k) dst[m][k] = *(const LAS bf16x8*)(lds + PG8_SA(b, h) + aoff + m * 2048 + k * 1024); } while (0)
; #define PG8_MMA(ai, bj, At, Bt) do { __builtin_amdgcn_s_setprio(1); _Pragma("unroll") for (int m = 0; m < 4; ++m) _Pragma("unroll") for (int n = 0; n < 2; ++n) _Pragma("unroll") for (int k = 0; k < 2; ++k) \
;         acc[ai][bj][m][n] = __builtin_amdgcn_mfma_f32_16x16x32_bf16(Bt[n][k], At[m][k], acc[ai][bj][m][n], 0, 0, 0); __builtin_amdgcn_s_setprio(0); } while (0)
; #define PG8_WAIT_V(n) asm volatile("s_waitcnt vmcnt(" #n ")" ::: "memory")
; #define PG8_WAIT_L(n) asm volatile("s_waitcnt lgkmcnt(" #n ")" ::: "memory")
; #define PG8_BAR __builtin_amdgcn_s_barrier()
; #define PG8_SCHED __builtin_amdgcn_sched_barrier(0)
; template <int MODE, class EpiT, class Sched>
; __device__ __forceinline__ void gemm_phase(LAS unsigned char* lds, const Gemm g, const Sched& S, const EpiT& E) {
;     ...
;             PG8_BAR; PG8_WAIT_L(0); PG8_MMA(0, 1, At, B1); PG8_BAR;
;             PG8_LDA(At, 1, 1); PG8_STAGE(PG8_SA(1, 0), a3, voffA);
;             PG8_BAR; PG8_WAIT_L(0); PG8_MMA(1, 0, At, B0); PG8_BAR; PG8_SCHED;
;             PG8_STAGE(PG8_SB(1, 1), b3 + hstep, voffB);
;             PG8_WAIT_V(6); PG8_BAR; PG8_MMA(1, 1, At, B1); PG8_BAR;
	v_mfma_f32_16x16x32_bf16 v[98:101], v[224:227], v[166:169], v[98:101]
	v_mfma_f32_16x16x32_bf16 v[78:81], v[196:199], v[184:187], v[78:81]
	v_mfma_f32_16x16x32_bf16 v[66:69], v[224:227], v[184:187], v[66:69]
	s_mov_b32 m0, s51
	v_lshl_add_u64 v[228:229], v[232:233], 0, s[76:77]
	ds_read_b128 v[138:141], v194 offset:49152
	ds_read_b128 v[142:145], v194 offset:50176
	ds_read_b128 v[146:149], v194 offset:51200
	ds_read_b128 v[154:157], v194 offset:52224
	ds_read_b128 v[162:165], v194 offset:53248
	ds_read_b128 v[166:169], v194 offset:54272
	ds_read_b128 v[170:173], v194 offset:55296
	ds_read_b128 v[184:187], v194 offset:56320
	global_load_lds_dwordx4 v[228:229], off
	v_lshl_add_u64 v[228:229], v[234:235], 0, s[76:77]
	s_mov_b32 m0, s56
	s_nop 0
	global_load_lds_dwordx4 v[228:229], off
	s_barrier
	s_waitcnt lgkmcnt(0)
	v_mfma_f32_16x16x32_bf16 v[62:65], v[70:73], v[138:141], v[62:65]
	v_mfma_f32_16x16x32_bf16 v[58:61], v[82:85], v[138:141], v[58:61]
	v_mfma_f32_16x16x32_bf16 v[46:49], v[70:73], v[146:149], v[46:49]
	v_mfma_f32_16x16x32_bf16 v[42:45], v[82:85], v[146:149], v[42:45]
	v_mfma_f32_16x16x32_bf16 v[30:33], v[70:73], v[162:165], v[30:33]
	v_mfma_f32_16x16x32_bf16 v[26:29], v[82:85], v[162:165], v[26:29]
	v_mfma_f32_16x16x32_bf16 v[14:17], v[70:73], v[170:173], v[14:17]
	v_mfma_f32_16x16x32_bf16 v[10:13], v[82:85], v[170:173], v[10:13]
	v_mfma_f32_16x16x32_bf16 v[62:65], v[74:77], v[142:145], v[62:65]
	v_mfma_f32_16x16x32_bf16 v[58:61], v[86:89], v[142:145], v[58:61]
	v_mfma_f32_16x16x32_bf16 v[46:49], v[74:77], v[154:157], v[46:49]
	v_mfma_f32_16x16x32_bf16 v[42:45], v[86:89], v[154:157], v[42:45]
	v_mfma_f32_16x16x32_bf16 v[30:33], v[74:77], v[166:169], v[30:33]
	s_barrier
	v_mfma_f32_16x16x32_bf16 v[26:29], v[86:89], v[166:169], v[26:29]
	v_mfma_f32_16x16x32_bf16 v[14:17], v[74:77], v[184:187], v[14:17]
	v_mfma_f32_16x16x32_bf16 v[10:13], v[86:89], v[184:187], v[10:13]
	s_add_i32 s52, s52, s9
	v_lshl_add_u64 v[70:71], v[236:237], 0, s[76:77]
	s_mov_b32 m0, s52
	s_nop 0
	global_load_lds_dwordx4 v[70:71], off
	v_lshl_add_u64 v[70:71], v[238:239], 0, s[76:77]
	s_add_i32 m0, s52, 0x2000
	s_nop 0
	global_load_lds_dwordx4 v[70:71], off
	s_waitcnt vmcnt(6)
	s_barrier
	v_mfma_f32_16x16x32_bf16 v[54:57], v[188:191], v[138:141], v[54:57]
	v_mfma_f32_16x16x32_bf16 v[50:53], v[220:223], v[138:141], v[50:53]
	v_mfma_f32_16x16x32_bf16 v[38:41], v[188:191], v[146:149], v[38:41]
	v_mfma_f32_16x16x32_bf16 v[34:37], v[220:223], v[146:149], v[34:37]
	v_mfma_f32_16x16x32_bf16 v[22:25], v[188:191], v[162:165], v[22:25]
	v_mfma_f32_16x16x32_bf16 v[18:21], v[220:223], v[162:165], v[18:21]
	v_mfma_f32_16x16x32_bf16 v[6:9], v[188:191], v[170:173], v[6:9]
	v_mfma_f32_16x16x32_bf16 v[2:5], v[220:223], v[170:173], v[2:5]
	v_mfma_f32_16x16x32_bf16 v[54:57], v[196:199], v[142:145], v[54:57]
	v_mfma_f32_16x16x32_bf16 v[50:53], v[224:227], v[142:145], v[50:53]
	v_mfma_f32_16x16x32_bf16 v[38:41], v[196:199], v[154:157], v[38:41]
	v_mfma_f32_16x16x32_bf16 v[34:37], v[224:227], v[154:157], v[34:37]
	v_mfma_f32_16x16x32_bf16 v[22:25], v[196:199], v[166:169], v[22:25]
	s_barrier
	v_mfma_f32_16x16x32_bf16 v[18:21], v[224:227], v[166:169], v[18:21]
	v_mfma_f32_16x16x32_bf16 v[6:9], v[196:199], v[184:187], v[6:9]
	v_mfma_f32_16x16x32_bf16 v[2:5], v[224:227], v[184:187], v[2:5]
	s_add_u32 s44, s44, 0x100
	s_addc_u32 s45, s45, 0
	s_add_u32 vcc_lo, vcc_lo, 0x100
	s_addc_u32 vcc_hi, vcc_hi, 0
	s_cmp_ge_u32 s58, s50
	s_mov_b32 s52, s58
	s_cbranch_scc0 .LBB0_115
	v_lshl_or_b32 v184, s24, 8, v193
	v_ashrrev_i32_e32 v185, 31, v184
	v_mov_b32_e32 v74, 0
	v_cndmask_b32_e64 v70, 0, 1, s[68:69]
	v_lshl_add_u64 v[138:139], v[184:185], 2, s[12:13]
	v_cmp_ne_u32_e64 s[44:45], 1, v70
	s_andn2_b64 vcc, exec, s[68:69]
	v_mov_b32_e32 v86, 0
	v_mov_b32_e32 v87, v74
	v_mov_b32_e32 v186, 0
	v_mov_b32_e32 v187, v74
	s_cbranch_vccnz .LBB0_118
	global_load_dwordx4 v[86:89], v[138:139], off
	s_waitcnt vmcnt(0)
	v_mov_b32_e32 v186, v88
	v_mov_b32_e32 v187, v89

; #define PG8_STAGE(bufoff, gbase, voff) do { _Pragma("unroll") for (int _i = 0; _i < 2; ++_i) \
;         __builtin_amdgcn_global_load_lds((const unsigned*)((const char*)(gbase) + (voff)[_i]), (LAS unsigned*)(lds + (bufoff) + ldsw + _i * 8192), 16, 0, 0); } while (0)
; #define PG8_LDA(dst, b, h) do { _Pragma("unroll") for (int m = 0; m < 4; ++m) _Pragma("unroll") for (int k = 0; k < 2; ++k) dst[m][k] = *(const LAS bf16x8*)(lds + PG8_SA(b, h) + aoff + m * 2048 + k * 1024); } while (0)
; #define PG8_LDB(dst, b, h) do { _Pragma("unroll") for (int n = 0; n < 2; ++n) _Pragma("unroll") for (int k = 0; k < 2; ++k) dst[n][k] = *(const LAS bf16x8*)(lds + PG8_SB(b, h) + boff + n * 2048 + k * 1024); } while (0)
; #define PG8_MMA(ai, bj, At, Bt) do { __builtin_amdgcn_s_setprio(1); _Pragma("unroll") for (int m = 0; m < 4; ++m) _Pragma("unroll") for (int n = 0; n < 2; ++n) _Pragma("unroll") for (int k = 0; k < 2; ++k) \
;         acc[ai][bj][m][n] = __builtin_amdgcn_mfma_f32_16x16x32_bf16(Bt[n][k], At[m][k], acc[ai][bj][m][n], 0, 0, 0); __builtin_amdgcn_s_setprio(0); } while (0)
; #define PG8_WAIT_L(n) asm volatile("s_waitcnt lgkmcnt(" #n ")" ::: "memory")
; #define PG8_BAR __builtin_amdgcn_s_barrier()
; #define PG8_SCHED __builtin_amdgcn_sched_barrier(0)
; template <int MODE, class EpiT, class Sched>
; __device__ __forceinline__ void gemm_phase(LAS unsigned char* lds, const Gemm g, const Sched& S, const EpiT& E) {
;     ...
;             const bool last = (t == nt - 2);
;             const char* a1 = cA + (size_t)(t + 1) * kstep;
;             const char* a2 = last ? nA : cA + (size_t)(t + 2) * kstep; const char* b2 = last ? nB : cB + (size_t)(t + 2) * kstep;
;             const char* a3 = a2 + kstep; const char* b3 = b2 + kstep;
;             PG8_LDB(B0, 0, 0); PG8_SCHED; PG8_LDA(At, 0, 0); PG8_STAGE(PG8_SA(1, 1), a1 + hstep, voffA);
;             PG8_WAIT_L(8); PG8_BAR; PG8_WAIT_L(0); PG8_MMA(0, 0, At, B0); PG8_BAR; PG8_SCHED;
;             PG8_LDB(B1, 0, 1); PG8_STAGE(PG8_SB(0, 0), b2, voffB);
;             PG8_BAR; PG8_WAIT_L(0); PG8_MMA(0, 1, At, B1); PG8_BAR;
;             PG8_LDA(At, 0, 1); PG8_STAGE(PG8_SA(0, 0), a2, voffA);
;             PG8_BAR; PG8_WAIT_L(0); PG8_MMA(1, 0, At, B0); PG8_BAR; PG8_SCHED;
.LBB0_159:
	s_add_i32 s89, s30, 2
	s_add_u32 s44, s4, 0x80
	s_addc_u32 s45, s5, 0
	s_add_i32 s58, 0, 0x10000
	v_add_u32_e32 v142, s58, v220
	ds_read_b128 v[130:133], v142
	ds_read_b128 v[134:137], v142 offset:1024
	ds_read_b128 v[138:141], v142 offset:2048
	ds_read_b128 v[142:145], v142 offset:3072
	s_cmp_eq_u32 s61, s30
	s_cselect_b32 s45, s79, s45
	s_cselect_b32 s44, s78, s44
	s_cselect_b32 s53, s47, s24
	s_cselect_b32 s52, s46, s23
	v_lshl_add_u64 v[188:189], s[4:5], 0, v[184:185]
	s_add_i32 m0, s69, 0xc000
	ds_read_b128 v[146:149], v223
	ds_read_b128 v[150:153], v223 offset:1024
	ds_read_b128 v[154:157], v223 offset:2048
	ds_read_b128 v[158:161], v223 offset:3072
	ds_read_b128 v[162:165], v223 offset:4096
	ds_read_b128 v[166:169], v223 offset:5120
	ds_read_b128 v[170:173], v223 offset:6144
	ds_read_b128 v[174:177], v223 offset:7168
	global_load_lds_dwordx4 v[188:189], off
	v_lshl_add_u64 v[188:189], s[4:5], 0, v[186:187]
	s_add_i32 m0, s69, 0xe000
	s_nop 0
	global_load_lds_dwordx4 v[188:189], off
	s_waitcnt lgkmcnt(8)
	s_barrier
	s_waitcnt lgkmcnt(0)
	v_mfma_f32_16x16x32_bf16 v[126:129], v[130:133], v[146:149], v[126:129]
	v_mfma_f32_16x16x32_bf16 v[122:125], v[138:141], v[146:149], v[122:125]
	v_mfma_f32_16x16x32_bf16 v[110:113], v[130:133], v[154:157], v[110:113]
	v_mfma_f32_16x16x32_bf16 v[106:109], v[138:141], v[154:157], v[106:109]
	v_mfma_f32_16x16x32_bf16 v[94:97], v[130:133], v[162:165], v[94:97]
	v_mfma_f32_16x16x32_bf16 v[90:93], v[138:141], v[162:165], v[90:93]
	v_mfma_f32_16x16x32_bf16 v[78:81], v[130:133], v[170:173], v[78:81]
	v_mfma_f32_16x16x32_bf16 v[74:77], v[138:141], v[170:173], v[74:77]
	v_mfma_f32_16x16x32_bf16 v[126:129], v[134:137], v[150:153], v[126:129]
	v_mfma_f32_16x16x32_bf16 v[122:125], v[142:145], v[150:153], v[122:125]
	v_mfma_f32_16x16x32_bf16 v[110:113], v[134:137], v[158:161], v[110:113]
	v_mfma_f32_16x16x32_bf16 v[106:109], v[142:145], v[158:161], v[106:109]
	v_mfma_f32_16x16x32_bf16 v[94:97], v[134:137], v[166:169], v[94:97]
	s_barrier
	v_mfma_f32_16x16x32_bf16 v[90:93], v[142:145], v[166:169], v[90:93]
	v_mfma_f32_16x16x32_bf16 v[78:81], v[134:137], v[174:177], v[78:81]
	v_mfma_f32_16x16x32_bf16 v[74:77], v[142:145], v[174:177], v[74:77]
	s_add_i32 s30, 0, 0x14000
	s_add_i32 s58, s58, s68
	v_add_u32_e32 v200, s30, v220
	v_lshl_add_u64 v[228:229], s[52:53], 0, v[0:1]
	s_mov_b32 m0, s58
	ds_read_b128 v[188:191], v200
	ds_read_b128 v[192:195], v200 offset:1024
	ds_read_b128 v[196:199], v200 offset:2048
	ds_read_b128 v[224:227], v200 offset:3072
	global_load_lds_dwordx4 v[228:229], off
	v_lshl_add_u64 v[230:231], s[52:53], 0, v[182:183]
	s_add_i32 m0, s58, 0x2000
	s_nop 0
	global_load_lds_dwordx4 v[230:231], off
	s_barrier
	s_waitcnt lgkmcnt(0)
	v_mfma_f32_16x16x32_bf16 v[118:121], v[188:191], v[146:149], v[118:121]
	v_mfma_f32_16x16x32_bf16 v[114:117], v[196:199], v[146:149], v[114:117]
	v_mfma_f32_16x16x32_bf16 v[102:105], v[188:191], v[154:157], v[102:105]
	v_mfma_f32_16x16x32_bf16 v[98:101], v[196:199], v[154:157], v[98:101]
	v_mfma_f32_16x16x32_bf16 v[86:89], v[188:191], v[162:165], v[86:89]
	v_mfma_f32_16x16x32_bf16 v[82:85], v[196:199], v[162:165], v[82:85]
	v_mfma_f32_16x16x32_bf16 v[70:73], v[188:191], v[170:173], v[70:73]
	v_mfma_f32_16x16x32_bf16 v[66:69], v[196:199], v[170:173], v[66:69]
	v_mfma_f32_16x16x32_bf16 v[118:121], v[192:195], v[150:153], v[118:121]
	v_mfma_f32_16x16x32_bf16 v[114:117], v[224:227], v[150:153], v[114:117]
	v_mfma_f32_16x16x32_bf16 v[102:105], v[192:195], v[158:161], v[102:105]
	v_mfma_f32_16x16x32_bf16 v[98:101], v[224:227], v[158:161], v[98:101]
	v_mfma_f32_16x16x32_bf16 v[86:89], v[192:195], v[166:169], v[86:89]
	s_barrier
	v_mfma_f32_16x16x32_bf16 v[82:85], v[224:227], v[166:169], v[82:85]
	v_mfma_f32_16x16x32_bf16 v[70:73], v[192:195], v[174:177], v[70:73]
	v_mfma_f32_16x16x32_bf16 v[66:69], v[224:227], v[174:177], v[66:69]
	s_mov_b32 m0, s69
	v_lshl_add_u64 v[232:233], s[44:45], 0, v[0:1]
	ds_read_b128 v[146:149], v223 offset:16384
	ds_read_b128 v[150:153], v223 offset:17408
	ds_read_b128 v[154:157], v223 offset:18432
	ds_read_b128 v[158:161], v223 offset:19456
	ds_read_b128 v[162:165], v223 offset:20480
	ds_read_b128 v[166:169], v223 offset:21504
	ds_read_b128 v[170:173], v223 offset:22528
	ds_read_b128 v[174:177], v223 offset:23552
	global_load_lds_dwordx4 v[232:233], off
	v_lshl_add_u64 v[234:235], s[44:45], 0, v[182:183]
	s_mov_b32 m0, s74
	s_nop 0
	global_load_lds_dwordx4 v[234:235], off
	s_barrier
	s_waitcnt lgkmcnt(0)
	v_mfma_f32_16x16x32_bf16 v[62:65], v[130:133], v[146:149], v[62:65]
	v_mfma_f32_16x16x32_bf16 v[58:61], v[138:141], v[146:149], v[58:61]
	v_mfma_f32_16x16x32_bf16 v[46:49], v[130:133], v[154:157], v[46:49]
	v_mfma_f32_16x16x32_bf16 v[42:45], v[138:141], v[154:157], v[42:45]
	v_mfma_f32_16x16x32_bf16 v[30:33], v[130:133], v[162:165], v[30:33]
	v_mfma_f32_16x16x32_bf16 v[26:29], v[138:141], v[162:165], v[26:29]
	v_mfma_f32_16x16x32_bf16 v[14:17], v[130:133], v[170:173], v[14:17]
	v_mfma_f32_16x16x32_bf16 v[10:13], v[138:141], v[170:173], v[10:13]
	v_mfma_f32_16x16x32_bf16 v[62:65], v[134:137], v[150:153], v[62:65]
	v_mfma_f32_16x16x32_bf16 v[58:61], v[142:145], v[150:153], v[58:61]
	v_mfma_f32_16x16x32_bf16 v[46:49], v[134:137], v[158:161], v[46:49]
	v_mfma_f32_16x16x32_bf16 v[42:45], v[142:145], v[158:161], v[42:45]
	v_mfma_f32_16x16x32_bf16 v[30:33], v[134:137], v[166:169], v[30:33]
	s_barrier
; #define PG8_STAGE(bufoff, gbase, voff) do { _Pragma("unroll") for (int _i = 0; _i < 2; ++_i) \
;         __builtin_amdgcn_global_load_lds((const unsigned*)((const char*)(gbase) + (voff)[_i]), (LAS unsigned*)(lds + (bufoff) + ldsw + _i * 8192), 16, 0, 0); } while (0)
; #define PG8_LDA(dst, b, h) do { _Pragma("unroll") for (int m = 0; m < 4; ++m) _Pragma("unroll") for (int k = 0; k < 2; ++k) dst[m][k] = *(const LAS bf16x8*)(lds + PG8_SA(b, h) + aoff + m * 2048 + k * 1024); } while (0)
; #define PG8_LDB(dst, b, h) do { _Pragma("unroll") for (int n = 0; n < 2; ++n) _Pragma("unroll") for (int k = 0; k < 2; ++k) dst[n][k] = *(const LAS bf16x8*)(lds + PG8_SB(b, h) + boff + n * 2048 + k * 1024); } while (0)
; #define PG8_MMA(ai, bj, At, Bt) do { __builtin_amdgcn_s_setprio(1); _Pragma("unroll") for (int m = 0; m < 4; ++m) _Pragma("unroll") for (int n = 0; n < 2; ++n) _Pragma("unroll") for (int k = 0; k < 2; ++k) \
;         acc[ai][bj][m][n] = __builtin_amdgcn_mfma_f32_16x16x32_bf16(Bt[n][k], At[m][k], acc[ai][bj][m][n], 0, 0, 0); __builtin_amdgcn_s_setprio(0); } while (0)
; #define PG8_WAIT_V(n) asm volatile("s_waitcnt vmcnt(" #n ")" ::: "memory")
; #define PG8_WAIT_L(n) asm volatile("s_waitcnt lgkmcnt(" #n ")" ::: "memory")
; #define PG8_BAR __builtin_amdgcn_s_barrier()
; #define PG8_SCHED __builtin_amdgcn_sched_barrier(0)
; template <int MODE, class EpiT, class Sched>
; __device__ __forceinline__ void gemm_phase(LAS unsigned char* lds, const Gemm g, const Sched& S, const EpiT& E) {
;     ...
;             PG8_BAR; PG8_WAIT_L(0); PG8_MMA(1, 0, At, B0); PG8_BAR; PG8_SCHED;
;             PG8_STAGE(PG8_SB(0, 1), b2 + hstep, voffB);
;             PG8_WAIT_V(6); PG8_BAR; PG8_MMA(1, 1, At, B1); PG8_BAR;
;             PG8_LDB(B0, 1, 0); PG8_SCHED; PG8_LDA(At, 1, 0); PG8_STAGE(PG8_SA(0, 1), a2 + hstep, voffA);
;             PG8_WAIT_L(8); PG8_BAR; PG8_WAIT_L(0); PG8_MMA(0, 0, At, B0); PG8_BAR; PG8_SCHED;
;             PG8_LDB(B1, 1, 1); PG8_STAGE(PG8_SB(1, 0), b3, voffB);
;             PG8_BAR; PG8_WAIT_L(0); PG8_MMA(0, 1, At, B1); PG8_BAR;
;             PG8_LDA(At, 1, 1); PG8_STAGE(PG8_SA(1, 0), a3, voffA);
	v_mfma_f32_16x16x32_bf16 v[26:29], v[142:145], v[166:169], v[26:29]
	v_mfma_f32_16x16x32_bf16 v[14:17], v[134:137], v[174:177], v[14:17]
	v_mfma_f32_16x16x32_bf16 v[10:13], v[142:145], v[174:177], v[10:13]
	s_add_u32 s52, s52, s38
	s_addc_u32 s53, s53, 0
	s_add_i32 s30, s30, s68
	v_lshl_add_u64 v[236:237], s[52:53], 0, v[0:1]
	s_mov_b32 m0, s30
	v_lshl_add_u64 v[238:239], s[52:53], 0, v[182:183]
	global_load_lds_dwordx4 v[236:237], off
	s_add_i32 m0, s30, 0x2000
	s_nop 0
	global_load_lds_dwordx4 v[238:239], off
	s_waitcnt vmcnt(6)
	s_barrier
	v_mfma_f32_16x16x32_bf16 v[54:57], v[188:191], v[146:149], v[54:57]
	v_mfma_f32_16x16x32_bf16 v[50:53], v[196:199], v[146:149], v[50:53]
	v_mfma_f32_16x16x32_bf16 v[38:41], v[188:191], v[154:157], v[38:41]
	v_mfma_f32_16x16x32_bf16 v[34:37], v[196:199], v[154:157], v[34:37]
	v_mfma_f32_16x16x32_bf16 v[22:25], v[188:191], v[162:165], v[22:25]
	v_mfma_f32_16x16x32_bf16 v[18:21], v[196:199], v[162:165], v[18:21]
	v_mfma_f32_16x16x32_bf16 v[6:9], v[188:191], v[170:173], v[6:9]
	v_mfma_f32_16x16x32_bf16 v[2:5], v[196:199], v[170:173], v[2:5]
	v_mfma_f32_16x16x32_bf16 v[54:57], v[192:195], v[150:153], v[54:57]
	v_mfma_f32_16x16x32_bf16 v[50:53], v[224:227], v[150:153], v[50:53]
	v_mfma_f32_16x16x32_bf16 v[38:41], v[192:195], v[158:161], v[38:41]
	v_mfma_f32_16x16x32_bf16 v[34:37], v[224:227], v[158:161], v[34:37]
	v_mfma_f32_16x16x32_bf16 v[22:25], v[192:195], v[166:169], v[22:25]
	s_barrier
	v_mfma_f32_16x16x32_bf16 v[18:21], v[224:227], v[166:169], v[18:21]
	v_mfma_f32_16x16x32_bf16 v[6:9], v[192:195], v[174:177], v[6:9]
	v_mfma_f32_16x16x32_bf16 v[2:5], v[224:227], v[174:177], v[2:5]
	s_add_i32 s30, 0, 0x18000
	v_add_u32_e32 v142, s30, v220
	ds_read_b128 v[130:133], v142
	ds_read_b128 v[134:137], v142 offset:1024
	ds_read_b128 v[138:141], v142 offset:2048
	ds_read_b128 v[142:145], v142 offset:3072
	s_add_u32 s44, s44, s38
	s_addc_u32 s45, s45, 0
	s_mov_b32 m0, s75
	v_lshl_add_u64 v[188:189], s[44:45], 0, v[0:1]
	ds_read_b128 v[146:149], v223 offset:32768
	ds_read_b128 v[150:153], v223 offset:33792
	ds_read_b128 v[154:157], v223 offset:34816
	ds_read_b128 v[158:161], v223 offset:35840
	ds_read_b128 v[162:165], v223 offset:36864
	ds_read_b128 v[166:169], v223 offset:37888
	ds_read_b128 v[170:173], v223 offset:38912
	ds_read_b128 v[174:177], v223 offset:39936
	global_load_lds_dwordx4 v[188:189], off
	v_lshl_add_u64 v[188:189], s[44:45], 0, v[182:183]
	s_mov_b32 m0, s9
	s_nop 0
	global_load_lds_dwordx4 v[188:189], off
	s_waitcnt lgkmcnt(8)
	s_barrier
	s_waitcnt lgkmcnt(0)
	v_mfma_f32_16x16x32_bf16 v[126:129], v[130:133], v[146:149], v[126:129]
	v_mfma_f32_16x16x32_bf16 v[122:125], v[138:141], v[146:149], v[122:125]
	v_mfma_f32_16x16x32_bf16 v[110:113], v[130:133], v[154:157], v[110:113]
	v_mfma_f32_16x16x32_bf16 v[106:109], v[138:141], v[154:157], v[106:109]
	v_mfma_f32_16x16x32_bf16 v[94:97], v[130:133], v[162:165], v[94:97]
	v_mfma_f32_16x16x32_bf16 v[90:93], v[138:141], v[162:165], v[90:93]
	v_mfma_f32_16x16x32_bf16 v[78:81], v[130:133], v[170:173], v[78:81]
	v_mfma_f32_16x16x32_bf16 v[74:77], v[138:141], v[170:173], v[74:77]
	v_mfma_f32_16x16x32_bf16 v[126:129], v[134:137], v[150:153], v[126:129]
	v_mfma_f32_16x16x32_bf16 v[122:125], v[142:145], v[150:153], v[122:125]
	v_mfma_f32_16x16x32_bf16 v[110:113], v[134:137], v[158:161], v[110:113]
	v_mfma_f32_16x16x32_bf16 v[106:109], v[142:145], v[158:161], v[106:109]
	v_mfma_f32_16x16x32_bf16 v[94:97], v[134:137], v[166:169], v[94:97]
	s_barrier
	v_mfma_f32_16x16x32_bf16 v[90:93], v[142:145], v[166:169], v[90:93]
	v_mfma_f32_16x16x32_bf16 v[78:81], v[134:137], v[174:177], v[78:81]
	v_mfma_f32_16x16x32_bf16 v[74:77], v[142:145], v[174:177], v[74:77]
	s_add_i32 s44, 0, 0x1c000
	s_add_i32 s30, s30, s68
	v_add_u32_e32 v200, s44, v220
	v_lshl_add_u64 v[228:229], v[228:229], 0, s[76:77]
	s_mov_b32 m0, s30
	ds_read_b128 v[188:191], v200
	ds_read_b128 v[192:195], v200 offset:1024
	ds_read_b128 v[196:199], v200 offset:2048
	ds_read_b128 v[224:227], v200 offset:3072
	global_load_lds_dwordx4 v[228:229], off
	v_lshl_add_u64 v[228:229], v[230:231], 0, s[76:77]
	s_add_i32 m0, s30, 0x2000
	s_nop 0
	global_load_lds_dwordx4 v[228:229], off
	s_barrier
	s_waitcnt lgkmcnt(0)
	v_mfma_f32_16x16x32_bf16 v[118:121], v[188:191], v[146:149], v[118:121]
	v_mfma_f32_16x16x32_bf16 v[114:117], v[196:199], v[146:149], v[114:117]
	v_mfma_f32_16x16x32_bf16 v[102:105], v[188:191], v[154:157], v[102:105]
	v_mfma_f32_16x16x32_bf16 v[98:101], v[196:199], v[154:157], v[98:101]
	v_mfma_f32_16x16x32_bf16 v[86:89], v[188:191], v[162:165], v[86:89]
	v_mfma_f32_16x16x32_bf16 v[82:85], v[196:199], v[162:165], v[82:85]
	v_mfma_f32_16x16x32_bf16 v[70:73], v[188:191], v[170:173], v[70:73]
	v_mfma_f32_16x16x32_bf16 v[66:69], v[196:199], v[170:173], v[66:69]
	v_mfma_f32_16x16x32_bf16 v[118:121], v[192:195], v[150:153], v[118:121]
	v_mfma_f32_16x16x32_bf16 v[114:117], v[224:227], v[150:153], v[114:117]
	v_mfma_f32_16x16x32_bf16 v[102:105], v[192:195], v[158:161], v[102:105]
	v_mfma_f32_16x16x32_bf16 v[98:101], v[224:227], v[158:161], v[98:101]
	v_mfma_f32_16x16x32_bf16 v[86:89], v[192:195], v[166:169], v[86:89]
	s_barrier
	v_mfma_f32_16x16x32_bf16 v[82:85], v[224:227], v[166:169], v[82:85]
	v_mfma_f32_16x16x32_bf16 v[70:73], v[192:195], v[174:177], v[70:73]
	v_mfma_f32_16x16x32_bf16 v[66:69], v[224:227], v[174:177], v[66:69]
	s_mov_b32 m0, s57
	v_lshl_add_u64 v[228:229], v[232:233], 0, s[76:77]
	ds_read_b128 v[146:149], v223 offset:49152
	ds_read_b128 v[150:153], v223 offset:50176
	ds_read_b128 v[154:157], v223 offset:51200
	ds_read_b128 v[158:161], v223 offset:52224
	ds_read_b128 v[162:165], v223 offset:53248
	ds_read_b128 v[166:169], v223 offset:54272
	ds_read_b128 v[170:173], v223 offset:55296
	ds_read_b128 v[174:177], v223 offset:56320
	global_load_lds_dwordx4 v[228:229], off
	v_lshl_add_u64 v[228:229], v[234:235], 0, s[76:77]
	s_mov_b32 m0, s60
	s_nop 0
	global_load_lds_dwordx4 v[228:229], off
	s_barrier
;     __device__ __forceinline__ void scales2(const Unit& u, int wr, int fr, int fq, float& sA, float& sB) const {
;         const int rowA = u.pm * BM + wr * 64 + fq * 16 + fr;
;         const f32x4* pa = (const f32x4*)(ssq_in + (size_t)rowA * 16); const f32x4* pb = (const f32x4*)(ssq_in + (size_t)(rowA + HALF) * 16);
;         const f32x4 a0 = pa[0], a1 = pa[1], a2 = pa[2], a3 = pa[3], b0 = pb[0], b1 = pb[1], b2 = pb[2], b3 = pb[3];
;         const float ta = (((a0[0] + a0[1]) + (a0[2] + a0[3])) + ((a1[0] + a1[1]) + (a1[2] + a1[3]))) + (((a2[0] + a2[1]) + (a2[2] + a2[3])) + ((a3[0] + a3[1]) + (a3[2] + a3[3])));
;         const float tb = (((b0[0] + b0[1]) + (b0[2] + b0[3])) + ((b1[0] + b1[1]) + (b1[2] + b1[3]))) + (((b2[0] + b2[1]) + (b2[2] + b2[3])) + ((b3[0] + b3[1]) + (b3[2] + b3[3])));
;         sA = rsqrtf(ta * (1.0f / 1024.0f) + EPS); sB = rsqrtf(tb * (1.0f / 1024.0f) + EPS);
;     template <int mode> __device__ __forceinline__ void run(const f32x4 (&acc)[2][2][4][2], const Unit& u, int wr, int wc, int fr, int fq, const LAS float* sc) const {
;     ...
;             {
;                 const size_t off = (size_t)row0 * D + col0;
; #pragma unroll
;                 for (int bj = 0; bj < 2; ++bj) {
;                     const size_t o = off + bj * HALF;
;                     if (mode == 5) { xi[0][2 * bj] = *(const f32x4*)(xin + o); xi[0][2 * bj + 1] = *(const f32x4*)(xin + o + 4); }
;                     else { xh[0][bj] = *(const u32x4*)(hin + o); xl[0][bj] = *(const u32x4*)(lin + o); }
;                     if (mode == 4) pq[0][bj] = *(const u32x4*)(ob + o);
;                 }
;             }
; #pragma unroll
;             for (int g = 0; g < 8; ++g) {
;                 const int ai = g >> 2, m = g & 3, cb = g & 1, nb = cb ^ 1;
;                 const int row = row0 + ai * HALF + m * 16;
;                 const size_t off = (size_t)row * D + col0;
;                 if (g < 7) {
;                     const size_t offn = (size_t)(row0 + ((g + 1) >> 2) * HALF + ((g + 1) & 3) * 16) * D + col0;
; #pragma unroll
;                     for (int bj = 0; bj < 2; ++bj) {
;                         const size_t o = offn + bj * HALF;
;                         if (mode == 5) { xi[nb][2 * bj] = *(const f32x4*)(xin + o); xi[nb][2 * bj + 1] = *(const f32x4*)(xin + o + 4); }
	s_waitcnt lgkmcnt(0)
	v_mfma_f32_16x16x32_bf16 v[62:65], v[130:133], v[146:149], v[62:65]
	v_mfma_f32_16x16x32_bf16 v[58:61], v[138:141], v[146:149], v[58:61]
	v_mfma_f32_16x16x32_bf16 v[46:49], v[130:133], v[154:157], v[46:49]
	v_mfma_f32_16x16x32_bf16 v[42:45], v[138:141], v[154:157], v[42:45]
	v_mfma_f32_16x16x32_bf16 v[30:33], v[130:133], v[162:165], v[30:33]
	v_mfma_f32_16x16x32_bf16 v[26:29], v[138:141], v[162:165], v[26:29]
	v_mfma_f32_16x16x32_bf16 v[14:17], v[130:133], v[170:173], v[14:17]
	v_mfma_f32_16x16x32_bf16 v[10:13], v[138:141], v[170:173], v[10:13]
	v_mfma_f32_16x16x32_bf16 v[62:65], v[134:137], v[150:153], v[62:65]
	v_mfma_f32_16x16x32_bf16 v[58:61], v[142:145], v[150:153], v[58:61]
	v_mfma_f32_16x16x32_bf16 v[46:49], v[134:137], v[158:161], v[46:49]
	v_mfma_f32_16x16x32_bf16 v[42:45], v[142:145], v[158:161], v[42:45]
	v_mfma_f32_16x16x32_bf16 v[30:33], v[134:137], v[166:169], v[30:33]
	s_barrier
	v_mfma_f32_16x16x32_bf16 v[26:29], v[142:145], v[166:169], v[26:29]
	v_mfma_f32_16x16x32_bf16 v[14:17], v[134:137], v[174:177], v[14:17]
	v_mfma_f32_16x16x32_bf16 v[10:13], v[142:145], v[174:177], v[10:13]
	s_add_i32 s30, s44, s68
	v_lshl_add_u64 v[130:131], v[236:237], 0, s[76:77]
	s_mov_b32 m0, s30
	s_nop 0
	global_load_lds_dwordx4 v[130:131], off
	v_lshl_add_u64 v[130:131], v[238:239], 0, s[76:77]
	s_add_i32 m0, s30, 0x2000
	s_nop 0
	global_load_lds_dwordx4 v[130:131], off
	s_waitcnt vmcnt(6)
	s_barrier
	v_mfma_f32_16x16x32_bf16 v[54:57], v[188:191], v[146:149], v[54:57]
	v_mfma_f32_16x16x32_bf16 v[50:53], v[196:199], v[146:149], v[50:53]
	v_mfma_f32_16x16x32_bf16 v[38:41], v[188:191], v[154:157], v[38:41]
	v_mfma_f32_16x16x32_bf16 v[34:37], v[196:199], v[154:157], v[34:37]
	v_mfma_f32_16x16x32_bf16 v[22:25], v[188:191], v[162:165], v[22:25]
	v_mfma_f32_16x16x32_bf16 v[18:21], v[196:199], v[162:165], v[18:21]
	v_mfma_f32_16x16x32_bf16 v[6:9], v[188:191], v[170:173], v[6:9]
	v_mfma_f32_16x16x32_bf16 v[2:5], v[196:199], v[170:173], v[2:5]
	v_mfma_f32_16x16x32_bf16 v[54:57], v[192:195], v[150:153], v[54:57]
	v_mfma_f32_16x16x32_bf16 v[50:53], v[224:227], v[150:153], v[50:53]
	v_mfma_f32_16x16x32_bf16 v[38:41], v[192:195], v[158:161], v[38:41]
	v_mfma_f32_16x16x32_bf16 v[34:37], v[224:227], v[158:161], v[34:37]
	v_mfma_f32_16x16x32_bf16 v[22:25], v[192:195], v[166:169], v[22:25]
	s_barrier
	v_mfma_f32_16x16x32_bf16 v[18:21], v[224:227], v[166:169], v[18:21]
	v_mfma_f32_16x16x32_bf16 v[6:9], v[192:195], v[174:177], v[6:9]
	v_mfma_f32_16x16x32_bf16 v[2:5], v[224:227], v[174:177], v[2:5]
	s_add_u32 s4, s4, 0x100
	s_addc_u32 s5, s5, 0
	s_add_u32 s23, s23, 0x100
	s_addc_u32 s24, s24, 0
	s_cmp_ge_u32 s89, s21
	s_mov_b32 s30, s89
	s_cbranch_scc0 .LBB0_159
	s_lshl_b32 s4, s22, 8
	s_add_i32 s4, s4, s56
	v_or_b32_e32 v130, s4, v222
	v_ashrrev_i32_e32 v131, 31, v130
	v_lshlrev_b64 v[130:131], 6, v[130:131]
	v_lshl_add_u64 v[146:147], s[66:67], 0, v[130:131]
	global_load_dwordx4 v[130:133], v[146:147], off offset:16
	global_load_dwordx4 v[134:137], v[146:147], off offset:48
	global_load_dwordx4 v[138:141], v[146:147], off
	global_load_dwordx4 v[142:145], v[146:147], off offset:32
	v_or_b32_e32 v192, s4, v181
	s_mov_b64 s[4:5], 0x2000
	v_lshl_add_u64 v[158:159], v[146:147], 0, s[4:5]
	v_add_co_u32_e32 v146, vcc, 0x2000, v146
	s_mov_b32 s4, 0x3a800000
	s_nop 0
	v_addc_co_u32_e32 v147, vcc, 0, v147, vcc
	global_load_dwordx4 v[146:149], v[146:147], off
	s_nop 0
	global_load_dwordx4 v[150:153], v[158:159], off offset:16
	global_load_dwordx4 v[154:157], v[158:159], off offset:48
	s_nop 0
	global_load_dwordx4 v[158:161], v[158:159], off offset:32
	v_lshl_or_b32 v188, s2, 8, v221
	v_ashrrev_i32_e32 v193, 31, v192
	v_ashrrev_i32_e32 v189, 31, v188
	v_or_b32_e32 v194, 16, v192
	v_ashrrev_i32_e32 v195, 31, v194
	s_waitcnt vmcnt(0)
	v_mov_b32_e32 v162, v138
	v_mov_b32_e32 v163, v142
	v_mov_b32_e32 v142, v139
	v_pk_add_f32 v[138:139], v[162:163], v[142:143]
	v_mov_b32_e32 v142, v140
	v_mov_b32_e32 v143, v144
	v_mov_b32_e32 v144, v141
	v_pk_add_f32 v[140:141], v[142:143], v[144:145]
	s_nop 0
	v_pk_add_f32 v[138:139], v[138:139], v[140:141]
	v_mov_b32_e32 v140, v130
	v_mov_b32_e32 v141, v134
	v_mov_b32_e32 v134, v131
	v_pk_add_f32 v[130:131], v[140:141], v[134:135]
	v_mov_b32_e32 v134, v132
	v_mov_b32_e32 v135, v136
	v_mov_b32_e32 v136, v133
	v_pk_add_f32 v[132:133], v[134:135], v[136:137]
	v_mov_b32_e32 v134, v148
	v_pk_add_f32 v[130:131], v[130:131], v[132:133]
	v_mov_b32_e32 v132, v146
	v_mov_b32_e32 v133, v158
	v_mov_b32_e32 v158, v147
	v_mov_b32_e32 v135, v160
	v_mov_b32_e32 v160, v149
	v_pk_add_f32 v[132:133], v[132:133], v[158:159]
	v_pk_add_f32 v[134:135], v[134:135], v[160:161]
	v_mov_b32_e32 v136, v152
	v_pk_add_f32 v[132:133], v[132:133], v[134:135]
	v_mov_b32_e32 v134, v150
	v_mov_b32_e32 v135, v154
	v_mov_b32_e32 v154, v151
	v_mov_b32_e32 v137, v156
	v_mov_b32_e32 v156, v153
	v_pk_add_f32 v[134:135], v[134:135], v[154:155]
	v_pk_add_f32 v[136:137], v[136:137], v[156:157]
	v_pk_add_f32 v[130:131], v[138:139], v[130:131]
	v_pk_add_f32 v[134:135], v[134:135], v[136:137]
	s_nop 0
	v_pk_add_f32 v[132:133], v[132:133], v[134:135]
	v_mov_b32_e32 v135, v130
	v_mov_b32_e32 v134, v132
	v_mov_b32_e32 v130, v133
	v_pk_add_f32 v[130:131], v[134:135], v[130:131]
	s_nop 0
	v_pk_fma_f32 v[190:191], v[130:131], s[4:5], v[178:179] op_sel_hi:[1,0,0]
	s_mov_b32 s4, 0x800000
	v_mul_f32_e32 v130, 0x4b800000, v191
	v_cmp_gt_f32_e64 s[44:45], s4, v191
	v_cmp_gt_f32_e32 vcc, s4, v190
	s_nop 0
	v_cndmask_b32_e64 v130, v191, v130, s[44:45]
	v_rsq_f32_e32 v130, v130
	s_nop 0
	v_mul_f32_e32 v131, 0x45800000, v130
	v_cndmask_b32_e64 v226, v130, v131, s[44:45]
	v_lshlrev_b64 v[130:131], 10, v[192:193]
	v_lshl_add_u64 v[130:131], v[130:131], 0, v[188:189]
	v_lshlrev_b64 v[198:199], 1, v[130:131]
	v_lshl_add_u64 v[130:131], s[34:35], 0, v[198:199]
	v_lshl_add_u64 v[132:133], s[92:93], 0, v[198:199]
	global_load_dwordx4 v[170:173], v[130:131], off
	global_load_dwordx4 v[174:177], v[132:133], off
	v_lshl_add_u64 v[134:135], s[6:7], 0, v[198:199]
	global_load_dwordx4 v[166:169], v[134:135], off
	global_load_dwordx4 v[158:161], v[130:131], off offset:256
	global_load_dwordx4 v[162:165], v[132:133], off offset:256
	global_load_dwordx4 v[146:149], v[134:135], off offset:256
	v_and_b32_e32 v130, 64, v205
	v_or_b32_e32 v200, v130, v181
	v_lshlrev_b32_e32 v225, 2, v200
	ds_bpermute_b32 v200, v225, v226
	v_xor_b32_e32 v131, 16, v205
	v_add_u32_e32 v130, 64, v130
	v_cmp_lt_i32_e64 s[44:45], v131, v130
	s_waitcnt lgkmcnt(0)
; __device__ __forceinline__ float bf_lo(unsigned w) { return __uint_as_float(w << 16); }
;     template <int mode> __device__ __forceinline__ void run(const f32x4 (&acc)[2][2][4][2], const Unit& u, int wr, int wc, int fr, int fq, const LAS float* sc) const {
;     ...
;                     const size_t offn = (size_t)(row0 + ((g + 1) >> 2) * HALF + ((g + 1) & 3) * 16) * D + col0;
; #pragma unroll
;                     for (int bj = 0; bj < 2; ++bj) {
;                         const size_t o = offn + bj * HALF;
;                         if (mode == 5) { xi[nb][2 * bj] = *(const f32x4*)(xin + o); xi[nb][2 * bj + 1] = *(const f32x4*)(xin + o + 4); }
;                         else { xh[nb][bj] = *(const u32x4*)(hin + o); xl[nb][bj] = *(const u32x4*)(lin + o); }
;                         if (mode == 4) pq[nb][bj] = *(const u32x4*)(ob + o);
;                     }
;                 }
;                 float s = 1.f;
;                 if (mode == 4) s = __shfl(ai ? sB : sA, m * 16 + fr);
;                 float ss = 0.f;
; #pragma unroll
;                 for (int bj = 0; bj < 2; ++bj) {
;                     u32x4 wh, wl;
; #pragma unroll
;                     for (int n = 0; n < 2; ++n) {
;                         const int q = 2 * bj + n;
;                         const unsigned h0 = n ? xh[cb][bj].z : xh[cb][bj].x, h1 = n ? xh[cb][bj].w : xh[cb][bj].y, l0 = n ? xl[cb][bj].z : xl[cb][bj].x, l1 = n ? xl[cb][bj].w : xl[cb][bj].y;
;                         f32x4 xo;
;                         if (mode == 5) xo = xi[cb][q];
;                         else { xo[0] = bf_lo(h0) + bf_lo(l0); xo[1] = bf_hi(h0) + bf_hi(l0); xo[2] = bf_lo(h1) + bf_lo(l1); xo[3] = bf_hi(h1) + bf_hi(l1); }
;                         f32x4 v;
;                         if (mode != 4) v = xo + acc[ai][bj][m][n] * alpha + bvv[q];
;                         else {
;                             const f32x4 a = acc[ai][bj][m][n] * s;
;                             const unsigned p0 = n ? pq[cb][bj].z : pq[cb][bj].x, p1 = n ? pq[cb][bj].w : pq[cb][bj].y;
;                             v[0] = xo[0] + sigmoidf_(a[0]) * bf_lo(p0); v[1] = xo[1] + sigmoidf_(a[1]) * bf_hi(p0);
;                             v[2] = xo[2] + sigmoidf_(a[2]) * bf_lo(p1); v[3] = xo[3] + sigmoidf_(a[3]) * bf_hi(p1);
;                         }
;                         const unsigned w0 = pk2(v[0], v[1]), w1 = pk2(v[2], v[3]);
	v_pk_mul_f32 v[126:127], v[126:127], v[200:201] op_sel_hi:[1,0]
	v_cndmask_b32_e64 v131, v205, v131, s[44:45]
	v_lshlrev_b32_e32 v191, 2, v131
	v_xor_b32_e32 v131, 32, v205
	v_mul_f32_e32 v126, 0xbfb8aa3b, v126
	v_cmp_lt_i32_e64 s[44:45], v131, v130
	v_exp_f32_e32 v126, v126
	v_pk_mul_f32 v[128:129], v[128:129], v[200:201] op_sel_hi:[1,0]
	v_cndmask_b32_e64 v130, v205, v131, s[44:45]
	v_lshlrev_b32_e32 v224, 2, v130
	v_lshlrev_b64 v[130:131], 10, v[194:195]
	v_lshl_add_u64 v[130:131], v[130:131], 0, v[188:189]
	v_lshlrev_b64 v[196:197], 1, v[130:131]
	v_add_f32_e32 v126, 1.0, v126
	v_lshl_add_u64 v[130:131], s[34:35], 0, v[196:197]
	v_lshl_add_u64 v[132:133], s[92:93], 0, v[196:197]
	v_lshl_add_u64 v[228:229], s[6:7], 0, v[196:197]
	v_rcp_f32_e32 v126, v126
	global_load_dwordx4 v[150:153], v[130:131], off
	global_load_dwordx4 v[154:157], v[132:133], off
	global_load_dwordx4 v[142:145], v[228:229], off
	global_load_dwordx4 v[134:137], v[130:131], off offset:256
	global_load_dwordx4 v[138:141], v[132:133], off offset:256
	s_nop 0
	global_load_dwordx4 v[130:133], v[228:229], off offset:256
	v_pk_mul_f32 v[122:123], v[122:123], v[200:201] op_sel_hi:[1,0]
	v_pk_mul_f32 v[124:125], v[124:125], v[200:201] op_sel_hi:[1,0]
	v_mul_f32_e32 v122, 0xbfb8aa3b, v122
	v_exp_f32_e32 v122, v122
	v_pk_mul_f32 v[118:119], v[118:119], v[200:201] op_sel_hi:[1,0]
	v_pk_mul_f32 v[120:121], v[120:121], v[200:201] op_sel_hi:[1,0]
	v_mul_f32_e32 v118, 0xbfb8aa3b, v118
	v_add_f32_e32 v122, 1.0, v122
	v_rcp_f32_e32 v122, v122
	v_exp_f32_e32 v118, v118
	v_pk_mul_f32 v[114:115], v[114:115], v[200:201] op_sel_hi:[1,0]
	v_pk_mul_f32 v[116:117], v[116:117], v[200:201] op_sel_hi:[1,0]
	v_mul_f32_e32 v114, 0xbfb8aa3b, v114
	v_add_f32_e32 v118, 1.0, v118
	v_rcp_f32_e32 v118, v118
	v_exp_f32_e32 v114, v114
	s_lshl_b32 s44, s2, 2
	s_ashr_i32 s45, s44, 31
	v_add_f32_e32 v114, 1.0, v114
	v_rcp_f32_e32 v114, v114
	s_waitcnt vmcnt(11)
	v_lshlrev_b32_e32 v227, 16, v170
	s_waitcnt vmcnt(10)
	v_lshlrev_b32_e32 v228, 16, v174
	v_and_b32_e32 v174, 0xffff0000, v174
	v_and_b32_e32 v170, 0xffff0000, v170
	v_add_f32_e32 v227, v228, v227
	v_add_f32_e32 v170, v174, v170
	v_lshlrev_b32_e32 v174, 16, v171
	v_lshlrev_b32_e32 v228, 16, v175
	v_and_b32_e32 v175, 0xffff0000, v175
	v_and_b32_e32 v171, 0xffff0000, v171
	v_add_f32_e32 v171, v175, v171
	s_waitcnt vmcnt(9)
	v_lshlrev_b32_e32 v175, 16, v166
	v_fmac_f32_e32 v227, v126, v175
	v_mul_f32_e32 v126, 0xbfb8aa3b, v127
	v_exp_f32_e32 v126, v126
	v_and_b32_e32 v127, 0xffff0000, v166
	v_add_f32_e32 v174, v228, v174
	v_add_f32_e32 v126, 1.0, v126
	v_rcp_f32_e32 v126, v126
	s_nop 0
	v_fmac_f32_e32 v170, v126, v127
	v_mul_f32_e32 v126, 0xbfb8aa3b, v128
	v_exp_f32_e32 v126, v126
	v_lshlrev_b32_e32 v127, 16, v167
	v_add_f32_e32 v126, 1.0, v126
	v_rcp_f32_e32 v126, v126
	s_nop 0
	v_fmac_f32_e32 v174, v126, v127
	v_mul_f32_e32 v126, 0xbfb8aa3b, v129
	v_exp_f32_e32 v126, v126
	v_and_b32_e32 v127, 0xffff0000, v167
	v_add_f32_e32 v126, 1.0, v126
	v_rcp_f32_e32 v126, v126
	s_nop 0
	v_fmac_f32_e32 v171, v126, v127
	v_cvt_pk_bf16_f32 v126, v227, v170
	v_cvt_pk_bf16_f32 v127, v174, v171
	s_nop 0
	v_lshlrev_b32_e32 v128, 16, v126
	v_and_b32_e32 v129, 0xffff0000, v126
	v_sub_f32_e32 v128, v227, v128
	v_sub_f32_e32 v129, v170, v129
	v_cvt_pk_bf16_f32 v166, v128, v129
	v_lshlrev_b32_e32 v128, 16, v127
	v_and_b32_e32 v129, 0xffff0000, v127
	v_sub_f32_e32 v128, v174, v128
	v_sub_f32_e32 v129, v171, v129
	v_cvt_pk_bf16_f32 v167, v128, v129
	v_mul_f32_e32 v128, v170, v170
	v_mul_f32_e32 v129, v171, v171
	v_fmac_f32_e32 v128, v227, v227
	v_fmac_f32_e32 v129, v174, v174
	v_add_f32_e32 v170, v128, v129
	v_lshlrev_b32_e32 v128, 16, v172
	v_lshlrev_b32_e32 v129, 16, v176
	v_add_f32_e32 v171, v129, v128
	v_and_b32_e32 v128, 0xffff0000, v176
	v_and_b32_e32 v129, 0xffff0000, v172
	v_add_f32_e32 v172, v128, v129
	v_lshlrev_b32_e32 v128, 16, v173
	v_lshlrev_b32_e32 v129, 16, v177
	v_add_f32_e32 v174, v129, v128
	v_and_b32_e32 v128, 0xffff0000, v177
	v_and_b32_e32 v129, 0xffff0000, v173
	v_add_f32_e32 v173, v128, v129
	v_lshlrev_b32_e32 v128, 16, v168
	v_fmac_f32_e32 v171, v122, v128
	v_mul_f32_e32 v122, 0xbfb8aa3b, v123
	v_exp_f32_e32 v122, v122
	v_and_b32_e32 v123, 0xffff0000, v168
	v_add_f32_e32 v122, 1.0, v122
	v_rcp_f32_e32 v122, v122
	s_nop 0
	v_fmac_f32_e32 v172, v122, v123
	v_mul_f32_e32 v122, 0xbfb8aa3b, v124
	v_exp_f32_e32 v122, v122
	v_lshlrev_b32_e32 v123, 16, v169
	v_cvt_pk_bf16_f32 v128, v171, v172
	v_add_f32_e32 v122, 1.0, v122
	v_rcp_f32_e32 v122, v122
	s_nop 0
	v_fmac_f32_e32 v174, v122, v123
	v_mul_f32_e32 v122, 0xbfb8aa3b, v125
	v_exp_f32_e32 v122, v122
	v_and_b32_e32 v123, 0xffff0000, v169
	v_lshl_add_u64 v[124:125], s[28:29], 0, v[198:199]
	v_add_f32_e32 v122, 1.0, v122
	v_rcp_f32_e32 v122, v122
	s_nop 0
	v_fmac_f32_e32 v173, v122, v123
	v_lshlrev_b32_e32 v122, 16, v128
	v_and_b32_e32 v123, 0xffff0000, v128
	v_sub_f32_e32 v122, v171, v122
	v_sub_f32_e32 v123, v172, v123
	v_cvt_pk_bf16_f32 v129, v174, v173
	v_cvt_pk_bf16_f32 v168, v122, v123
	s_nop 0
	v_lshlrev_b32_e32 v122, 16, v129
	v_and_b32_e32 v123, 0xffff0000, v129
	v_sub_f32_e32 v122, v174, v122
	v_sub_f32_e32 v123, v173, v123
	v_cvt_pk_bf16_f32 v169, v122, v123
	v_mul_f32_e32 v122, v172, v172
	v_mul_f32_e32 v123, v173, v173
	v_fmac_f32_e32 v122, v171, v171
	v_fmac_f32_e32 v123, v174, v174
	v_add_f32_e32 v122, v122, v123
	v_add_f32_e32 v170, v170, v122
	v_lshl_add_u64 v[122:123], s[10:11], 0, v[198:199]
	global_store_dwordx4 v[122:123], v[126:129], off
	global_store_dwordx4 v[124:125], v[166:169], off
	s_waitcnt vmcnt(10)
; __device__ __forceinline__ float bf_lo(unsigned w) { return __uint_as_float(w << 16); }
; __device__ __forceinline__ float bf_hi(unsigned w) { return __uint_as_float(w & 0xffff0000u); }
;     template <int mode> __device__ __forceinline__ void run(const f32x4 (&acc)[2][2][4][2], const Unit& u, int wr, int wc, int fr, int fq, const LAS float* sc) const {
;     ...
;                 for (int bj = 0; bj < 2; ++bj) {
;                     u32x4 wh, wl;
; #pragma unroll
;                     for (int n = 0; n < 2; ++n) {
;                         const int q = 2 * bj + n;
;                         const unsigned h0 = n ? xh[cb][bj].z : xh[cb][bj].x, h1 = n ? xh[cb][bj].w : xh[cb][bj].y, l0 = n ? xl[cb][bj].z : xl[cb][bj].x, l1 = n ? xl[cb][bj].w : xl[cb][bj].y;
;                         f32x4 xo;
;                         if (mode == 5) xo = xi[cb][q];
;                         else { xo[0] = bf_lo(h0) + bf_lo(l0); xo[1] = bf_hi(h0) + bf_hi(l0); xo[2] = bf_lo(h1) + bf_lo(l1); xo[3] = bf_hi(h1) + bf_hi(l1); }
;                         f32x4 v;
;                         if (mode != 4) v = xo + acc[ai][bj][m][n] * alpha + bvv[q];
;                         else {
;                             const f32x4 a = acc[ai][bj][m][n] * s;
;                             const unsigned p0 = n ? pq[cb][bj].z : pq[cb][bj].x, p1 = n ? pq[cb][bj].w : pq[cb][bj].y;
;                             v[0] = xo[0] + sigmoidf_(a[0]) * bf_lo(p0); v[1] = xo[1] + sigmoidf_(a[1]) * bf_hi(p0);
;                             v[2] = xo[2] + sigmoidf_(a[2]) * bf_lo(p1); v[3] = xo[3] + sigmoidf_(a[3]) * bf_hi(p1);
;                         }
;                         const unsigned w0 = pk2(v[0], v[1]), w1 = pk2(v[2], v[3]);
;                         const unsigned m0 = pk2(v[0] - bf_lo(w0), v[1] - bf_hi(w0)), m1 = pk2(v[2] - bf_lo(w1), v[3] - bf_hi(w1));
;                         if (n == 0) { wh.x = w0; wh.y = w1; wl.x = m0; wl.y = m1; } else { wh.z = w0; wh.w = w1; wl.z = m0; wl.w = m1; }
;                         ss += (v[0] * v[0] + v[1] * v[1]) + (v[2] * v[2] + v[3] * v[3]);
;                     }
;                     *(u32x4*)(xb + off + bj * HALF) = wh;
;                     *(u32x4*)(lout + off + bj * HALF) = wl;
;                 }
;                 ss += __shfl_xor(ss, 16); ss += __shfl_xor(ss, 32);
;                 if (fq == 0) ssq_out[(size_t)row * 16 + u.pn * 4 + wc] = ss;
	v_lshlrev_b32_e32 v126, 16, v158
	s_waitcnt vmcnt(9)
	v_lshlrev_b32_e32 v127, 16, v162
	v_add_f32_e32 v128, v127, v126
	v_and_b32_e32 v126, 0xffff0000, v162
	v_and_b32_e32 v127, 0xffff0000, v158
	v_add_f32_e32 v129, v126, v127
	v_lshlrev_b32_e32 v126, 16, v159
	v_lshlrev_b32_e32 v127, 16, v163
	v_add_f32_e32 v158, v127, v126
	v_and_b32_e32 v126, 0xffff0000, v163
	v_and_b32_e32 v127, 0xffff0000, v159
	v_add_f32_e32 v159, v126, v127
	s_waitcnt vmcnt(8)
	v_lshlrev_b32_e32 v126, 16, v146
	v_fmac_f32_e32 v128, v118, v126
	v_mul_f32_e32 v118, 0xbfb8aa3b, v119
	v_exp_f32_e32 v118, v118
	v_and_b32_e32 v119, 0xffff0000, v146
	v_add_f32_e32 v118, 1.0, v118
	v_rcp_f32_e32 v118, v118
	s_nop 0
	v_fmac_f32_e32 v129, v118, v119
	v_mul_f32_e32 v118, 0xbfb8aa3b, v120
	v_exp_f32_e32 v118, v118
	v_lshlrev_b32_e32 v119, 16, v147
	v_add_f32_e32 v118, 1.0, v118
	v_rcp_f32_e32 v118, v118
	s_nop 0
	v_fmac_f32_e32 v158, v118, v119
	v_mul_f32_e32 v118, 0xbfb8aa3b, v121
	v_exp_f32_e32 v118, v118
	v_and_b32_e32 v119, 0xffff0000, v147
	v_add_f32_e32 v118, 1.0, v118
	v_rcp_f32_e32 v118, v118
	s_nop 0
	v_fmac_f32_e32 v159, v118, v119
	v_cvt_pk_bf16_f32 v118, v128, v129
	v_cvt_pk_bf16_f32 v119, v158, v159
	s_nop 0
	v_lshlrev_b32_e32 v120, 16, v118
	v_and_b32_e32 v121, 0xffff0000, v118
	v_sub_f32_e32 v120, v128, v120
	v_sub_f32_e32 v121, v129, v121
	v_cvt_pk_bf16_f32 v126, v120, v121
	v_lshlrev_b32_e32 v120, 16, v119
	v_and_b32_e32 v121, 0xffff0000, v119
	v_sub_f32_e32 v120, v158, v120
	v_sub_f32_e32 v121, v159, v121
	v_cvt_pk_bf16_f32 v127, v120, v121
	v_mul_f32_e32 v120, v129, v129
	v_mul_f32_e32 v121, v159, v159
	v_fmac_f32_e32 v120, v128, v128
	v_fmac_f32_e32 v121, v158, v158
	v_add_f32_e32 v120, v120, v121
	v_add_f32_e32 v146, v120, v170
	v_lshlrev_b32_e32 v120, 16, v160
	v_lshlrev_b32_e32 v121, 16, v164
	v_add_f32_e32 v147, v121, v120
	v_and_b32_e32 v120, 0xffff0000, v164
	v_and_b32_e32 v121, 0xffff0000, v160
	v_add_f32_e32 v158, v120, v121
	v_lshlrev_b32_e32 v120, 16, v161
	v_lshlrev_b32_e32 v121, 16, v165
	v_add_f32_e32 v159, v121, v120
	v_and_b32_e32 v120, 0xffff0000, v165
	v_and_b32_e32 v121, 0xffff0000, v161
	v_add_f32_e32 v160, v120, v121
	v_lshlrev_b32_e32 v120, 16, v148
	v_fmac_f32_e32 v147, v114, v120
	v_mul_f32_e32 v114, 0xbfb8aa3b, v115
	v_exp_f32_e32 v114, v114
	v_and_b32_e32 v115, 0xffff0000, v148
	v_add_f32_e32 v114, 1.0, v114
	v_rcp_f32_e32 v114, v114
	s_nop 0
	v_fmac_f32_e32 v158, v114, v115
	v_mul_f32_e32 v114, 0xbfb8aa3b, v116
	v_exp_f32_e32 v114, v114
	v_lshlrev_b32_e32 v115, 16, v149
	v_cvt_pk_bf16_f32 v120, v147, v158
	v_add_f32_e32 v114, 1.0, v114
	v_rcp_f32_e32 v114, v114
	s_nop 0
	v_fmac_f32_e32 v159, v114, v115
	v_mul_f32_e32 v114, 0xbfb8aa3b, v117
	v_exp_f32_e32 v114, v114
	v_and_b32_e32 v115, 0xffff0000, v149
	v_add_f32_e32 v114, 1.0, v114
	v_rcp_f32_e32 v114, v114
	s_nop 0
	v_fmac_f32_e32 v160, v114, v115
	v_lshlrev_b32_e32 v114, 16, v120
	v_and_b32_e32 v115, 0xffff0000, v120
	v_sub_f32_e32 v114, v147, v114
	v_sub_f32_e32 v115, v158, v115
	v_cvt_pk_bf16_f32 v121, v159, v160
	v_cvt_pk_bf16_f32 v128, v114, v115
	s_nop 0
	v_lshlrev_b32_e32 v114, 16, v121
	v_and_b32_e32 v115, 0xffff0000, v121
	v_sub_f32_e32 v114, v159, v114
	v_sub_f32_e32 v115, v160, v115
	v_cvt_pk_bf16_f32 v129, v114, v115
	v_mul_f32_e32 v114, v158, v158
	v_mul_f32_e32 v115, v160, v160
	v_fmac_f32_e32 v114, v147, v147
	v_fmac_f32_e32 v115, v159, v159
	v_add_f32_e32 v114, v114, v115
	v_add_f32_e32 v114, v114, v146
	ds_bpermute_b32 v115, v191, v114
	global_store_dwordx4 v[122:123], v[118:121], off offset:256
	global_store_dwordx4 v[124:125], v[126:129], off offset:256
	s_waitcnt lgkmcnt(0)
	v_add_f32_e32 v114, v114, v115
	ds_bpermute_b32 v115, v224, v114
	s_and_saveexec_b64 s[4:5], s[40:41]
	s_cbranch_execz .LBB0_162
	v_lshlrev_b64 v[116:117], 6, v[192:193]
	v_lshl_add_u64 v[116:117], s[62:63], 0, v[116:117]
	v_lshl_add_u64 v[116:117], s[44:45], 2, v[116:117]
	s_lshl_b32 s24, s20, 2
	v_lshl_add_u64 v[116:117], v[116:117], 0, s[24:25]
	s_waitcnt lgkmcnt(0)
	v_add_f32_e32 v114, v114, v115
	global_store_dword v[116:117], v114, off

; #define PG8_STAGE(bufoff, gbase, voff) do { _Pragma("unroll") for (int _i = 0; _i < 2; ++_i) \
;         __builtin_amdgcn_global_load_lds((const unsigned*)((const char*)(gbase) + (voff)[_i]), (LAS unsigned*)(lds + (bufoff) + ldsw + _i * 8192), 16, 0, 0); } while (0)
; #define PG8_LDA(dst, b, h) do { _Pragma("unroll") for (int m = 0; m < 4; ++m) _Pragma("unroll") for (int k = 0; k < 2; ++k) dst[m][k] = *(const LAS bf16x8*)(lds + PG8_SA(b, h) + aoff + m * 2048 + k * 1024); } while (0)
; #define PG8_LDB(dst, b, h) do { _Pragma("unroll") for (int n = 0; n < 2; ++n) _Pragma("unroll") for (int k = 0; k < 2; ++k) dst[n][k] = *(const LAS bf16x8*)(lds + PG8_SB(b, h) + boff + n * 2048 + k * 1024); } while (0)
; #define PG8_MMA(ai, bj, At, Bt) do { __builtin_amdgcn_s_setprio(1); _Pragma("unroll") for (int m = 0; m < 4; ++m) _Pragma("unroll") for (int n = 0; n < 2; ++n) _Pragma("unroll") for (int k = 0; k < 2; ++k) \
;         acc[ai][bj][m][n] = __builtin_amdgcn_mfma_f32_16x16x32_bf16(Bt[n][k], At[m][k], acc[ai][bj][m][n], 0, 0, 0); __builtin_amdgcn_s_setprio(0); } while (0)
; #define PG8_WAIT_V(n) asm volatile("s_waitcnt vmcnt(" #n ")" ::: "memory")
; #define PG8_WAIT_L(n) asm volatile("s_waitcnt lgkmcnt(" #n ")" ::: "memory")
; #define PG8_BAR __builtin_amdgcn_s_barrier()
; template <int MODE, class EpiT, class Sched>
; __device__ __forceinline__ void gemm_phase(LAS unsigned char* lds, const Gemm g, const Sched& S, const EpiT& E) {
;     ...
;             const bool last = (t == nt - 2);
;             const char* a1 = cA + (size_t)(t + 1) * kstep;
;             const char* a2 = last ? nA : cA + (size_t)(t + 2) * kstep; const char* b2 = last ? nB : cB + (size_t)(t + 2) * kstep;
;             const char* a3 = a2 + kstep; const char* b3 = b2 + kstep;
;             PG8_LDB(B0, 0, 0); PG8_SCHED; PG8_LDA(At, 0, 0); PG8_STAGE(PG8_SA(1, 1), a1 + hstep, voffA);
;             PG8_WAIT_L(8); PG8_BAR; PG8_WAIT_L(0); PG8_MMA(0, 0, At, B0); PG8_BAR; PG8_SCHED;
;             PG8_LDB(B1, 0, 1); PG8_STAGE(PG8_SB(0, 0), b2, voffB);
;             PG8_BAR; PG8_WAIT_L(0); PG8_MMA(0, 1, At, B1); PG8_BAR;
;             PG8_LDA(At, 0, 1); PG8_STAGE(PG8_SA(0, 0), a2, voffA);
;             PG8_BAR; PG8_WAIT_L(0); PG8_MMA(1, 0, At, B0); PG8_BAR; PG8_SCHED;
;             PG8_STAGE(PG8_SB(0, 1), b2 + hstep, voffB);
;             PG8_WAIT_V(6); PG8_BAR; PG8_MMA(1, 1, At, B1); PG8_BAR;
.LBB0_195:
	s_add_i32 vcc_lo, s44, 2
	s_add_u32 s52, s4, 0x80
	s_addc_u32 s45, s5, 0
	s_add_i32 s58, 0, 0x10000
	v_add_u32_e32 v74, s58, v194
	ds_read_b128 v[58:61], v74
	ds_read_b128 v[62:65], v74 offset:1024
	ds_read_b128 v[70:73], v74 offset:2048
	ds_read_b128 v[74:77], v74 offset:3072
	s_cmp_eq_u32 s75, s44
	s_cselect_b32 s44, s68, s52
	s_cselect_b32 s45, s69, s45
	s_cselect_b32 s53, s47, s90
	s_cselect_b32 s52, s46, s89
	v_lshl_add_u64 v[188:189], s[4:5], 0, v[176:177]
	s_add_i32 m0, s21, 0xc000
	ds_read_b128 v[138:141], v196
	ds_read_b128 v[142:145], v196 offset:1024
	ds_read_b128 v[146:149], v196 offset:2048
	ds_read_b128 v[150:153], v196 offset:3072
	ds_read_b128 v[162:165], v196 offset:4096
	ds_read_b128 v[166:169], v196 offset:5120
	ds_read_b128 v[170:173], v196 offset:6144
	ds_read_b128 v[184:187], v196 offset:7168
	global_load_lds_dwordx4 v[188:189], off
	v_lshl_add_u64 v[188:189], s[4:5], 0, v[182:183]
	s_add_i32 m0, s21, 0xe000
	s_nop 0
	global_load_lds_dwordx4 v[188:189], off
	s_waitcnt lgkmcnt(8)
	s_barrier
	s_waitcnt lgkmcnt(0)
	v_mfma_f32_16x16x32_bf16 v[158:161], v[58:61], v[138:141], v[158:161]
	v_mfma_f32_16x16x32_bf16 v[154:157], v[70:73], v[138:141], v[154:157]
	v_mfma_f32_16x16x32_bf16 v[126:129], v[58:61], v[146:149], v[126:129]
	v_mfma_f32_16x16x32_bf16 v[122:125], v[70:73], v[146:149], v[122:125]
	v_mfma_f32_16x16x32_bf16 v[110:113], v[58:61], v[162:165], v[110:113]
	v_mfma_f32_16x16x32_bf16 v[106:109], v[70:73], v[162:165], v[106:109]
	v_mfma_f32_16x16x32_bf16 v[94:97], v[58:61], v[170:173], v[94:97]
	v_mfma_f32_16x16x32_bf16 v[90:93], v[70:73], v[170:173], v[90:93]
	v_mfma_f32_16x16x32_bf16 v[158:161], v[62:65], v[142:145], v[158:161]
	v_mfma_f32_16x16x32_bf16 v[154:157], v[74:77], v[142:145], v[154:157]
	v_mfma_f32_16x16x32_bf16 v[126:129], v[62:65], v[150:153], v[126:129]
	v_mfma_f32_16x16x32_bf16 v[122:125], v[74:77], v[150:153], v[122:125]
	v_mfma_f32_16x16x32_bf16 v[110:113], v[62:65], v[166:169], v[110:113]
	s_barrier
	v_mfma_f32_16x16x32_bf16 v[106:109], v[74:77], v[166:169], v[106:109]
	v_mfma_f32_16x16x32_bf16 v[94:97], v[62:65], v[184:187], v[94:97]
	v_mfma_f32_16x16x32_bf16 v[90:93], v[74:77], v[184:187], v[90:93]
	s_add_i32 s59, 0, 0x14000
	v_add_u32_e32 v192, s59, v194
	s_add_i32 s58, s58, s20
	ds_read_b128 v[188:191], v192
	ds_read_b128 v[220:223], v192 offset:1024
	ds_read_b128 v[224:227], v192 offset:2048
	ds_read_b128 v[228:231], v192 offset:3072
	v_lshl_add_u64 v[192:193], s[52:53], 0, v[0:1]
	s_mov_b32 m0, s58
	v_lshl_add_u64 v[198:199], s[52:53], 0, v[174:175]
	global_load_lds_dwordx4 v[192:193], off
	s_add_i32 m0, s58, 0x2000
	s_nop 0
	global_load_lds_dwordx4 v[198:199], off
	s_barrier
	s_waitcnt lgkmcnt(0)
	v_mfma_f32_16x16x32_bf16 v[134:137], v[188:191], v[138:141], v[134:137]
	v_mfma_f32_16x16x32_bf16 v[130:133], v[224:227], v[138:141], v[130:133]
	v_mfma_f32_16x16x32_bf16 v[118:121], v[188:191], v[146:149], v[118:121]
	v_mfma_f32_16x16x32_bf16 v[114:117], v[224:227], v[146:149], v[114:117]
	v_mfma_f32_16x16x32_bf16 v[102:105], v[188:191], v[162:165], v[102:105]
	v_mfma_f32_16x16x32_bf16 v[98:101], v[224:227], v[162:165], v[98:101]
	v_mfma_f32_16x16x32_bf16 v[86:89], v[188:191], v[170:173], v[86:89]
	v_mfma_f32_16x16x32_bf16 v[82:85], v[224:227], v[170:173], v[82:85]
	v_mfma_f32_16x16x32_bf16 v[134:137], v[220:223], v[142:145], v[134:137]
	v_mfma_f32_16x16x32_bf16 v[130:133], v[228:231], v[142:145], v[130:133]
	v_mfma_f32_16x16x32_bf16 v[118:121], v[220:223], v[150:153], v[118:121]
	v_mfma_f32_16x16x32_bf16 v[114:117], v[228:231], v[150:153], v[114:117]
	v_mfma_f32_16x16x32_bf16 v[102:105], v[220:223], v[166:169], v[102:105]
	s_barrier
	v_mfma_f32_16x16x32_bf16 v[98:101], v[228:231], v[166:169], v[98:101]
	v_mfma_f32_16x16x32_bf16 v[86:89], v[220:223], v[184:187], v[86:89]
	v_mfma_f32_16x16x32_bf16 v[82:85], v[228:231], v[184:187], v[82:85]
	s_mov_b32 m0, s21
	v_lshl_add_u64 v[232:233], s[44:45], 0, v[0:1]
	ds_read_b128 v[138:141], v196 offset:16384
	ds_read_b128 v[142:145], v196 offset:17408
	ds_read_b128 v[146:149], v196 offset:18432
	ds_read_b128 v[150:153], v196 offset:19456
	ds_read_b128 v[162:165], v196 offset:20480
	ds_read_b128 v[166:169], v196 offset:21504
	ds_read_b128 v[170:173], v196 offset:22528
	ds_read_b128 v[184:187], v196 offset:23552
	global_load_lds_dwordx4 v[232:233], off
	v_lshl_add_u64 v[234:235], s[44:45], 0, v[174:175]
	s_mov_b32 m0, s50
	s_nop 0
	global_load_lds_dwordx4 v[234:235], off
	s_barrier
	s_waitcnt lgkmcnt(0)
	v_mfma_f32_16x16x32_bf16 v[78:81], v[58:61], v[138:141], v[78:81]
	v_mfma_f32_16x16x32_bf16 v[66:69], v[70:73], v[138:141], v[66:69]
	v_mfma_f32_16x16x32_bf16 v[46:49], v[58:61], v[146:149], v[46:49]
	v_mfma_f32_16x16x32_bf16 v[42:45], v[70:73], v[146:149], v[42:45]
	v_mfma_f32_16x16x32_bf16 v[30:33], v[58:61], v[162:165], v[30:33]
	v_mfma_f32_16x16x32_bf16 v[26:29], v[70:73], v[162:165], v[26:29]
	v_mfma_f32_16x16x32_bf16 v[14:17], v[58:61], v[170:173], v[14:17]
	v_mfma_f32_16x16x32_bf16 v[10:13], v[70:73], v[170:173], v[10:13]
	v_mfma_f32_16x16x32_bf16 v[78:81], v[62:65], v[142:145], v[78:81]
	v_mfma_f32_16x16x32_bf16 v[66:69], v[74:77], v[142:145], v[66:69]
	v_mfma_f32_16x16x32_bf16 v[46:49], v[62:65], v[150:153], v[46:49]
	v_mfma_f32_16x16x32_bf16 v[42:45], v[74:77], v[150:153], v[42:45]
	v_mfma_f32_16x16x32_bf16 v[30:33], v[62:65], v[166:169], v[30:33]
	s_barrier
	v_mfma_f32_16x16x32_bf16 v[26:29], v[74:77], v[166:169], v[26:29]
	v_mfma_f32_16x16x32_bf16 v[14:17], v[62:65], v[184:187], v[14:17]
	v_mfma_f32_16x16x32_bf16 v[10:13], v[74:77], v[184:187], v[10:13]
	s_add_u32 s52, s52, s38
	s_addc_u32 s53, s53, 0
	s_add_i32 s58, s59, s20
	v_lshl_add_u64 v[236:237], s[52:53], 0, v[0:1]
	s_mov_b32 m0, s58
	v_lshl_add_u64 v[238:239], s[52:53], 0, v[174:175]
	global_load_lds_dwordx4 v[236:237], off
	s_add_i32 m0, s58, 0x2000
	s_nop 0
	global_load_lds_dwordx4 v[238:239], off
	s_waitcnt vmcnt(6)
	s_barrier
; #define PG8_STAGE(bufoff, gbase, voff) do { _Pragma("unroll") for (int _i = 0; _i < 2; ++_i) \
;         __builtin_amdgcn_global_load_lds((const unsigned*)((const char*)(gbase) + (voff)[_i]), (LAS unsigned*)(lds + (bufoff) + ldsw + _i * 8192), 16, 0, 0); } while (0)
; #define PG8_LDA(dst, b, h) do { _Pragma("unroll") for (int m = 0; m < 4; ++m) _Pragma("unroll") for (int k = 0; k < 2; ++k) dst[m][k] = *(const LAS bf16x8*)(lds + PG8_SA(b, h) + aoff + m * 2048 + k * 1024); } while (0)
; #define PG8_LDB(dst, b, h) do { _Pragma("unroll") for (int n = 0; n < 2; ++n) _Pragma("unroll") for (int k = 0; k < 2; ++k) dst[n][k] = *(const LAS bf16x8*)(lds + PG8_SB(b, h) + boff + n * 2048 + k * 1024); } while (0)
; #define PG8_MMA(ai, bj, At, Bt) do { __builtin_amdgcn_s_setprio(1); _Pragma("unroll") for (int m = 0; m < 4; ++m) _Pragma("unroll") for (int n = 0; n < 2; ++n) _Pragma("unroll") for (int k = 0; k < 2; ++k) \
;         acc[ai][bj][m][n] = __builtin_amdgcn_mfma_f32_16x16x32_bf16(Bt[n][k], At[m][k], acc[ai][bj][m][n], 0, 0, 0); __builtin_amdgcn_s_setprio(0); } while (0)
; #define PG8_WAIT_V(n) asm volatile("s_waitcnt vmcnt(" #n ")" ::: "memory")
; #define PG8_WAIT_L(n) asm volatile("s_waitcnt lgkmcnt(" #n ")" ::: "memory")
; #define PG8_BAR __builtin_amdgcn_s_barrier()
; #define PG8_SCHED __builtin_amdgcn_sched_barrier(0)
; template <int MODE, class EpiT, class Sched>
; __device__ __forceinline__ void gemm_phase(LAS unsigned char* lds, const Gemm g, const Sched& S, const EpiT& E) {
;     ...
;             PG8_WAIT_V(6); PG8_BAR; PG8_MMA(1, 1, At, B1); PG8_BAR;
;             PG8_LDB(B0, 1, 0); PG8_SCHED; PG8_LDA(At, 1, 0); PG8_STAGE(PG8_SA(0, 1), a2 + hstep, voffA);
;             PG8_WAIT_L(8); PG8_BAR; PG8_WAIT_L(0); PG8_MMA(0, 0, At, B0); PG8_BAR; PG8_SCHED;
;             PG8_LDB(B1, 1, 1); PG8_STAGE(PG8_SB(1, 0), b3, voffB);
;             PG8_BAR; PG8_WAIT_L(0); PG8_MMA(0, 1, At, B1); PG8_BAR;
	v_mfma_f32_16x16x32_bf16 v[54:57], v[188:191], v[138:141], v[54:57]
	v_mfma_f32_16x16x32_bf16 v[50:53], v[224:227], v[138:141], v[50:53]
	v_mfma_f32_16x16x32_bf16 v[38:41], v[188:191], v[146:149], v[38:41]
	v_mfma_f32_16x16x32_bf16 v[34:37], v[224:227], v[146:149], v[34:37]
	v_mfma_f32_16x16x32_bf16 v[22:25], v[188:191], v[162:165], v[22:25]
	v_mfma_f32_16x16x32_bf16 v[18:21], v[224:227], v[162:165], v[18:21]
	v_mfma_f32_16x16x32_bf16 v[6:9], v[188:191], v[170:173], v[6:9]
	v_mfma_f32_16x16x32_bf16 v[2:5], v[224:227], v[170:173], v[2:5]
	v_mfma_f32_16x16x32_bf16 v[54:57], v[220:223], v[142:145], v[54:57]
	v_mfma_f32_16x16x32_bf16 v[50:53], v[228:231], v[142:145], v[50:53]
	v_mfma_f32_16x16x32_bf16 v[38:41], v[220:223], v[150:153], v[38:41]
	v_mfma_f32_16x16x32_bf16 v[34:37], v[228:231], v[150:153], v[34:37]
	v_mfma_f32_16x16x32_bf16 v[22:25], v[220:223], v[166:169], v[22:25]
	s_barrier
	v_mfma_f32_16x16x32_bf16 v[18:21], v[228:231], v[166:169], v[18:21]
	v_mfma_f32_16x16x32_bf16 v[6:9], v[220:223], v[184:187], v[6:9]
	v_mfma_f32_16x16x32_bf16 v[2:5], v[228:231], v[184:187], v[2:5]
	s_add_i32 s52, 0, 0x18000
	v_add_u32_e32 v74, s52, v194
	ds_read_b128 v[58:61], v74
	ds_read_b128 v[62:65], v74 offset:1024
	ds_read_b128 v[70:73], v74 offset:2048
	ds_read_b128 v[74:77], v74 offset:3072
	s_add_u32 s44, s44, s38
	s_addc_u32 s45, s45, 0
	s_mov_b32 m0, s51
	v_lshl_add_u64 v[188:189], s[44:45], 0, v[0:1]
	ds_read_b128 v[138:141], v196 offset:32768
	ds_read_b128 v[142:145], v196 offset:33792
	ds_read_b128 v[146:149], v196 offset:34816
	ds_read_b128 v[150:153], v196 offset:35840
	ds_read_b128 v[162:165], v196 offset:36864
	ds_read_b128 v[166:169], v196 offset:37888
	ds_read_b128 v[170:173], v196 offset:38912
	ds_read_b128 v[184:187], v196 offset:39936
	global_load_lds_dwordx4 v[188:189], off
	v_lshl_add_u64 v[188:189], s[44:45], 0, v[174:175]
	s_mov_b32 m0, s56
	s_nop 0
	global_load_lds_dwordx4 v[188:189], off
	s_waitcnt lgkmcnt(8)
	s_barrier
	s_waitcnt lgkmcnt(0)
	v_mfma_f32_16x16x32_bf16 v[158:161], v[58:61], v[138:141], v[158:161]
	v_mfma_f32_16x16x32_bf16 v[154:157], v[70:73], v[138:141], v[154:157]
	v_mfma_f32_16x16x32_bf16 v[126:129], v[58:61], v[146:149], v[126:129]
	v_mfma_f32_16x16x32_bf16 v[122:125], v[70:73], v[146:149], v[122:125]
	v_mfma_f32_16x16x32_bf16 v[110:113], v[58:61], v[162:165], v[110:113]
	v_mfma_f32_16x16x32_bf16 v[106:109], v[70:73], v[162:165], v[106:109]
	v_mfma_f32_16x16x32_bf16 v[94:97], v[58:61], v[170:173], v[94:97]
	v_mfma_f32_16x16x32_bf16 v[90:93], v[70:73], v[170:173], v[90:93]
	v_mfma_f32_16x16x32_bf16 v[158:161], v[62:65], v[142:145], v[158:161]
	v_mfma_f32_16x16x32_bf16 v[154:157], v[74:77], v[142:145], v[154:157]
	v_mfma_f32_16x16x32_bf16 v[126:129], v[62:65], v[150:153], v[126:129]
	v_mfma_f32_16x16x32_bf16 v[122:125], v[74:77], v[150:153], v[122:125]
	v_mfma_f32_16x16x32_bf16 v[110:113], v[62:65], v[166:169], v[110:113]
	s_barrier
	v_mfma_f32_16x16x32_bf16 v[106:109], v[74:77], v[166:169], v[106:109]
	v_mfma_f32_16x16x32_bf16 v[94:97], v[62:65], v[184:187], v[94:97]
	v_mfma_f32_16x16x32_bf16 v[90:93], v[74:77], v[184:187], v[90:93]
	s_add_i32 s44, 0, 0x1c000
	s_add_i32 s45, s52, s20
	v_add_u32_e32 v197, s44, v194
	v_lshl_add_u64 v[192:193], v[192:193], 0, s[76:77]
	s_mov_b32 m0, s45
	ds_read_b128 v[188:191], v197
	ds_read_b128 v[220:223], v197 offset:1024
	ds_read_b128 v[224:227], v197 offset:2048
	ds_read_b128 v[228:231], v197 offset:3072
	global_load_lds_dwordx4 v[192:193], off
	v_lshl_add_u64 v[192:193], v[198:199], 0, s[76:77]
	s_add_i32 m0, s45, 0x2000
	s_nop 0
	global_load_lds_dwordx4 v[192:193], off
	s_barrier
	s_waitcnt lgkmcnt(0)
	v_mfma_f32_16x16x32_bf16 v[134:137], v[188:191], v[138:141], v[134:137]
	v_mfma_f32_16x16x32_bf16 v[130:133], v[224:227], v[138:141], v[130:133]
	v_mfma_f32_16x16x32_bf16 v[118:121], v[188:191], v[146:149], v[118:121]
	v_mfma_f32_16x16x32_bf16 v[114:117], v[224:227], v[146:149], v[114:117]
	v_mfma_f32_16x16x32_bf16 v[102:105], v[188:191], v[162:165], v[102:105]
	v_mfma_f32_16x16x32_bf16 v[98:101], v[224:227], v[162:165], v[98:101]
	v_mfma_f32_16x16x32_bf16 v[86:89], v[188:191], v[170:173], v[86:89]
	v_mfma_f32_16x16x32_bf16 v[82:85], v[224:227], v[170:173], v[82:85]
	v_mfma_f32_16x16x32_bf16 v[134:137], v[220:223], v[142:145], v[134:137]
	v_mfma_f32_16x16x32_bf16 v[130:133], v[228:231], v[142:145], v[130:133]
	v_mfma_f32_16x16x32_bf16 v[118:121], v[220:223], v[150:153], v[118:121]
	v_mfma_f32_16x16x32_bf16 v[114:117], v[228:231], v[150:153], v[114:117]
	v_mfma_f32_16x16x32_bf16 v[102:105], v[220:223], v[166:169], v[102:105]
	s_barrier
; #define PG8_STAGE(bufoff, gbase, voff) do { _Pragma("unroll") for (int _i = 0; _i < 2; ++_i) \
;         __builtin_amdgcn_global_load_lds((const unsigned*)((const char*)(gbase) + (voff)[_i]), (LAS unsigned*)(lds + (bufoff) + ldsw + _i * 8192), 16, 0, 0); } while (0)
; #define PG8_LDA(dst, b, h) do { _Pragma("unroll") for (int m = 0; m < 4; ++m) _Pragma("unroll") for (int k = 0; k < 2; ++k) dst[m][k] = *(const LAS bf16x8*)(lds + PG8_SA(b, h) + aoff + m * 2048 + k * 1024); } while (0)
; #define PG8_MMA(ai, bj, At, Bt) do { __builtin_amdgcn_s_setprio(1); _Pragma("unroll") for (int m = 0; m < 4; ++m) _Pragma("unroll") for (int n = 0; n < 2; ++n) _Pragma("unroll") for (int k = 0; k < 2; ++k) \
;         acc[ai][bj][m][n] = __builtin_amdgcn_mfma_f32_16x16x32_bf16(Bt[n][k], At[m][k], acc[ai][bj][m][n], 0, 0, 0); __builtin_amdgcn_s_setprio(0); } while (0)
; #define PG8_WAIT_V(n) asm volatile("s_waitcnt vmcnt(" #n ")" ::: "memory")
; #define PG8_WAIT_L(n) asm volatile("s_waitcnt lgkmcnt(" #n ")" ::: "memory")
; #define PG8_BAR __builtin_amdgcn_s_barrier()
; #define PG8_SCHED __builtin_amdgcn_sched_barrier(0)
; template <int MODE, class EpiT, class Sched>
; __device__ __forceinline__ void gemm_phase(LAS unsigned char* lds, const Gemm g, const Sched& S, const EpiT& E) {
;     ...
;             PG8_BAR; PG8_WAIT_L(0); PG8_MMA(0, 1, At, B1); PG8_BAR;
;             PG8_LDA(At, 1, 1); PG8_STAGE(PG8_SA(1, 0), a3, voffA);
;             PG8_BAR; PG8_WAIT_L(0); PG8_MMA(1, 0, At, B0); PG8_BAR; PG8_SCHED;
;             PG8_STAGE(PG8_SB(1, 1), b3 + hstep, voffB);
;             PG8_WAIT_V(6); PG8_BAR; PG8_MMA(1, 1, At, B1); PG8_BAR;
	v_mfma_f32_16x16x32_bf16 v[98:101], v[228:231], v[166:169], v[98:101]
	v_mfma_f32_16x16x32_bf16 v[86:89], v[220:223], v[184:187], v[86:89]
	v_mfma_f32_16x16x32_bf16 v[82:85], v[228:231], v[184:187], v[82:85]
	s_mov_b32 m0, s61
	v_lshl_add_u64 v[192:193], v[232:233], 0, s[76:77]
	ds_read_b128 v[138:141], v196 offset:49152
	ds_read_b128 v[142:145], v196 offset:50176
	ds_read_b128 v[146:149], v196 offset:51200
	ds_read_b128 v[150:153], v196 offset:52224
	ds_read_b128 v[162:165], v196 offset:53248
	ds_read_b128 v[166:169], v196 offset:54272
	ds_read_b128 v[170:173], v196 offset:55296
	ds_read_b128 v[184:187], v196 offset:56320
	global_load_lds_dwordx4 v[192:193], off
	v_lshl_add_u64 v[192:193], v[234:235], 0, s[76:77]
	s_mov_b32 m0, s74
	s_nop 0
	global_load_lds_dwordx4 v[192:193], off
	s_barrier
	s_waitcnt lgkmcnt(0)
	v_mfma_f32_16x16x32_bf16 v[78:81], v[58:61], v[138:141], v[78:81]
	v_mfma_f32_16x16x32_bf16 v[66:69], v[70:73], v[138:141], v[66:69]
	v_mfma_f32_16x16x32_bf16 v[46:49], v[58:61], v[146:149], v[46:49]
	v_mfma_f32_16x16x32_bf16 v[42:45], v[70:73], v[146:149], v[42:45]
	v_mfma_f32_16x16x32_bf16 v[30:33], v[58:61], v[162:165], v[30:33]
	v_mfma_f32_16x16x32_bf16 v[26:29], v[70:73], v[162:165], v[26:29]
	v_mfma_f32_16x16x32_bf16 v[14:17], v[58:61], v[170:173], v[14:17]
	v_mfma_f32_16x16x32_bf16 v[10:13], v[70:73], v[170:173], v[10:13]
	v_mfma_f32_16x16x32_bf16 v[78:81], v[62:65], v[142:145], v[78:81]
	v_mfma_f32_16x16x32_bf16 v[66:69], v[74:77], v[142:145], v[66:69]
	v_mfma_f32_16x16x32_bf16 v[46:49], v[62:65], v[150:153], v[46:49]
	v_mfma_f32_16x16x32_bf16 v[42:45], v[74:77], v[150:153], v[42:45]
	v_mfma_f32_16x16x32_bf16 v[30:33], v[62:65], v[166:169], v[30:33]
	s_barrier
	v_mfma_f32_16x16x32_bf16 v[26:29], v[74:77], v[166:169], v[26:29]
	v_mfma_f32_16x16x32_bf16 v[14:17], v[62:65], v[184:187], v[14:17]
	v_mfma_f32_16x16x32_bf16 v[10:13], v[74:77], v[184:187], v[10:13]
	s_add_i32 s44, s44, s20
	v_lshl_add_u64 v[58:59], v[236:237], 0, s[76:77]
	s_mov_b32 m0, s44
	s_nop 0
	global_load_lds_dwordx4 v[58:59], off
	v_lshl_add_u64 v[58:59], v[238:239], 0, s[76:77]
	s_add_i32 m0, s44, 0x2000
	s_nop 0
	global_load_lds_dwordx4 v[58:59], off
	s_waitcnt vmcnt(6)
	s_barrier
	v_mfma_f32_16x16x32_bf16 v[54:57], v[188:191], v[138:141], v[54:57]
	v_mfma_f32_16x16x32_bf16 v[50:53], v[224:227], v[138:141], v[50:53]
	v_mfma_f32_16x16x32_bf16 v[38:41], v[188:191], v[146:149], v[38:41]
	v_mfma_f32_16x16x32_bf16 v[34:37], v[224:227], v[146:149], v[34:37]
	v_mfma_f32_16x16x32_bf16 v[22:25], v[188:191], v[162:165], v[22:25]
	v_mfma_f32_16x16x32_bf16 v[18:21], v[224:227], v[162:165], v[18:21]
	v_mfma_f32_16x16x32_bf16 v[6:9], v[188:191], v[170:173], v[6:9]
	v_mfma_f32_16x16x32_bf16 v[2:5], v[224:227], v[170:173], v[2:5]
	v_mfma_f32_16x16x32_bf16 v[54:57], v[220:223], v[142:145], v[54:57]
	v_mfma_f32_16x16x32_bf16 v[50:53], v[228:231], v[142:145], v[50:53]
	v_mfma_f32_16x16x32_bf16 v[38:41], v[220:223], v[150:153], v[38:41]
	v_mfma_f32_16x16x32_bf16 v[34:37], v[228:231], v[150:153], v[34:37]
	v_mfma_f32_16x16x32_bf16 v[22:25], v[220:223], v[166:169], v[22:25]
	s_barrier
	v_mfma_f32_16x16x32_bf16 v[18:21], v[228:231], v[166:169], v[18:21]
	v_mfma_f32_16x16x32_bf16 v[6:9], v[220:223], v[184:187], v[6:9]
	v_mfma_f32_16x16x32_bf16 v[2:5], v[228:231], v[184:187], v[2:5]
	s_add_u32 s4, s4, 0x100
	s_addc_u32 s5, s5, 0
	s_add_u32 s89, s89, 0x100
	s_addc_u32 s90, s90, 0
	s_cmp_ge_u32 vcc_lo, s60
	s_mov_b32 s44, vcc_lo
	s_cbranch_scc0 .LBB0_195
	v_lshl_or_b32 v186, s24, 8, v195
	v_ashrrev_i32_e32 v187, 31, v186
	v_mov_b32_e32 v70, 0
	v_cndmask_b32_e64 v58, 0, 1, s[78:79]
	v_lshl_add_u64 v[138:139], v[186:187], 2, s[12:13]
	v_cmp_ne_u32_e64 s[44:45], 1, v58
	s_andn2_b64 vcc, exec, s[78:79]
	v_mov_b32_e32 v74, 0
	v_mov_b32_e32 v75, v70
	v_mov_b32_e32 v184, 0
	v_mov_b32_e32 v185, v70
	s_cbranch_vccnz .LBB0_198
	global_load_dwordx4 v[74:77], v[138:139], off
	s_waitcnt vmcnt(0)
	v_mov_b32_e32 v184, v76
	v_mov_b32_e32 v185, v77

; #define PG8_STAGE(bufoff, gbase, voff) do { _Pragma("unroll") for (int _i = 0; _i < 2; ++_i) \
;         __builtin_amdgcn_global_load_lds((const unsigned*)((const char*)(gbase) + (voff)[_i]), (LAS unsigned*)(lds + (bufoff) + ldsw + _i * 8192), 16, 0, 0); } while (0)
; #define PG8_LDA(dst, b, h) do { _Pragma("unroll") for (int m = 0; m < 4; ++m) _Pragma("unroll") for (int k = 0; k < 2; ++k) dst[m][k] = *(const LAS bf16x8*)(lds + PG8_SA(b, h) + aoff + m * 2048 + k * 1024); } while (0)
; #define PG8_LDB(dst, b, h) do { _Pragma("unroll") for (int n = 0; n < 2; ++n) _Pragma("unroll") for (int k = 0; k < 2; ++k) dst[n][k] = *(const LAS bf16x8*)(lds + PG8_SB(b, h) + boff + n * 2048 + k * 1024); } while (0)
; #define PG8_MMA(ai, bj, At, Bt) do { __builtin_amdgcn_s_setprio(1); _Pragma("unroll") for (int m = 0; m < 4; ++m) _Pragma("unroll") for (int n = 0; n < 2; ++n) _Pragma("unroll") for (int k = 0; k < 2; ++k) \
;         acc[ai][bj][m][n] = __builtin_amdgcn_mfma_f32_16x16x32_bf16(Bt[n][k], At[m][k], acc[ai][bj][m][n], 0, 0, 0); __builtin_amdgcn_s_setprio(0); } while (0)
; #define PG8_WAIT_L(n) asm volatile("s_waitcnt lgkmcnt(" #n ")" ::: "memory")
; #define PG8_BAR __builtin_amdgcn_s_barrier()
; #define PG8_SCHED __builtin_amdgcn_sched_barrier(0)
; template <int MODE, class EpiT, class Sched>
; __device__ __forceinline__ void gemm_phase(LAS unsigned char* lds, const Gemm g, const Sched& S, const EpiT& E) {
;     ...
;             const bool last = (t == nt - 2);
;             const char* a1 = cA + (size_t)(t + 1) * kstep;
;             const char* a2 = last ? nA : cA + (size_t)(t + 2) * kstep; const char* b2 = last ? nB : cB + (size_t)(t + 2) * kstep;
;             const char* a3 = a2 + kstep; const char* b3 = b2 + kstep;
;             PG8_LDB(B0, 0, 0); PG8_SCHED; PG8_LDA(At, 0, 0); PG8_STAGE(PG8_SA(1, 1), a1 + hstep, voffA);
;             PG8_WAIT_L(8); PG8_BAR; PG8_WAIT_L(0); PG8_MMA(0, 0, At, B0); PG8_BAR; PG8_SCHED;
;             PG8_LDB(B1, 0, 1); PG8_STAGE(PG8_SB(0, 0), b2, voffB);
;             PG8_BAR; PG8_WAIT_L(0); PG8_MMA(0, 1, At, B1); PG8_BAR;
;             PG8_LDA(At, 0, 1); PG8_STAGE(PG8_SA(0, 0), a2, voffA);
;             PG8_BAR; PG8_WAIT_L(0); PG8_MMA(1, 0, At, B0); PG8_BAR; PG8_SCHED;
.LBB0_236:
	s_add_i32 s44, s34, 2
	s_add_u32 s38, s28, 0x80
	s_addc_u32 s35, s29, 0
	s_add_i32 s45, 0, 0x10000
	v_add_u32_e32 v136, s45, v139
	ds_read_b128 v[142:145], v136
	ds_read_b128 v[146:149], v136 offset:1024
	ds_read_b128 v[150:153], v136 offset:2048
	ds_read_b128 v[154:157], v136 offset:3072
	s_cmp_eq_u32 s52, s34
	s_cselect_b32 s34, s4, s38
	s_cselect_b32 s35, s5, s35
	s_cselect_b32 s39, s11, s43
	s_cselect_b32 s38, s10, s42
	v_lshl_add_u64 v[136:137], s[28:29], 0, v[132:133]
	s_add_i32 m0, s22, 0xc000
	ds_read_b128 v[158:161], v141
	ds_read_b128 v[162:165], v141 offset:1024
	ds_read_b128 v[166:169], v141 offset:2048
	ds_read_b128 v[170:173], v141 offset:3072
	ds_read_b128 v[174:177], v141 offset:4096
	ds_read_b128 v[182:185], v141 offset:5120
	ds_read_b128 v[186:189], v141 offset:6144
	ds_read_b128 v[190:193], v141 offset:7168
	global_load_lds_dwordx4 v[136:137], off
	v_lshl_add_u64 v[136:137], s[28:29], 0, v[134:135]
	s_add_i32 m0, s22, 0xe000
	s_nop 0
	global_load_lds_dwordx4 v[136:137], off
	s_waitcnt lgkmcnt(8)
	s_barrier
	s_waitcnt lgkmcnt(0)
	v_mfma_f32_16x16x32_bf16 v[126:129], v[142:145], v[158:161], v[126:129]
	v_mfma_f32_16x16x32_bf16 v[122:125], v[150:153], v[158:161], v[122:125]
	v_mfma_f32_16x16x32_bf16 v[118:121], v[142:145], v[166:169], v[118:121]
	v_mfma_f32_16x16x32_bf16 v[110:113], v[150:153], v[166:169], v[110:113]
	v_mfma_f32_16x16x32_bf16 v[102:105], v[142:145], v[174:177], v[102:105]
	v_mfma_f32_16x16x32_bf16 v[94:97], v[150:153], v[174:177], v[94:97]
	v_mfma_f32_16x16x32_bf16 v[86:89], v[142:145], v[186:189], v[86:89]
	v_mfma_f32_16x16x32_bf16 v[78:81], v[150:153], v[186:189], v[78:81]
	v_mfma_f32_16x16x32_bf16 v[126:129], v[146:149], v[162:165], v[126:129]
	v_mfma_f32_16x16x32_bf16 v[122:125], v[154:157], v[162:165], v[122:125]
	v_mfma_f32_16x16x32_bf16 v[118:121], v[146:149], v[170:173], v[118:121]
	v_mfma_f32_16x16x32_bf16 v[110:113], v[154:157], v[170:173], v[110:113]
	v_mfma_f32_16x16x32_bf16 v[102:105], v[146:149], v[182:185], v[102:105]
	s_barrier
	v_mfma_f32_16x16x32_bf16 v[94:97], v[154:157], v[182:185], v[94:97]
	v_mfma_f32_16x16x32_bf16 v[86:89], v[146:149], v[190:193], v[86:89]
	v_mfma_f32_16x16x32_bf16 v[78:81], v[154:157], v[190:193], v[78:81]
	s_add_i32 s58, 0, 0x14000
	v_add_u32_e32 v136, s58, v139
	s_add_i32 s45, s45, s9
	ds_read_b128 v[194:197], v136
	ds_read_b128 v[220:223], v136 offset:1024
	ds_read_b128 v[224:227], v136 offset:2048
	ds_read_b128 v[228:231], v136 offset:3072
	v_lshl_add_u64 v[136:137], s[38:39], 0, v[0:1]
	s_mov_b32 m0, s45
	v_lshl_add_u64 v[198:199], s[38:39], 0, v[130:131]
	global_load_lds_dwordx4 v[136:137], off
	s_add_i32 m0, s45, 0x2000
	s_nop 0
	global_load_lds_dwordx4 v[198:199], off
	s_barrier
	s_waitcnt lgkmcnt(0)
	v_mfma_f32_16x16x32_bf16 v[114:117], v[194:197], v[158:161], v[114:117]
	v_mfma_f32_16x16x32_bf16 v[106:109], v[224:227], v[158:161], v[106:109]
	v_mfma_f32_16x16x32_bf16 v[98:101], v[194:197], v[166:169], v[98:101]
	v_mfma_f32_16x16x32_bf16 v[90:93], v[224:227], v[166:169], v[90:93]
	v_mfma_f32_16x16x32_bf16 v[82:85], v[194:197], v[174:177], v[82:85]
	v_mfma_f32_16x16x32_bf16 v[74:77], v[224:227], v[174:177], v[74:77]
	v_mfma_f32_16x16x32_bf16 v[70:73], v[194:197], v[186:189], v[70:73]
	v_mfma_f32_16x16x32_bf16 v[66:69], v[224:227], v[186:189], v[66:69]
	v_mfma_f32_16x16x32_bf16 v[114:117], v[220:223], v[162:165], v[114:117]
	v_mfma_f32_16x16x32_bf16 v[106:109], v[228:231], v[162:165], v[106:109]
	v_mfma_f32_16x16x32_bf16 v[98:101], v[220:223], v[170:173], v[98:101]
	v_mfma_f32_16x16x32_bf16 v[90:93], v[228:231], v[170:173], v[90:93]
	v_mfma_f32_16x16x32_bf16 v[82:85], v[220:223], v[182:185], v[82:85]
	s_barrier
	v_mfma_f32_16x16x32_bf16 v[74:77], v[228:231], v[182:185], v[74:77]
	v_mfma_f32_16x16x32_bf16 v[70:73], v[220:223], v[190:193], v[70:73]
	v_mfma_f32_16x16x32_bf16 v[66:69], v[228:231], v[190:193], v[66:69]
	s_mov_b32 m0, s22
	v_lshl_add_u64 v[232:233], s[34:35], 0, v[0:1]
	ds_read_b128 v[158:161], v141 offset:16384
	ds_read_b128 v[162:165], v141 offset:17408
	ds_read_b128 v[166:169], v141 offset:18432
	ds_read_b128 v[170:173], v141 offset:19456
	ds_read_b128 v[174:177], v141 offset:20480
	ds_read_b128 v[182:185], v141 offset:21504
	ds_read_b128 v[186:189], v141 offset:22528
	ds_read_b128 v[190:193], v141 offset:23552
	global_load_lds_dwordx4 v[232:233], off
	v_lshl_add_u64 v[234:235], s[34:35], 0, v[130:131]
	s_mov_b32 m0, s23
	s_nop 0
	global_load_lds_dwordx4 v[234:235], off
	s_barrier
	s_waitcnt lgkmcnt(0)
	v_mfma_f32_16x16x32_bf16 v[62:65], v[142:145], v[158:161], v[62:65]
	v_mfma_f32_16x16x32_bf16 v[58:61], v[150:153], v[158:161], v[58:61]
	v_mfma_f32_16x16x32_bf16 v[54:57], v[142:145], v[166:169], v[54:57]
	v_mfma_f32_16x16x32_bf16 v[46:49], v[150:153], v[166:169], v[46:49]
	v_mfma_f32_16x16x32_bf16 v[38:41], v[142:145], v[174:177], v[38:41]
	v_mfma_f32_16x16x32_bf16 v[30:33], v[150:153], v[174:177], v[30:33]
	v_mfma_f32_16x16x32_bf16 v[22:25], v[142:145], v[186:189], v[22:25]
	v_mfma_f32_16x16x32_bf16 v[14:17], v[150:153], v[186:189], v[14:17]
	v_mfma_f32_16x16x32_bf16 v[62:65], v[146:149], v[162:165], v[62:65]
	v_mfma_f32_16x16x32_bf16 v[58:61], v[154:157], v[162:165], v[58:61]
	v_mfma_f32_16x16x32_bf16 v[54:57], v[146:149], v[170:173], v[54:57]
	v_mfma_f32_16x16x32_bf16 v[46:49], v[154:157], v[170:173], v[46:49]
	v_mfma_f32_16x16x32_bf16 v[38:41], v[146:149], v[182:185], v[38:41]
	s_barrier
; #define PG8_STAGE(bufoff, gbase, voff) do { _Pragma("unroll") for (int _i = 0; _i < 2; ++_i) \
;         __builtin_amdgcn_global_load_lds((const unsigned*)((const char*)(gbase) + (voff)[_i]), (LAS unsigned*)(lds + (bufoff) + ldsw + _i * 8192), 16, 0, 0); } while (0)
; #define PG8_LDA(dst, b, h) do { _Pragma("unroll") for (int m = 0; m < 4; ++m) _Pragma("unroll") for (int k = 0; k < 2; ++k) dst[m][k] = *(const LAS bf16x8*)(lds + PG8_SA(b, h) + aoff + m * 2048 + k * 1024); } while (0)
; #define PG8_LDB(dst, b, h) do { _Pragma("unroll") for (int n = 0; n < 2; ++n) _Pragma("unroll") for (int k = 0; k < 2; ++k) dst[n][k] = *(const LAS bf16x8*)(lds + PG8_SB(b, h) + boff + n * 2048 + k * 1024); } while (0)
; #define PG8_MMA(ai, bj, At, Bt) do { __builtin_amdgcn_s_setprio(1); _Pragma("unroll") for (int m = 0; m < 4; ++m) _Pragma("unroll") for (int n = 0; n < 2; ++n) _Pragma("unroll") for (int k = 0; k < 2; ++k) \
;         acc[ai][bj][m][n] = __builtin_amdgcn_mfma_f32_16x16x32_bf16(Bt[n][k], At[m][k], acc[ai][bj][m][n], 0, 0, 0); __builtin_amdgcn_s_setprio(0); } while (0)
; #define PG8_WAIT_V(n) asm volatile("s_waitcnt vmcnt(" #n ")" ::: "memory")
; #define PG8_WAIT_L(n) asm volatile("s_waitcnt lgkmcnt(" #n ")" ::: "memory")
; #define PG8_BAR __builtin_amdgcn_s_barrier()
; #define PG8_SCHED __builtin_amdgcn_sched_barrier(0)
; template <int MODE, class EpiT, class Sched>
; __device__ __forceinline__ void gemm_phase(LAS unsigned char* lds, const Gemm g, const Sched& S, const EpiT& E) {
;     ...
;             PG8_BAR; PG8_WAIT_L(0); PG8_MMA(1, 0, At, B0); PG8_BAR; PG8_SCHED;
;             PG8_STAGE(PG8_SB(0, 1), b2 + hstep, voffB);
;             PG8_WAIT_V(6); PG8_BAR; PG8_MMA(1, 1, At, B1); PG8_BAR;
;             PG8_LDB(B0, 1, 0); PG8_SCHED; PG8_LDA(At, 1, 0); PG8_STAGE(PG8_SA(0, 1), a2 + hstep, voffA);
;             PG8_WAIT_L(8); PG8_BAR; PG8_WAIT_L(0); PG8_MMA(0, 0, At, B0); PG8_BAR; PG8_SCHED;
;             PG8_LDB(B1, 1, 1); PG8_STAGE(PG8_SB(1, 0), b3, voffB);
;             PG8_BAR; PG8_WAIT_L(0); PG8_MMA(0, 1, At, B1); PG8_BAR;
;             PG8_LDA(At, 1, 1); PG8_STAGE(PG8_SA(1, 0), a3, voffA);
	v_mfma_f32_16x16x32_bf16 v[30:33], v[154:157], v[182:185], v[30:33]
	v_mfma_f32_16x16x32_bf16 v[22:25], v[146:149], v[190:193], v[22:25]
	v_mfma_f32_16x16x32_bf16 v[14:17], v[154:157], v[190:193], v[14:17]
	s_add_u32 s38, s38, s24
	s_addc_u32 s39, s39, 0
	s_add_i32 s45, s58, s9
	v_lshl_add_u64 v[236:237], s[38:39], 0, v[0:1]
	s_mov_b32 m0, s45
	v_lshl_add_u64 v[238:239], s[38:39], 0, v[130:131]
	global_load_lds_dwordx4 v[236:237], off
	s_add_i32 m0, s45, 0x2000
	s_nop 0
	global_load_lds_dwordx4 v[238:239], off
	s_waitcnt vmcnt(6)
	s_barrier
	v_mfma_f32_16x16x32_bf16 v[50:53], v[194:197], v[158:161], v[50:53]
	v_mfma_f32_16x16x32_bf16 v[42:45], v[224:227], v[158:161], v[42:45]
	v_mfma_f32_16x16x32_bf16 v[34:37], v[194:197], v[166:169], v[34:37]
	v_mfma_f32_16x16x32_bf16 v[26:29], v[224:227], v[166:169], v[26:29]
	v_mfma_f32_16x16x32_bf16 v[18:21], v[194:197], v[174:177], v[18:21]
	v_mfma_f32_16x16x32_bf16 v[10:13], v[224:227], v[174:177], v[10:13]
	v_mfma_f32_16x16x32_bf16 v[6:9], v[194:197], v[186:189], v[6:9]
	v_mfma_f32_16x16x32_bf16 v[2:5], v[224:227], v[186:189], v[2:5]
	v_mfma_f32_16x16x32_bf16 v[50:53], v[220:223], v[162:165], v[50:53]
	v_mfma_f32_16x16x32_bf16 v[42:45], v[228:231], v[162:165], v[42:45]
	v_mfma_f32_16x16x32_bf16 v[34:37], v[220:223], v[170:173], v[34:37]
	v_mfma_f32_16x16x32_bf16 v[26:29], v[228:231], v[170:173], v[26:29]
	v_mfma_f32_16x16x32_bf16 v[18:21], v[220:223], v[182:185], v[18:21]
	s_barrier
	v_mfma_f32_16x16x32_bf16 v[10:13], v[228:231], v[182:185], v[10:13]
	v_mfma_f32_16x16x32_bf16 v[6:9], v[220:223], v[190:193], v[6:9]
	v_mfma_f32_16x16x32_bf16 v[2:5], v[228:231], v[190:193], v[2:5]
	s_add_i32 s38, 0, 0x18000
	v_add_u32_e32 v154, s38, v139
	ds_read_b128 v[142:145], v154
	ds_read_b128 v[146:149], v154 offset:1024
	ds_read_b128 v[150:153], v154 offset:2048
	ds_read_b128 v[154:157], v154 offset:3072
	s_add_u32 s34, s34, s24
	s_addc_u32 s35, s35, 0
	s_mov_b32 m0, s30
	v_lshl_add_u64 v[194:195], s[34:35], 0, v[0:1]
	ds_read_b128 v[158:161], v141 offset:32768
	ds_read_b128 v[162:165], v141 offset:33792
	ds_read_b128 v[166:169], v141 offset:34816
	ds_read_b128 v[170:173], v141 offset:35840
	ds_read_b128 v[174:177], v141 offset:36864
	ds_read_b128 v[182:185], v141 offset:37888
	ds_read_b128 v[186:189], v141 offset:38912
	ds_read_b128 v[190:193], v141 offset:39936
	global_load_lds_dwordx4 v[194:195], off
	v_lshl_add_u64 v[194:195], s[34:35], 0, v[130:131]
	s_mov_b32 m0, s46
	s_nop 0
	global_load_lds_dwordx4 v[194:195], off
	s_waitcnt lgkmcnt(8)
	s_barrier
	s_waitcnt lgkmcnt(0)
	v_mfma_f32_16x16x32_bf16 v[126:129], v[142:145], v[158:161], v[126:129]
	v_mfma_f32_16x16x32_bf16 v[122:125], v[150:153], v[158:161], v[122:125]
	v_mfma_f32_16x16x32_bf16 v[118:121], v[142:145], v[166:169], v[118:121]
	v_mfma_f32_16x16x32_bf16 v[110:113], v[150:153], v[166:169], v[110:113]
	v_mfma_f32_16x16x32_bf16 v[102:105], v[142:145], v[174:177], v[102:105]
	v_mfma_f32_16x16x32_bf16 v[94:97], v[150:153], v[174:177], v[94:97]
	v_mfma_f32_16x16x32_bf16 v[86:89], v[142:145], v[186:189], v[86:89]
	v_mfma_f32_16x16x32_bf16 v[78:81], v[150:153], v[186:189], v[78:81]
	v_mfma_f32_16x16x32_bf16 v[126:129], v[146:149], v[162:165], v[126:129]
	v_mfma_f32_16x16x32_bf16 v[122:125], v[154:157], v[162:165], v[122:125]
	v_mfma_f32_16x16x32_bf16 v[118:121], v[146:149], v[170:173], v[118:121]
	v_mfma_f32_16x16x32_bf16 v[110:113], v[154:157], v[170:173], v[110:113]
	v_mfma_f32_16x16x32_bf16 v[102:105], v[146:149], v[182:185], v[102:105]
	s_barrier
	v_mfma_f32_16x16x32_bf16 v[94:97], v[154:157], v[182:185], v[94:97]
	v_mfma_f32_16x16x32_bf16 v[86:89], v[146:149], v[190:193], v[86:89]
	v_mfma_f32_16x16x32_bf16 v[78:81], v[154:157], v[190:193], v[78:81]
	s_add_i32 s34, 0, 0x1c000
	s_add_i32 s35, s38, s9
	v_add_u32_e32 v181, s34, v139
	v_lshl_add_u64 v[136:137], v[136:137], 0, s[76:77]
	s_mov_b32 m0, s35
	ds_read_b128 v[194:197], v181
	ds_read_b128 v[220:223], v181 offset:1024
	ds_read_b128 v[224:227], v181 offset:2048
	ds_read_b128 v[228:231], v181 offset:3072
	global_load_lds_dwordx4 v[136:137], off
	v_lshl_add_u64 v[136:137], v[198:199], 0, s[76:77]
	s_add_i32 m0, s35, 0x2000
	s_nop 0
	global_load_lds_dwordx4 v[136:137], off
	s_barrier
	s_waitcnt lgkmcnt(0)
	v_mfma_f32_16x16x32_bf16 v[114:117], v[194:197], v[158:161], v[114:117]
	v_mfma_f32_16x16x32_bf16 v[106:109], v[224:227], v[158:161], v[106:109]
	v_mfma_f32_16x16x32_bf16 v[98:101], v[194:197], v[166:169], v[98:101]
	v_mfma_f32_16x16x32_bf16 v[90:93], v[224:227], v[166:169], v[90:93]
	v_mfma_f32_16x16x32_bf16 v[82:85], v[194:197], v[174:177], v[82:85]
	v_mfma_f32_16x16x32_bf16 v[74:77], v[224:227], v[174:177], v[74:77]
	v_mfma_f32_16x16x32_bf16 v[70:73], v[194:197], v[186:189], v[70:73]
	v_mfma_f32_16x16x32_bf16 v[66:69], v[224:227], v[186:189], v[66:69]
	v_mfma_f32_16x16x32_bf16 v[114:117], v[220:223], v[162:165], v[114:117]
	v_mfma_f32_16x16x32_bf16 v[106:109], v[228:231], v[162:165], v[106:109]
	v_mfma_f32_16x16x32_bf16 v[98:101], v[220:223], v[170:173], v[98:101]
	v_mfma_f32_16x16x32_bf16 v[90:93], v[228:231], v[170:173], v[90:93]
	v_mfma_f32_16x16x32_bf16 v[82:85], v[220:223], v[182:185], v[82:85]
	s_barrier
	v_mfma_f32_16x16x32_bf16 v[74:77], v[228:231], v[182:185], v[74:77]
	v_mfma_f32_16x16x32_bf16 v[70:73], v[220:223], v[190:193], v[70:73]
	v_mfma_f32_16x16x32_bf16 v[66:69], v[228:231], v[190:193], v[66:69]
	s_mov_b32 m0, s50
	v_lshl_add_u64 v[136:137], v[232:233], 0, s[76:77]
	ds_read_b128 v[158:161], v141 offset:49152
	ds_read_b128 v[162:165], v141 offset:50176
	ds_read_b128 v[166:169], v141 offset:51200
	ds_read_b128 v[170:173], v141 offset:52224
	ds_read_b128 v[174:177], v141 offset:53248
	ds_read_b128 v[182:185], v141 offset:54272
	ds_read_b128 v[186:189], v141 offset:55296
	ds_read_b128 v[190:193], v141 offset:56320
	global_load_lds_dwordx4 v[136:137], off
	v_lshl_add_u64 v[136:137], v[234:235], 0, s[76:77]
	s_mov_b32 m0, s51
	s_nop 0
	global_load_lds_dwordx4 v[136:137], off
	s_barrier
; #define PG8_STAGE(bufoff, gbase, voff) do { _Pragma("unroll") for (int _i = 0; _i < 2; ++_i) \
;         __builtin_amdgcn_global_load_lds((const unsigned*)((const char*)(gbase) + (voff)[_i]), (LAS unsigned*)(lds + (bufoff) + ldsw + _i * 8192), 16, 0, 0); } while (0)
; #define PG8_MMA(ai, bj, At, Bt) do { __builtin_amdgcn_s_setprio(1); _Pragma("unroll") for (int m = 0; m < 4; ++m) _Pragma("unroll") for (int n = 0; n < 2; ++n) _Pragma("unroll") for (int k = 0; k < 2; ++k) \
;         acc[ai][bj][m][n] = __builtin_amdgcn_mfma_f32_16x16x32_bf16(Bt[n][k], At[m][k], acc[ai][bj][m][n], 0, 0, 0); __builtin_amdgcn_s_setprio(0); } while (0)
; #define PG8_WAIT_V(n) asm volatile("s_waitcnt vmcnt(" #n ")" ::: "memory")
; #define PG8_WAIT_L(n) asm volatile("s_waitcnt lgkmcnt(" #n ")" ::: "memory")
; #define PG8_BAR __builtin_amdgcn_s_barrier()
; #define PG8_SCHED __builtin_amdgcn_sched_barrier(0)
; template <int MODE, class EpiT, class Sched>
; __device__ __forceinline__ void gemm_phase(LAS unsigned char* lds, const Gemm g, const Sched& S, const EpiT& E) {
;     ...
;             PG8_BAR; PG8_WAIT_L(0); PG8_MMA(1, 0, At, B0); PG8_BAR; PG8_SCHED;
;             PG8_STAGE(PG8_SB(1, 1), b3 + hstep, voffB);
;             PG8_WAIT_V(6); PG8_BAR; PG8_MMA(1, 1, At, B1); PG8_BAR;
	s_waitcnt lgkmcnt(0)
	v_mfma_f32_16x16x32_bf16 v[62:65], v[142:145], v[158:161], v[62:65]
	v_mfma_f32_16x16x32_bf16 v[58:61], v[150:153], v[158:161], v[58:61]
	v_mfma_f32_16x16x32_bf16 v[54:57], v[142:145], v[166:169], v[54:57]
	v_mfma_f32_16x16x32_bf16 v[46:49], v[150:153], v[166:169], v[46:49]
	v_mfma_f32_16x16x32_bf16 v[38:41], v[142:145], v[174:177], v[38:41]
	v_mfma_f32_16x16x32_bf16 v[30:33], v[150:153], v[174:177], v[30:33]
	v_mfma_f32_16x16x32_bf16 v[22:25], v[142:145], v[186:189], v[22:25]
	v_mfma_f32_16x16x32_bf16 v[14:17], v[150:153], v[186:189], v[14:17]
	v_mfma_f32_16x16x32_bf16 v[62:65], v[146:149], v[162:165], v[62:65]
	v_mfma_f32_16x16x32_bf16 v[58:61], v[154:157], v[162:165], v[58:61]
	v_mfma_f32_16x16x32_bf16 v[54:57], v[146:149], v[170:173], v[54:57]
	v_mfma_f32_16x16x32_bf16 v[46:49], v[154:157], v[170:173], v[46:49]
	v_mfma_f32_16x16x32_bf16 v[38:41], v[146:149], v[182:185], v[38:41]
	s_barrier
	v_mfma_f32_16x16x32_bf16 v[30:33], v[154:157], v[182:185], v[30:33]
	v_mfma_f32_16x16x32_bf16 v[22:25], v[146:149], v[190:193], v[22:25]
	v_mfma_f32_16x16x32_bf16 v[14:17], v[154:157], v[190:193], v[14:17]
	s_add_i32 s34, s34, s9
	v_lshl_add_u64 v[136:137], v[236:237], 0, s[76:77]
	s_mov_b32 m0, s34
	s_nop 0
	global_load_lds_dwordx4 v[136:137], off
	v_lshl_add_u64 v[136:137], v[238:239], 0, s[76:77]
	s_add_i32 m0, s34, 0x2000
	s_nop 0
	global_load_lds_dwordx4 v[136:137], off
	s_waitcnt vmcnt(6)
	s_barrier
	v_mfma_f32_16x16x32_bf16 v[50:53], v[194:197], v[158:161], v[50:53]
	v_mfma_f32_16x16x32_bf16 v[42:45], v[224:227], v[158:161], v[42:45]
	v_mfma_f32_16x16x32_bf16 v[34:37], v[194:197], v[166:169], v[34:37]
	v_mfma_f32_16x16x32_bf16 v[26:29], v[224:227], v[166:169], v[26:29]
	v_mfma_f32_16x16x32_bf16 v[18:21], v[194:197], v[174:177], v[18:21]
	v_mfma_f32_16x16x32_bf16 v[10:13], v[224:227], v[174:177], v[10:13]
	v_mfma_f32_16x16x32_bf16 v[6:9], v[194:197], v[186:189], v[6:9]
	v_mfma_f32_16x16x32_bf16 v[2:5], v[224:227], v[186:189], v[2:5]
	v_mfma_f32_16x16x32_bf16 v[50:53], v[220:223], v[162:165], v[50:53]
	v_mfma_f32_16x16x32_bf16 v[42:45], v[228:231], v[162:165], v[42:45]
	v_mfma_f32_16x16x32_bf16 v[34:37], v[220:223], v[170:173], v[34:37]
	v_mfma_f32_16x16x32_bf16 v[26:29], v[228:231], v[170:173], v[26:29]
	v_mfma_f32_16x16x32_bf16 v[18:21], v[220:223], v[182:185], v[18:21]
	s_barrier
	v_mfma_f32_16x16x32_bf16 v[10:13], v[228:231], v[182:185], v[10:13]
	v_mfma_f32_16x16x32_bf16 v[6:9], v[220:223], v[190:193], v[6:9]
	v_mfma_f32_16x16x32_bf16 v[2:5], v[228:231], v[190:193], v[2:5]
	s_add_u32 s28, s28, 0x100
	s_addc_u32 s29, s29, 0
	s_add_u32 s42, s42, 0x100
	s_addc_u32 s43, s43, 0
	s_cmp_ge_u32 s44, s47
	s_mov_b32 s34, s44
	s_cbranch_scc0 .LBB0_236
; __device__ __forceinline__ unsigned pk2(float lo, float hi) { unsigned r; asm volatile("v_cvt_pk_bf16_f32 %0, %1, %2" : "=v"(r) : "v"(lo), "v"(hi)); return r; }
; #define PG8_WAIT_V(n) asm volatile("s_waitcnt vmcnt(" #n ")" ::: "memory")
; #define PG8_BAR __builtin_amdgcn_s_barrier()
;     template <int mode> __device__ __forceinline__ void run(const f32x4 (&acc)[2][2][4][2], const Unit& u, int wr, int wc, int fr, int fq, const LAS float* sc) const {
;     ...
;             for (int ai = 0; ai < 2; ++ai)
; #pragma unroll
;                 for (int m = 0; m < 4; ++m) {
;                     bf16_t* rowp = ob + (size_t)(row0 + ai * HALF + m * 16) * D + col0;
; #pragma unroll
;                     for (int bj = 0; bj < 2; ++bj) {
;                         const f32x4 v0 = acc[ai][bj][m][0], v1 = acc[ai][bj][m][1];
;                         u32x4 w; w.x = pk2(v0[0], v0[1]); w.y = pk2(v0[2], v0[3]); w.z = pk2(v1[0], v1[1]); w.w = pk2(v1[2], v1[3]);
;                         *(u32x4*)(rowp + bj * HALF) = w;
;                     }
; template <int MODE, class EpiT, class Sched>
; __device__ __forceinline__ void gemm_phase(LAS unsigned char* lds, const Gemm g, const Sched& S, const EpiT& E) {
;     ...
;         if (!has_next) break;
; #pragma unroll
;         for (int a = 0; a < 2; ++a)
; #pragma unroll
;             for (int b = 0; b < 2; ++b)
; #pragma unroll
;                 for (int m = 0; m < 4; ++m)
; #pragma unroll
;                     for (int n = 0; n < 2; ++n) acc[a][b][m][n] = (f32x4){0.f, 0.f, 0.f, 0.f};
;         cur = nxt; cA = nA; cB = nB; ++ui;
;     }
;     PG8_WAIT_V(0);
;     if (wr == 0) PG8_BAR;
;     PG8_BAR;
	v_lshl_add_u32 v142, s56, 8, v138
	v_lshl_or_b32 v136, s61, 8, v140
	v_ashrrev_i32_e32 v143, 31, v142
	v_ashrrev_i32_e32 v137, 31, v136
	v_lshlrev_b64 v[144:145], 11, v[142:143]
	v_lshl_add_u64 v[144:145], s[6:7], 0, v[144:145]
	v_lshlrev_b64 v[146:147], 1, v[136:137]
	v_lshl_add_u64 v[136:137], v[144:145], 0, v[146:147]
	v_cvt_pk_bf16_f32 v126, v126, v127
	v_cvt_pk_bf16_f32 v127, v128, v129
	v_cvt_pk_bf16_f32 v128, v122, v123
	v_cvt_pk_bf16_f32 v129, v124, v125
	global_store_dwordx4 v[136:137], v[126:129], off
	v_cvt_pk_bf16_f32 v114, v114, v115
	v_cvt_pk_bf16_f32 v115, v116, v117
	v_cvt_pk_bf16_f32 v116, v106, v107
	v_or_b32_e32 v106, 16, v142
	v_ashrrev_i32_e32 v107, 31, v106
	v_lshlrev_b64 v[106:107], 11, v[106:107]
	v_lshl_add_u64 v[106:107], s[6:7], 0, v[106:107]
	v_cvt_pk_bf16_f32 v117, v108, v109
	global_store_dwordx4 v[136:137], v[114:117], off offset:256
	s_mov_b64 s[28:29], 0x40000
	s_mov_b32 s61, s57
	v_lshl_add_u64 v[114:115], v[106:107], 0, v[146:147]
	v_cvt_pk_bf16_f32 v106, v118, v119
	v_cvt_pk_bf16_f32 v107, v120, v121
	v_cvt_pk_bf16_f32 v108, v110, v111
	v_cvt_pk_bf16_f32 v109, v112, v113
	global_store_dwordx4 v[114:115], v[106:109], off
	v_cvt_pk_bf16_f32 v98, v98, v99
	v_cvt_pk_bf16_f32 v99, v100, v101
	v_cvt_pk_bf16_f32 v100, v90, v91
	v_or_b32_e32 v90, 32, v142
	v_ashrrev_i32_e32 v91, 31, v90
	v_lshlrev_b64 v[90:91], 11, v[90:91]
	v_lshl_add_u64 v[90:91], s[6:7], 0, v[90:91]
	v_cvt_pk_bf16_f32 v101, v92, v93
	global_store_dwordx4 v[114:115], v[98:101], off offset:256
	s_mov_b32 s56, s60
	s_mov_b64 s[34:35], s[10:11]
	v_lshl_add_u64 v[98:99], v[90:91], 0, v[146:147]
	v_cvt_pk_bf16_f32 v90, v102, v103
	v_cvt_pk_bf16_f32 v91, v104, v105
	v_cvt_pk_bf16_f32 v92, v94, v95
	v_cvt_pk_bf16_f32 v93, v96, v97
	global_store_dwordx4 v[98:99], v[90:93], off
	v_cvt_pk_bf16_f32 v82, v82, v83
	v_cvt_pk_bf16_f32 v83, v84, v85
	v_cvt_pk_bf16_f32 v84, v74, v75
	v_or_b32_e32 v74, 48, v142
	v_ashrrev_i32_e32 v75, 31, v74
	v_lshlrev_b64 v[74:75], 11, v[74:75]
	v_lshl_add_u64 v[74:75], s[6:7], 0, v[74:75]
	v_cvt_pk_bf16_f32 v85, v76, v77
	global_store_dwordx4 v[98:99], v[82:85], off offset:256
	s_nop 1
	v_lshl_add_u64 v[82:83], v[74:75], 0, v[146:147]
	v_cvt_pk_bf16_f32 v74, v86, v87
	v_cvt_pk_bf16_f32 v75, v88, v89
	v_cvt_pk_bf16_f32 v76, v78, v79
	v_cvt_pk_bf16_f32 v77, v80, v81
	global_store_dwordx4 v[82:83], v[74:77], off
	v_cvt_pk_bf16_f32 v70, v70, v71
	v_cvt_pk_bf16_f32 v71, v72, v73
	v_cvt_pk_bf16_f32 v72, v66, v67
	v_cvt_pk_bf16_f32 v73, v68, v69
	global_store_dwordx4 v[82:83], v[70:73], off offset:256
	v_cvt_pk_bf16_f32 v62, v62, v63
	v_cvt_pk_bf16_f32 v63, v64, v65
	v_cvt_pk_bf16_f32 v64, v58, v59
	v_add_co_u32_e32 v58, vcc, s91, v136
	v_lshl_add_u64 v[66:67], v[136:137], 0, s[28:29]
	s_nop 0
	v_addc_co_u32_e32 v59, vcc, 0, v137, vcc
	v_cvt_pk_bf16_f32 v65, v60, v61
	global_store_dwordx4 v[58:59], v[62:65], off
	v_cvt_pk_bf16_f32 v50, v50, v51
	v_cvt_pk_bf16_f32 v51, v52, v53
	s_mov_b64 s[28:29], 0x48000
	v_cvt_pk_bf16_f32 v52, v42, v43
	v_cvt_pk_bf16_f32 v53, v44, v45
	global_store_dwordx4 v[66:67], v[50:53], off offset:256
	v_cvt_pk_bf16_f32 v42, v54, v55
	v_cvt_pk_bf16_f32 v43, v56, v57
	v_cvt_pk_bf16_f32 v44, v46, v47
	v_cvt_pk_bf16_f32 v45, v48, v49
	s_nop 1
	v_lshl_add_u64 v[50:51], v[136:137], 0, s[28:29]
	s_mov_b32 s28, 0x48000
	v_add_co_u32_e32 v46, vcc, s28, v136
	s_mov_b64 s[28:29], 0x50000
	s_nop 0
	v_addc_co_u32_e32 v47, vcc, 0, v137, vcc
	global_store_dwordx4 v[46:47], v[42:45], off
	v_cvt_pk_bf16_f32 v34, v34, v35
	v_cvt_pk_bf16_f32 v35, v36, v37
	v_cvt_pk_bf16_f32 v36, v26, v27
	v_cvt_pk_bf16_f32 v37, v28, v29
	global_store_dwordx4 v[50:51], v[34:37], off offset:256
	v_cvt_pk_bf16_f32 v26, v38, v39
	v_cvt_pk_bf16_f32 v27, v40, v41
	v_cvt_pk_bf16_f32 v28, v30, v31
	v_cvt_pk_bf16_f32 v29, v32, v33
	s_nop 1
	v_lshl_add_u64 v[34:35], v[136:137], 0, s[28:29]
	s_mov_b32 s28, 0x50000
	v_add_co_u32_e32 v30, vcc, s28, v136
	s_mov_b64 s[28:29], 0x58000
	s_nop 0
	v_addc_co_u32_e32 v31, vcc, 0, v137, vcc
	global_store_dwordx4 v[30:31], v[26:29], off
	v_cvt_pk_bf16_f32 v18, v18, v19
	v_cvt_pk_bf16_f32 v19, v20, v21
	v_cvt_pk_bf16_f32 v20, v10, v11
	v_cvt_pk_bf16_f32 v21, v12, v13
	global_store_dwordx4 v[34:35], v[18:21], off offset:256
	v_cvt_pk_bf16_f32 v10, v22, v23
	v_cvt_pk_bf16_f32 v11, v24, v25
	v_cvt_pk_bf16_f32 v12, v14, v15
	v_cvt_pk_bf16_f32 v13, v16, v17
	s_nop 1
	v_lshl_add_u64 v[18:19], v[136:137], 0, s[28:29]
	s_mov_b32 s28, 0x58000
	v_add_co_u32_e32 v14, vcc, s28, v136
	s_mov_b64 s[28:29], s[4:5]
	s_nop 0
	v_addc_co_u32_e32 v15, vcc, 0, v137, vcc
	s_and_b64 vcc, exec, s[40:41]
	global_store_dwordx4 v[14:15], v[10:13], off
	v_cvt_pk_bf16_f32 v6, v6, v7
	v_cvt_pk_bf16_f32 v7, v8, v9
	v_cvt_pk_bf16_f32 v8, v2, v3
	v_cvt_pk_bf16_f32 v9, v4, v5
	global_store_dwordx4 v[18:19], v[6:9], off offset:256
	s_cbranch_vccz .LBB0_229
	s_waitcnt vmcnt(0)
	v_readlane_b32 s46, v247, 49
	v_readlane_b32 s50, v246, 29
	v_readlane_b32 s56, v246, 31
	v_readlane_b32 s58, v246, 33
	v_readlane_b32 s60, v246, 35
	s_cmpk_gt_u32 s2, 0xff
	s_mov_b32 s52, 0x800000
	s_movk_i32 s53, 0x1000
	s_movk_i32 s23, 0x2000
	s_movk_i32 s30, 0x2840
	s_movk_i32 s42, 0x3000
	s_mov_b64 s[44:45], 0x1800
	v_readlane_b32 s47, v247, 50
	v_readlane_b32 s43, v247, 51
	v_readlane_b32 s51, v246, 30
	v_readlane_b32 s57, v246, 32
	v_readlane_b32 s59, v246, 34
	v_readlane_b32 s61, v246, 36
	s_cbranch_scc1 .LBB0_240
	s_barrier

; #define PG8_STAGE(bufoff, gbase, voff) do { _Pragma("unroll") for (int _i = 0; _i < 2; ++_i) \
;         __builtin_amdgcn_global_load_lds((const unsigned*)((const char*)(gbase) + (voff)[_i]), (LAS unsigned*)(lds + (bufoff) + ldsw + _i * 8192), 16, 0, 0); } while (0)
; #define PG8_LDA(dst, b, h) do { _Pragma("unroll") for (int m = 0; m < 4; ++m) _Pragma("unroll") for (int k = 0; k < 2; ++k) dst[m][k] = *(const LAS bf16x8*)(lds + PG8_SA(b, h) + aoff + m * 2048 + k * 1024); } while (0)
; #define PG8_LDB(dst, b, h) do { _Pragma("unroll") for (int n = 0; n < 2; ++n) _Pragma("unroll") for (int k = 0; k < 2; ++k) dst[n][k] = *(const LAS bf16x8*)(lds + PG8_SB(b, h) + boff + n * 2048 + k * 1024); } while (0)
; #define PG8_MMA(ai, bj, At, Bt) do { __builtin_amdgcn_s_setprio(1); _Pragma("unroll") for (int m = 0; m < 4; ++m) _Pragma("unroll") for (int n = 0; n < 2; ++n) _Pragma("unroll") for (int k = 0; k < 2; ++k) \
;         acc[ai][bj][m][n] = __builtin_amdgcn_mfma_f32_16x16x32_bf16(Bt[n][k], At[m][k], acc[ai][bj][m][n], 0, 0, 0); __builtin_amdgcn_s_setprio(0); } while (0)
; #define PG8_WAIT_L(n) asm volatile("s_waitcnt lgkmcnt(" #n ")" ::: "memory")
; #define PG8_BAR __builtin_amdgcn_s_barrier()
; #define PG8_SCHED __builtin_amdgcn_sched_barrier(0)
; template <int MODE, class EpiT, class Sched>
; __device__ __forceinline__ void gemm_phase(LAS unsigned char* lds, const Gemm g, const Sched& S, const EpiT& E) {
;     ...
;             const bool last = (t == nt - 2);
;             const char* a1 = cA + (size_t)(t + 1) * kstep;
;             const char* a2 = last ? nA : cA + (size_t)(t + 2) * kstep; const char* b2 = last ? nB : cB + (size_t)(t + 2) * kstep;
;             const char* a3 = a2 + kstep; const char* b3 = b2 + kstep;
;             PG8_LDB(B0, 0, 0); PG8_SCHED; PG8_LDA(At, 0, 0); PG8_STAGE(PG8_SA(1, 1), a1 + hstep, voffA);
;             PG8_WAIT_L(8); PG8_BAR; PG8_WAIT_L(0); PG8_MMA(0, 0, At, B0); PG8_BAR; PG8_SCHED;
;             PG8_LDB(B1, 0, 1); PG8_STAGE(PG8_SB(0, 0), b2, voffB);
;             PG8_BAR; PG8_WAIT_L(0); PG8_MMA(0, 1, At, B1); PG8_BAR;
;             PG8_LDA(At, 0, 1); PG8_STAGE(PG8_SA(0, 0), a2, voffA);
;             PG8_BAR; PG8_WAIT_L(0); PG8_MMA(1, 0, At, B0); PG8_BAR; PG8_SCHED;
.LBB0_280:
	s_add_i32 s68, s46, 2
	s_add_u32 s52, s10, s44
	s_addc_u32 s47, s11, s45
	s_add_u32 s58, s4, s44
	s_addc_u32 s53, s5, s45
	s_add_i32 s59, 0, 0x10000
	v_add_u32_e32 v152, s59, v157
	ds_read_b128 v[134:137], v152
	ds_read_b128 v[138:141], v152 offset:1024
	ds_read_b128 v[142:145], v152 offset:2048
	ds_read_b128 v[152:155], v152 offset:3072
	s_cmp_eq_u32 s60, s46
	s_cselect_b32 s46, s34, s52
	s_cselect_b32 s47, s35, s47
	s_cselect_b32 s53, s39, s53
	s_cselect_b32 s52, s38, s58
	v_lshl_add_u64 v[198:199], s[10:11], 0, v[132:133]
	s_add_i32 m0, s30, 0xc000
	ds_read_b128 v[162:165], v160
	ds_read_b128 v[166:169], v160 offset:1024
	ds_read_b128 v[170:173], v160 offset:2048
	ds_read_b128 v[174:177], v160 offset:3072
	ds_read_b128 v[182:185], v160 offset:4096
	ds_read_b128 v[186:189], v160 offset:5120
	ds_read_b128 v[190:193], v160 offset:6144
	ds_read_b128 v[194:197], v160 offset:7168
	global_load_lds_dwordx4 v[198:199], off
	v_lshl_add_u64 v[198:199], s[10:11], 0, v[130:131]
	s_add_i32 m0, s30, 0xe000
	s_nop 0
	global_load_lds_dwordx4 v[198:199], off
	s_waitcnt lgkmcnt(8)
	s_barrier
	s_waitcnt lgkmcnt(0)
	v_mfma_f32_16x16x32_bf16 v[126:129], v[134:137], v[162:165], v[126:129]
	v_mfma_f32_16x16x32_bf16 v[122:125], v[142:145], v[162:165], v[122:125]
	v_mfma_f32_16x16x32_bf16 v[118:121], v[134:137], v[170:173], v[118:121]
	v_mfma_f32_16x16x32_bf16 v[114:117], v[142:145], v[170:173], v[114:117]
	v_mfma_f32_16x16x32_bf16 v[110:113], v[134:137], v[182:185], v[110:113]
	v_mfma_f32_16x16x32_bf16 v[106:109], v[142:145], v[182:185], v[106:109]
	v_mfma_f32_16x16x32_bf16 v[102:105], v[134:137], v[190:193], v[102:105]
	v_mfma_f32_16x16x32_bf16 v[98:101], v[142:145], v[190:193], v[98:101]
	v_mfma_f32_16x16x32_bf16 v[126:129], v[138:141], v[166:169], v[126:129]
	v_mfma_f32_16x16x32_bf16 v[122:125], v[152:155], v[166:169], v[122:125]
	v_mfma_f32_16x16x32_bf16 v[118:121], v[138:141], v[174:177], v[118:121]
	v_mfma_f32_16x16x32_bf16 v[114:117], v[152:155], v[174:177], v[114:117]
	v_mfma_f32_16x16x32_bf16 v[110:113], v[138:141], v[186:189], v[110:113]
	s_barrier
	v_mfma_f32_16x16x32_bf16 v[106:109], v[152:155], v[186:189], v[106:109]
	v_mfma_f32_16x16x32_bf16 v[102:105], v[138:141], v[194:197], v[102:105]
	v_mfma_f32_16x16x32_bf16 v[98:101], v[152:155], v[194:197], v[98:101]
	s_add_i32 s58, 0, 0x14000
	s_add_i32 s59, s59, s24
	v_add_u32_e32 v161, s58, v157
	v_lshl_add_u64 v[198:199], s[52:53], 0, v[0:1]
	s_mov_b32 m0, s59
	ds_read_b128 v[220:223], v161
	ds_read_b128 v[224:227], v161 offset:1024
	ds_read_b128 v[228:231], v161 offset:2048
	ds_read_b128 v[232:235], v161 offset:3072
	global_load_lds_dwordx4 v[198:199], off
	v_lshl_add_u64 v[236:237], s[52:53], 0, v[146:147]
	s_add_i32 m0, s59, 0x2000
	s_nop 0
	global_load_lds_dwordx4 v[236:237], off
	s_barrier
	s_waitcnt lgkmcnt(0)
	v_mfma_f32_16x16x32_bf16 v[94:97], v[220:223], v[162:165], v[94:97]
	v_mfma_f32_16x16x32_bf16 v[90:93], v[228:231], v[162:165], v[90:93]
	v_mfma_f32_16x16x32_bf16 v[86:89], v[220:223], v[170:173], v[86:89]
	v_mfma_f32_16x16x32_bf16 v[82:85], v[228:231], v[170:173], v[82:85]
	v_mfma_f32_16x16x32_bf16 v[78:81], v[220:223], v[182:185], v[78:81]
	v_mfma_f32_16x16x32_bf16 v[74:77], v[228:231], v[182:185], v[74:77]
	v_mfma_f32_16x16x32_bf16 v[70:73], v[220:223], v[190:193], v[70:73]
	v_mfma_f32_16x16x32_bf16 v[66:69], v[228:231], v[190:193], v[66:69]
	v_mfma_f32_16x16x32_bf16 v[94:97], v[224:227], v[166:169], v[94:97]
	v_mfma_f32_16x16x32_bf16 v[90:93], v[232:235], v[166:169], v[90:93]
	v_mfma_f32_16x16x32_bf16 v[86:89], v[224:227], v[174:177], v[86:89]
	v_mfma_f32_16x16x32_bf16 v[82:85], v[232:235], v[174:177], v[82:85]
	v_mfma_f32_16x16x32_bf16 v[78:81], v[224:227], v[186:189], v[78:81]
	s_barrier
	v_mfma_f32_16x16x32_bf16 v[74:77], v[232:235], v[186:189], v[74:77]
	v_mfma_f32_16x16x32_bf16 v[70:73], v[224:227], v[194:197], v[70:73]
	v_mfma_f32_16x16x32_bf16 v[66:69], v[232:235], v[194:197], v[66:69]
	s_mov_b32 m0, s30
	v_lshl_add_u64 v[238:239], s[46:47], 0, v[0:1]
	ds_read_b128 v[162:165], v160 offset:16384
	ds_read_b128 v[166:169], v160 offset:17408
	ds_read_b128 v[170:173], v160 offset:18432
	ds_read_b128 v[174:177], v160 offset:19456
	ds_read_b128 v[182:185], v160 offset:20480
	ds_read_b128 v[186:189], v160 offset:21504
	ds_read_b128 v[190:193], v160 offset:22528
	ds_read_b128 v[194:197], v160 offset:23552
	global_load_lds_dwordx4 v[238:239], off
	v_lshl_add_u64 v[240:241], s[46:47], 0, v[146:147]
	s_mov_b32 m0, s50
	s_nop 0
	global_load_lds_dwordx4 v[240:241], off
	s_barrier
	s_waitcnt lgkmcnt(0)
	v_mfma_f32_16x16x32_bf16 v[62:65], v[134:137], v[162:165], v[62:65]
	v_mfma_f32_16x16x32_bf16 v[58:61], v[142:145], v[162:165], v[58:61]
	v_mfma_f32_16x16x32_bf16 v[54:57], v[134:137], v[170:173], v[54:57]
	v_mfma_f32_16x16x32_bf16 v[50:53], v[142:145], v[170:173], v[50:53]
	v_mfma_f32_16x16x32_bf16 v[46:49], v[134:137], v[182:185], v[46:49]
	v_mfma_f32_16x16x32_bf16 v[42:45], v[142:145], v[182:185], v[42:45]
	v_mfma_f32_16x16x32_bf16 v[38:41], v[134:137], v[190:193], v[38:41]
	v_mfma_f32_16x16x32_bf16 v[34:37], v[142:145], v[190:193], v[34:37]
	v_mfma_f32_16x16x32_bf16 v[62:65], v[138:141], v[166:169], v[62:65]
	v_mfma_f32_16x16x32_bf16 v[58:61], v[152:155], v[166:169], v[58:61]
	v_mfma_f32_16x16x32_bf16 v[54:57], v[138:141], v[174:177], v[54:57]
	v_mfma_f32_16x16x32_bf16 v[50:53], v[152:155], v[174:177], v[50:53]
	v_mfma_f32_16x16x32_bf16 v[46:49], v[138:141], v[186:189], v[46:49]
	s_barrier
; #define PG8_STAGE(bufoff, gbase, voff) do { _Pragma("unroll") for (int _i = 0; _i < 2; ++_i) \
;         __builtin_amdgcn_global_load_lds((const unsigned*)((const char*)(gbase) + (voff)[_i]), (LAS unsigned*)(lds + (bufoff) + ldsw + _i * 8192), 16, 0, 0); } while (0)
; #define PG8_LDA(dst, b, h) do { _Pragma("unroll") for (int m = 0; m < 4; ++m) _Pragma("unroll") for (int k = 0; k < 2; ++k) dst[m][k] = *(const LAS bf16x8*)(lds + PG8_SA(b, h) + aoff + m * 2048 + k * 1024); } while (0)
; #define PG8_LDB(dst, b, h) do { _Pragma("unroll") for (int n = 0; n < 2; ++n) _Pragma("unroll") for (int k = 0; k < 2; ++k) dst[n][k] = *(const LAS bf16x8*)(lds + PG8_SB(b, h) + boff + n * 2048 + k * 1024); } while (0)
; #define PG8_MMA(ai, bj, At, Bt) do { __builtin_amdgcn_s_setprio(1); _Pragma("unroll") for (int m = 0; m < 4; ++m) _Pragma("unroll") for (int n = 0; n < 2; ++n) _Pragma("unroll") for (int k = 0; k < 2; ++k) \
;         acc[ai][bj][m][n] = __builtin_amdgcn_mfma_f32_16x16x32_bf16(Bt[n][k], At[m][k], acc[ai][bj][m][n], 0, 0, 0); __builtin_amdgcn_s_setprio(0); } while (0)
; #define PG8_WAIT_V(n) asm volatile("s_waitcnt vmcnt(" #n ")" ::: "memory")
; #define PG8_WAIT_L(n) asm volatile("s_waitcnt lgkmcnt(" #n ")" ::: "memory")
; #define PG8_BAR __builtin_amdgcn_s_barrier()
; #define PG8_SCHED __builtin_amdgcn_sched_barrier(0)
; template <int MODE, class EpiT, class Sched>
; __device__ __forceinline__ void gemm_phase(LAS unsigned char* lds, const Gemm g, const Sched& S, const EpiT& E) {
;     ...
;             PG8_BAR; PG8_WAIT_L(0); PG8_MMA(1, 0, At, B0); PG8_BAR; PG8_SCHED;
;             PG8_STAGE(PG8_SB(0, 1), b2 + hstep, voffB);
;             PG8_WAIT_V(6); PG8_BAR; PG8_MMA(1, 1, At, B1); PG8_BAR;
;             PG8_LDB(B0, 1, 0); PG8_SCHED; PG8_LDA(At, 1, 0); PG8_STAGE(PG8_SA(0, 1), a2 + hstep, voffA);
;             PG8_WAIT_L(8); PG8_BAR; PG8_WAIT_L(0); PG8_MMA(0, 0, At, B0); PG8_BAR; PG8_SCHED;
;             PG8_LDB(B1, 1, 1); PG8_STAGE(PG8_SB(1, 0), b3, voffB);
;             PG8_BAR; PG8_WAIT_L(0); PG8_MMA(0, 1, At, B1); PG8_BAR;
	v_mfma_f32_16x16x32_bf16 v[42:45], v[152:155], v[186:189], v[42:45]
	v_mfma_f32_16x16x32_bf16 v[38:41], v[138:141], v[194:197], v[38:41]
	v_mfma_f32_16x16x32_bf16 v[34:37], v[152:155], v[194:197], v[34:37]
	s_add_u32 s52, s52, s22
	s_addc_u32 s53, s53, 0
	s_add_i32 s58, s58, s24
	v_lshl_add_u64 v[242:243], s[52:53], 0, v[0:1]
	s_mov_b32 m0, s58
	v_lshl_add_u64 v[244:245], s[52:53], 0, v[146:147]
	global_load_lds_dwordx4 v[242:243], off
	s_add_i32 m0, s58, 0x2000
	s_nop 0
	global_load_lds_dwordx4 v[244:245], off
	s_waitcnt vmcnt(6)
	s_barrier
	v_mfma_f32_16x16x32_bf16 v[30:33], v[220:223], v[162:165], v[30:33]
	v_mfma_f32_16x16x32_bf16 v[26:29], v[228:231], v[162:165], v[26:29]
	v_mfma_f32_16x16x32_bf16 v[22:25], v[220:223], v[170:173], v[22:25]
	v_mfma_f32_16x16x32_bf16 v[18:21], v[228:231], v[170:173], v[18:21]
	v_mfma_f32_16x16x32_bf16 v[14:17], v[220:223], v[182:185], v[14:17]
	v_mfma_f32_16x16x32_bf16 v[10:13], v[228:231], v[182:185], v[10:13]
	v_mfma_f32_16x16x32_bf16 v[6:9], v[220:223], v[190:193], v[6:9]
	v_mfma_f32_16x16x32_bf16 v[2:5], v[228:231], v[190:193], v[2:5]
	v_mfma_f32_16x16x32_bf16 v[30:33], v[224:227], v[166:169], v[30:33]
	v_mfma_f32_16x16x32_bf16 v[26:29], v[232:235], v[166:169], v[26:29]
	v_mfma_f32_16x16x32_bf16 v[22:25], v[224:227], v[174:177], v[22:25]
	v_mfma_f32_16x16x32_bf16 v[18:21], v[232:235], v[174:177], v[18:21]
	v_mfma_f32_16x16x32_bf16 v[14:17], v[224:227], v[186:189], v[14:17]
	s_barrier
	v_mfma_f32_16x16x32_bf16 v[10:13], v[232:235], v[186:189], v[10:13]
	v_mfma_f32_16x16x32_bf16 v[6:9], v[224:227], v[194:197], v[6:9]
	v_mfma_f32_16x16x32_bf16 v[2:5], v[232:235], v[194:197], v[2:5]
	s_add_i32 s52, 0, 0x18000
	v_add_u32_e32 v152, s52, v157
	ds_read_b128 v[134:137], v152
	ds_read_b128 v[138:141], v152 offset:1024
	ds_read_b128 v[142:145], v152 offset:2048
	ds_read_b128 v[152:155], v152 offset:3072
	s_add_u32 s46, s46, s22
	s_addc_u32 s47, s47, 0
	s_mov_b32 m0, s51
	v_lshl_add_u64 v[220:221], s[46:47], 0, v[0:1]
	ds_read_b128 v[162:165], v160 offset:32768
	ds_read_b128 v[166:169], v160 offset:33792
	ds_read_b128 v[170:173], v160 offset:34816
	ds_read_b128 v[174:177], v160 offset:35840
	ds_read_b128 v[182:185], v160 offset:36864
	ds_read_b128 v[186:189], v160 offset:37888
	ds_read_b128 v[190:193], v160 offset:38912
	ds_read_b128 v[194:197], v160 offset:39936
	global_load_lds_dwordx4 v[220:221], off
	v_lshl_add_u64 v[220:221], s[46:47], 0, v[146:147]
	s_mov_b32 m0, s54
	s_nop 0
	global_load_lds_dwordx4 v[220:221], off
	s_waitcnt lgkmcnt(8)
	s_barrier
	s_waitcnt lgkmcnt(0)
	v_mfma_f32_16x16x32_bf16 v[126:129], v[134:137], v[162:165], v[126:129]
	v_mfma_f32_16x16x32_bf16 v[122:125], v[142:145], v[162:165], v[122:125]
	v_mfma_f32_16x16x32_bf16 v[118:121], v[134:137], v[170:173], v[118:121]
	v_mfma_f32_16x16x32_bf16 v[114:117], v[142:145], v[170:173], v[114:117]
	v_mfma_f32_16x16x32_bf16 v[110:113], v[134:137], v[182:185], v[110:113]
	v_mfma_f32_16x16x32_bf16 v[106:109], v[142:145], v[182:185], v[106:109]
	v_mfma_f32_16x16x32_bf16 v[102:105], v[134:137], v[190:193], v[102:105]
	v_mfma_f32_16x16x32_bf16 v[98:101], v[142:145], v[190:193], v[98:101]
	v_mfma_f32_16x16x32_bf16 v[126:129], v[138:141], v[166:169], v[126:129]
	v_mfma_f32_16x16x32_bf16 v[122:125], v[152:155], v[166:169], v[122:125]
	v_mfma_f32_16x16x32_bf16 v[118:121], v[138:141], v[174:177], v[118:121]
	v_mfma_f32_16x16x32_bf16 v[114:117], v[152:155], v[174:177], v[114:117]
	v_mfma_f32_16x16x32_bf16 v[110:113], v[138:141], v[186:189], v[110:113]
	s_barrier
	v_mfma_f32_16x16x32_bf16 v[106:109], v[152:155], v[186:189], v[106:109]
	v_mfma_f32_16x16x32_bf16 v[102:105], v[138:141], v[194:197], v[102:105]
	v_mfma_f32_16x16x32_bf16 v[98:101], v[152:155], v[194:197], v[98:101]
	s_add_i32 s46, 0, 0x1c000
	s_add_i32 s47, s52, s24
	v_add_u32_e32 v161, s46, v157
	v_lshl_add_u64 v[198:199], v[198:199], 0, s[76:77]
	s_mov_b32 m0, s47
	ds_read_b128 v[220:223], v161
	ds_read_b128 v[224:227], v161 offset:1024
	ds_read_b128 v[228:231], v161 offset:2048
	ds_read_b128 v[232:235], v161 offset:3072
	global_load_lds_dwordx4 v[198:199], off
	v_lshl_add_u64 v[198:199], v[236:237], 0, s[76:77]
	s_add_i32 m0, s47, 0x2000
	s_nop 0
	global_load_lds_dwordx4 v[198:199], off
	s_barrier
; #define PG8_STAGE(bufoff, gbase, voff) do { _Pragma("unroll") for (int _i = 0; _i < 2; ++_i) \
;         __builtin_amdgcn_global_load_lds((const unsigned*)((const char*)(gbase) + (voff)[_i]), (LAS unsigned*)(lds + (bufoff) + ldsw + _i * 8192), 16, 0, 0); } while (0)
; #define PG8_LDA(dst, b, h) do { _Pragma("unroll") for (int m = 0; m < 4; ++m) _Pragma("unroll") for (int k = 0; k < 2; ++k) dst[m][k] = *(const LAS bf16x8*)(lds + PG8_SA(b, h) + aoff + m * 2048 + k * 1024); } while (0)
; #define PG8_MMA(ai, bj, At, Bt) do { __builtin_amdgcn_s_setprio(1); _Pragma("unroll") for (int m = 0; m < 4; ++m) _Pragma("unroll") for (int n = 0; n < 2; ++n) _Pragma("unroll") for (int k = 0; k < 2; ++k) \
;         acc[ai][bj][m][n] = __builtin_amdgcn_mfma_f32_16x16x32_bf16(Bt[n][k], At[m][k], acc[ai][bj][m][n], 0, 0, 0); __builtin_amdgcn_s_setprio(0); } while (0)
; #define PG8_WAIT_V(n) asm volatile("s_waitcnt vmcnt(" #n ")" ::: "memory")
; #define PG8_WAIT_L(n) asm volatile("s_waitcnt lgkmcnt(" #n ")" ::: "memory")
; #define PG8_BAR __builtin_amdgcn_s_barrier()
; #define PG8_SCHED __builtin_amdgcn_sched_barrier(0)
; template <int MODE, class EpiT, class Sched>
; __device__ __forceinline__ void gemm_phase(LAS unsigned char* lds, const Gemm g, const Sched& S, const EpiT& E) {
;     ...
;             PG8_BAR; PG8_WAIT_L(0); PG8_MMA(0, 1, At, B1); PG8_BAR;
;             PG8_LDA(At, 1, 1); PG8_STAGE(PG8_SA(1, 0), a3, voffA);
;             PG8_BAR; PG8_WAIT_L(0); PG8_MMA(1, 0, At, B0); PG8_BAR; PG8_SCHED;
;             PG8_STAGE(PG8_SB(1, 1), b3 + hstep, voffB);
;             PG8_WAIT_V(6); PG8_BAR; PG8_MMA(1, 1, At, B1); PG8_BAR;
	s_waitcnt lgkmcnt(0)
	v_mfma_f32_16x16x32_bf16 v[94:97], v[220:223], v[162:165], v[94:97]
	v_mfma_f32_16x16x32_bf16 v[90:93], v[228:231], v[162:165], v[90:93]
	v_mfma_f32_16x16x32_bf16 v[86:89], v[220:223], v[170:173], v[86:89]
	v_mfma_f32_16x16x32_bf16 v[82:85], v[228:231], v[170:173], v[82:85]
	v_mfma_f32_16x16x32_bf16 v[78:81], v[220:223], v[182:185], v[78:81]
	v_mfma_f32_16x16x32_bf16 v[74:77], v[228:231], v[182:185], v[74:77]
	v_mfma_f32_16x16x32_bf16 v[70:73], v[220:223], v[190:193], v[70:73]
	v_mfma_f32_16x16x32_bf16 v[66:69], v[228:231], v[190:193], v[66:69]
	v_mfma_f32_16x16x32_bf16 v[94:97], v[224:227], v[166:169], v[94:97]
	v_mfma_f32_16x16x32_bf16 v[90:93], v[232:235], v[166:169], v[90:93]
	v_mfma_f32_16x16x32_bf16 v[86:89], v[224:227], v[174:177], v[86:89]
	v_mfma_f32_16x16x32_bf16 v[82:85], v[232:235], v[174:177], v[82:85]
	v_mfma_f32_16x16x32_bf16 v[78:81], v[224:227], v[186:189], v[78:81]
	s_barrier
	v_mfma_f32_16x16x32_bf16 v[74:77], v[232:235], v[186:189], v[74:77]
	v_mfma_f32_16x16x32_bf16 v[70:73], v[224:227], v[194:197], v[70:73]
	v_mfma_f32_16x16x32_bf16 v[66:69], v[232:235], v[194:197], v[66:69]
	s_mov_b32 m0, s56
	v_lshl_add_u64 v[198:199], v[238:239], 0, s[76:77]
	ds_read_b128 v[162:165], v160 offset:49152
	ds_read_b128 v[166:169], v160 offset:50176
	ds_read_b128 v[170:173], v160 offset:51200
	ds_read_b128 v[174:177], v160 offset:52224
	ds_read_b128 v[182:185], v160 offset:53248
	ds_read_b128 v[186:189], v160 offset:54272
	ds_read_b128 v[190:193], v160 offset:55296
	ds_read_b128 v[194:197], v160 offset:56320
	global_load_lds_dwordx4 v[198:199], off
	v_lshl_add_u64 v[198:199], v[240:241], 0, s[76:77]
	s_mov_b32 m0, s57
	s_nop 0
	global_load_lds_dwordx4 v[198:199], off
	s_barrier
	s_waitcnt lgkmcnt(0)
	v_mfma_f32_16x16x32_bf16 v[62:65], v[134:137], v[162:165], v[62:65]
	v_mfma_f32_16x16x32_bf16 v[58:61], v[142:145], v[162:165], v[58:61]
	v_mfma_f32_16x16x32_bf16 v[54:57], v[134:137], v[170:173], v[54:57]
	v_mfma_f32_16x16x32_bf16 v[50:53], v[142:145], v[170:173], v[50:53]
	v_mfma_f32_16x16x32_bf16 v[46:49], v[134:137], v[182:185], v[46:49]
	v_mfma_f32_16x16x32_bf16 v[42:45], v[142:145], v[182:185], v[42:45]
	v_mfma_f32_16x16x32_bf16 v[38:41], v[134:137], v[190:193], v[38:41]
	v_mfma_f32_16x16x32_bf16 v[34:37], v[142:145], v[190:193], v[34:37]
	v_mfma_f32_16x16x32_bf16 v[62:65], v[138:141], v[166:169], v[62:65]
	v_mfma_f32_16x16x32_bf16 v[58:61], v[152:155], v[166:169], v[58:61]
	v_mfma_f32_16x16x32_bf16 v[54:57], v[138:141], v[174:177], v[54:57]
	v_mfma_f32_16x16x32_bf16 v[50:53], v[152:155], v[174:177], v[50:53]
	v_mfma_f32_16x16x32_bf16 v[46:49], v[138:141], v[186:189], v[46:49]
	s_barrier
	v_mfma_f32_16x16x32_bf16 v[42:45], v[152:155], v[186:189], v[42:45]
	v_mfma_f32_16x16x32_bf16 v[38:41], v[138:141], v[194:197], v[38:41]
	v_mfma_f32_16x16x32_bf16 v[34:37], v[152:155], v[194:197], v[34:37]
	s_add_i32 s46, s46, s24
	v_lshl_add_u64 v[134:135], v[242:243], 0, s[76:77]
	s_mov_b32 m0, s46
	s_nop 0
	global_load_lds_dwordx4 v[134:135], off
	v_lshl_add_u64 v[134:135], v[244:245], 0, s[76:77]
	s_add_i32 m0, s46, 0x2000
	s_nop 0
	global_load_lds_dwordx4 v[134:135], off
	s_waitcnt vmcnt(6)
	s_barrier
	v_mfma_f32_16x16x32_bf16 v[30:33], v[220:223], v[162:165], v[30:33]
	v_mfma_f32_16x16x32_bf16 v[26:29], v[228:231], v[162:165], v[26:29]
	v_mfma_f32_16x16x32_bf16 v[22:25], v[220:223], v[170:173], v[22:25]
	v_mfma_f32_16x16x32_bf16 v[18:21], v[228:231], v[170:173], v[18:21]
	v_mfma_f32_16x16x32_bf16 v[14:17], v[220:223], v[182:185], v[14:17]
	v_mfma_f32_16x16x32_bf16 v[10:13], v[228:231], v[182:185], v[10:13]
	v_mfma_f32_16x16x32_bf16 v[6:9], v[220:223], v[190:193], v[6:9]
	v_mfma_f32_16x16x32_bf16 v[2:5], v[228:231], v[190:193], v[2:5]
	v_mfma_f32_16x16x32_bf16 v[30:33], v[224:227], v[166:169], v[30:33]
	v_mfma_f32_16x16x32_bf16 v[26:29], v[232:235], v[166:169], v[26:29]
	v_mfma_f32_16x16x32_bf16 v[22:25], v[224:227], v[174:177], v[22:25]
	v_mfma_f32_16x16x32_bf16 v[18:21], v[232:235], v[174:177], v[18:21]
	v_mfma_f32_16x16x32_bf16 v[14:17], v[224:227], v[186:189], v[14:17]
	s_barrier
	v_mfma_f32_16x16x32_bf16 v[10:13], v[232:235], v[186:189], v[10:13]
	v_mfma_f32_16x16x32_bf16 v[6:9], v[224:227], v[194:197], v[6:9]
	v_mfma_f32_16x16x32_bf16 v[2:5], v[232:235], v[194:197], v[2:5]
	s_add_u32 s44, s44, 0x100
	s_addc_u32 s45, s45, 0
	v_lshl_add_u64 v[132:133], v[132:133], 0, s[80:81]
	v_lshl_add_u64 v[130:131], v[130:131], 0, s[80:81]
	s_cmp_ge_u32 s68, s55
	s_mov_b32 s46, s68
	s_cbranch_scc0 .LBB0_280
	v_lshl_or_b32 v152, s3, 8, v159
	v_ashrrev_i32_e32 v153, 31, v152
	v_cndmask_b32_e64 v131, 0, 1, s[28:29]
	v_lshl_add_u64 v[154:155], v[152:153], 2, s[12:13]
	v_mov_b32_e32 v130, 0
	v_cmp_ne_u32_e64 s[44:45], 1, v131
	s_andn2_b64 vcc, exec, s[28:29]
	v_mov_b32_e32 v134, 0
	v_mov_b32_e32 v135, 0
	v_mov_b32_e32 v136, 0
	v_mov_b32_e32 v137, 0
	s_cbranch_vccnz .LBB0_283
	global_load_dwordx4 v[134:137], v[154:155], off

; #define PG8_STAGE(bufoff, gbase, voff) do { _Pragma("unroll") for (int _i = 0; _i < 2; ++_i) \
;         __builtin_amdgcn_global_load_lds((const unsigned*)((const char*)(gbase) + (voff)[_i]), (LAS unsigned*)(lds + (bufoff) + ldsw + _i * 8192), 16, 0, 0); } while (0)
; #define PG8_LDA(dst, b, h) do { _Pragma("unroll") for (int m = 0; m < 4; ++m) _Pragma("unroll") for (int k = 0; k < 2; ++k) dst[m][k] = *(const LAS bf16x8*)(lds + PG8_SA(b, h) + aoff + m * 2048 + k * 1024); } while (0)
; #define PG8_LDB(dst, b, h) do { _Pragma("unroll") for (int n = 0; n < 2; ++n) _Pragma("unroll") for (int k = 0; k < 2; ++k) dst[n][k] = *(const LAS bf16x8*)(lds + PG8_SB(b, h) + boff + n * 2048 + k * 1024); } while (0)
; #define PG8_MMA(ai, bj, At, Bt) do { __builtin_amdgcn_s_setprio(1); _Pragma("unroll") for (int m = 0; m < 4; ++m) _Pragma("unroll") for (int n = 0; n < 2; ++n) _Pragma("unroll") for (int k = 0; k < 2; ++k) \
;         acc[ai][bj][m][n] = __builtin_amdgcn_mfma_f32_16x16x32_bf16(Bt[n][k], At[m][k], acc[ai][bj][m][n], 0, 0, 0); __builtin_amdgcn_s_setprio(0); } while (0)
; #define PG8_WAIT_L(n) asm volatile("s_waitcnt lgkmcnt(" #n ")" ::: "memory")
; #define PG8_BAR __builtin_amdgcn_s_barrier()
; #define PG8_SCHED __builtin_amdgcn_sched_barrier(0)
; template <int MODE, class EpiT, class Sched>
; __device__ __forceinline__ void gemm_phase(LAS unsigned char* lds, const Gemm g, const Sched& S, const EpiT& E) {
;     ...
;             const bool last = (t == nt - 2);
;             const char* a1 = cA + (size_t)(t + 1) * kstep;
;             const char* a2 = last ? nA : cA + (size_t)(t + 2) * kstep; const char* b2 = last ? nB : cB + (size_t)(t + 2) * kstep;
;             const char* a3 = a2 + kstep; const char* b3 = b2 + kstep;
;             PG8_LDB(B0, 0, 0); PG8_SCHED; PG8_LDA(At, 0, 0); PG8_STAGE(PG8_SA(1, 1), a1 + hstep, voffA);
;             PG8_WAIT_L(8); PG8_BAR; PG8_WAIT_L(0); PG8_MMA(0, 0, At, B0); PG8_BAR; PG8_SCHED;
;             PG8_LDB(B1, 0, 1); PG8_STAGE(PG8_SB(0, 0), b2, voffB);
;             PG8_BAR; PG8_WAIT_L(0); PG8_MMA(0, 1, At, B1); PG8_BAR;
;             PG8_LDA(At, 0, 1); PG8_STAGE(PG8_SA(0, 0), a2, voffA);
;             PG8_BAR; PG8_WAIT_L(0); PG8_MMA(1, 0, At, B0); PG8_BAR; PG8_SCHED;
.LBB0_332:
	s_add_i32 s23, s22, 2
	s_add_u32 s30, s12, s4
	s_addc_u32 s38, s13, s5
	s_add_u32 s44, s10, s4
	s_addc_u32 s45, s11, s5
	s_add_i32 s58, 0, 0x10000
	v_add_u32_e32 v145, s58, v141
	ds_read_b128 v[146:149], v145
	ds_read_b128 v[150:153], v145 offset:1024
	ds_read_b128 v[154:157], v145 offset:2048
	ds_read_b128 v[158:161], v145 offset:3072
	s_cmp_eq_u32 s55, s22
	s_cselect_b32 s39, s29, s38
	s_cselect_b32 s38, s28, s30
	s_cselect_b32 s45, s35, s45
	s_cselect_b32 s44, s34, s44
	v_lshl_add_u64 v[198:199], s[12:13], 0, v[138:139]
	s_add_i32 m0, s47, 0xc000
	ds_read_b128 v[162:165], v144
	ds_read_b128 v[166:169], v144 offset:1024
	ds_read_b128 v[170:173], v144 offset:2048
	ds_read_b128 v[174:177], v144 offset:3072
	ds_read_b128 v[182:185], v144 offset:4096
	ds_read_b128 v[186:189], v144 offset:5120
	ds_read_b128 v[190:193], v144 offset:6144
	ds_read_b128 v[194:197], v144 offset:7168
	global_load_lds_dwordx4 v[198:199], off
	v_lshl_add_u64 v[198:199], s[12:13], 0, v[136:137]
	s_add_i32 m0, s47, 0xe000
	s_nop 0
	global_load_lds_dwordx4 v[198:199], off
	s_waitcnt lgkmcnt(8)
	s_barrier
	s_waitcnt lgkmcnt(0)
	v_mfma_f32_16x16x32_bf16 v[126:129], v[146:149], v[162:165], v[126:129]
	v_mfma_f32_16x16x32_bf16 v[122:125], v[154:157], v[162:165], v[122:125]
	v_mfma_f32_16x16x32_bf16 v[118:121], v[146:149], v[170:173], v[118:121]
	v_mfma_f32_16x16x32_bf16 v[114:117], v[154:157], v[170:173], v[114:117]
	v_mfma_f32_16x16x32_bf16 v[110:113], v[146:149], v[182:185], v[110:113]
	v_mfma_f32_16x16x32_bf16 v[106:109], v[154:157], v[182:185], v[106:109]
	v_mfma_f32_16x16x32_bf16 v[102:105], v[146:149], v[190:193], v[102:105]
	v_mfma_f32_16x16x32_bf16 v[98:101], v[154:157], v[190:193], v[98:101]
	v_mfma_f32_16x16x32_bf16 v[126:129], v[150:153], v[166:169], v[126:129]
	v_mfma_f32_16x16x32_bf16 v[122:125], v[158:161], v[166:169], v[122:125]
	v_mfma_f32_16x16x32_bf16 v[118:121], v[150:153], v[174:177], v[118:121]
	v_mfma_f32_16x16x32_bf16 v[114:117], v[158:161], v[174:177], v[114:117]
	v_mfma_f32_16x16x32_bf16 v[110:113], v[150:153], v[186:189], v[110:113]
	s_barrier
	v_mfma_f32_16x16x32_bf16 v[106:109], v[158:161], v[186:189], v[106:109]
	v_mfma_f32_16x16x32_bf16 v[102:105], v[150:153], v[194:197], v[102:105]
	v_mfma_f32_16x16x32_bf16 v[98:101], v[158:161], v[194:197], v[98:101]
	s_add_i32 s22, 0, 0x14000
	s_add_i32 s30, s58, s46
	v_add_u32_e32 v145, s22, v141
	v_lshl_add_u64 v[198:199], s[44:45], 0, v[0:1]
	s_mov_b32 m0, s30
	ds_read_b128 v[220:223], v145
	ds_read_b128 v[224:227], v145 offset:1024
	ds_read_b128 v[228:231], v145 offset:2048
	ds_read_b128 v[232:235], v145 offset:3072
	global_load_lds_dwordx4 v[198:199], off
	v_lshl_add_u64 v[236:237], s[44:45], 0, v[130:131]
	s_add_i32 m0, s30, 0x2000
	s_nop 0
	global_load_lds_dwordx4 v[236:237], off
	s_barrier
	s_waitcnt lgkmcnt(0)
	v_mfma_f32_16x16x32_bf16 v[94:97], v[220:223], v[162:165], v[94:97]
	v_mfma_f32_16x16x32_bf16 v[90:93], v[228:231], v[162:165], v[90:93]
	v_mfma_f32_16x16x32_bf16 v[86:89], v[220:223], v[170:173], v[86:89]
	v_mfma_f32_16x16x32_bf16 v[82:85], v[228:231], v[170:173], v[82:85]
	v_mfma_f32_16x16x32_bf16 v[78:81], v[220:223], v[182:185], v[78:81]
	v_mfma_f32_16x16x32_bf16 v[74:77], v[228:231], v[182:185], v[74:77]
	v_mfma_f32_16x16x32_bf16 v[70:73], v[220:223], v[190:193], v[70:73]
	v_mfma_f32_16x16x32_bf16 v[66:69], v[228:231], v[190:193], v[66:69]
	v_mfma_f32_16x16x32_bf16 v[94:97], v[224:227], v[166:169], v[94:97]
	v_mfma_f32_16x16x32_bf16 v[90:93], v[232:235], v[166:169], v[90:93]
	v_mfma_f32_16x16x32_bf16 v[86:89], v[224:227], v[174:177], v[86:89]
	v_mfma_f32_16x16x32_bf16 v[82:85], v[232:235], v[174:177], v[82:85]
	v_mfma_f32_16x16x32_bf16 v[78:81], v[224:227], v[186:189], v[78:81]
	s_barrier
	v_mfma_f32_16x16x32_bf16 v[74:77], v[232:235], v[186:189], v[74:77]
	v_mfma_f32_16x16x32_bf16 v[70:73], v[224:227], v[194:197], v[70:73]
	v_mfma_f32_16x16x32_bf16 v[66:69], v[232:235], v[194:197], v[66:69]
	s_mov_b32 m0, s47
	v_lshl_add_u64 v[238:239], s[38:39], 0, v[0:1]
	ds_read_b128 v[162:165], v144 offset:16384
	ds_read_b128 v[166:169], v144 offset:17408
	ds_read_b128 v[170:173], v144 offset:18432
	ds_read_b128 v[174:177], v144 offset:19456
	ds_read_b128 v[182:185], v144 offset:20480
	ds_read_b128 v[186:189], v144 offset:21504
	ds_read_b128 v[190:193], v144 offset:22528
	ds_read_b128 v[194:197], v144 offset:23552
	global_load_lds_dwordx4 v[238:239], off
	v_lshl_add_u64 v[240:241], s[38:39], 0, v[130:131]
	s_mov_b32 m0, s50
	s_nop 0
	global_load_lds_dwordx4 v[240:241], off
	s_barrier
	s_waitcnt lgkmcnt(0)
	v_mfma_f32_16x16x32_bf16 v[62:65], v[146:149], v[162:165], v[62:65]
	v_mfma_f32_16x16x32_bf16 v[58:61], v[154:157], v[162:165], v[58:61]
	v_mfma_f32_16x16x32_bf16 v[54:57], v[146:149], v[170:173], v[54:57]
	v_mfma_f32_16x16x32_bf16 v[50:53], v[154:157], v[170:173], v[50:53]
	v_mfma_f32_16x16x32_bf16 v[46:49], v[146:149], v[182:185], v[46:49]
	v_mfma_f32_16x16x32_bf16 v[42:45], v[154:157], v[182:185], v[42:45]
	v_mfma_f32_16x16x32_bf16 v[38:41], v[146:149], v[190:193], v[38:41]
	v_mfma_f32_16x16x32_bf16 v[34:37], v[154:157], v[190:193], v[34:37]
	v_mfma_f32_16x16x32_bf16 v[62:65], v[150:153], v[166:169], v[62:65]
	v_mfma_f32_16x16x32_bf16 v[58:61], v[158:161], v[166:169], v[58:61]
	v_mfma_f32_16x16x32_bf16 v[54:57], v[150:153], v[174:177], v[54:57]
	v_mfma_f32_16x16x32_bf16 v[50:53], v[158:161], v[174:177], v[50:53]
	v_mfma_f32_16x16x32_bf16 v[46:49], v[150:153], v[186:189], v[46:49]
	s_barrier
; #define PG8_STAGE(bufoff, gbase, voff) do { _Pragma("unroll") for (int _i = 0; _i < 2; ++_i) \
;         __builtin_amdgcn_global_load_lds((const unsigned*)((const char*)(gbase) + (voff)[_i]), (LAS unsigned*)(lds + (bufoff) + ldsw + _i * 8192), 16, 0, 0); } while (0)
; #define PG8_LDA(dst, b, h) do { _Pragma("unroll") for (int m = 0; m < 4; ++m) _Pragma("unroll") for (int k = 0; k < 2; ++k) dst[m][k] = *(const LAS bf16x8*)(lds + PG8_SA(b, h) + aoff + m * 2048 + k * 1024); } while (0)
; #define PG8_LDB(dst, b, h) do { _Pragma("unroll") for (int n = 0; n < 2; ++n) _Pragma("unroll") for (int k = 0; k < 2; ++k) dst[n][k] = *(const LAS bf16x8*)(lds + PG8_SB(b, h) + boff + n * 2048 + k * 1024); } while (0)
; #define PG8_WAIT_V(n) asm volatile("s_waitcnt vmcnt(" #n ")" ::: "memory")
; #define PG8_WAIT_L(n) asm volatile("s_waitcnt lgkmcnt(" #n ")" ::: "memory")
; #define PG8_BAR __builtin_amdgcn_s_barrier()
; #define PG8_SCHED __builtin_amdgcn_sched_barrier(0)
; template <int MODE, class EpiT, class Sched>
; __device__ __forceinline__ void gemm_phase(LAS unsigned char* lds, const Gemm g, const Sched& S, const EpiT& E) {
;     ...
;             PG8_LDB(B0, 0, 0); PG8_SCHED; PG8_LDA(At, 0, 0); PG8_STAGE(PG8_SA(1, 1), a1 + hstep, voffA);
;             PG8_WAIT_L(8); PG8_BAR; PG8_WAIT_L(0); PG8_MMA(0, 0, At, B0); PG8_BAR; PG8_SCHED;
;             PG8_LDB(B1, 0, 1); PG8_STAGE(PG8_SB(0, 0), b2, voffB);
;             PG8_BAR; PG8_WAIT_L(0); PG8_MMA(0, 1, At, B1); PG8_BAR;
;             PG8_LDA(At, 0, 1); PG8_STAGE(PG8_SA(0, 0), a2, voffA);
;             PG8_BAR; PG8_WAIT_L(0); PG8_MMA(1, 0, At, B0); PG8_BAR; PG8_SCHED;
;             PG8_STAGE(PG8_SB(0, 1), b2 + hstep, voffB);
;             PG8_WAIT_V(6); PG8_BAR; PG8_MMA(1, 1, At, B1); PG8_BAR;
;             PG8_LDB(B0, 1, 0); PG8_SCHED; PG8_LDA(At, 1, 0); PG8_STAGE(PG8_SA(0, 1), a2 + hstep, voffA);
;             PG8_WAIT_L(8); PG8_BAR; PG8_WAIT_L(0); PG8_MMA(0, 0, At, B0); PG8_BAR; PG8_SCHED;
;             PG8_LDB(B1, 1, 1); PG8_STAGE(PG8_SB(1, 0), b3, voffB);
;             PG8_BAR; PG8_WAIT_L(0); PG8_MMA(0, 1, At, B1); PG8_BAR;
;             PG8_LDA(At, 1, 1); PG8_STAGE(PG8_SA(1, 0), a3, voffA);
;             PG8_BAR; PG8_WAIT_L(0); PG8_MMA(1, 0, At, B0); PG8_BAR; PG8_SCHED;
;             PG8_STAGE(PG8_SB(1, 1), b3 + hstep, voffB);
;             PG8_WAIT_V(6); PG8_BAR; PG8_MMA(1, 1, At, B1); PG8_BAR;
	v_mfma_f32_16x16x32_bf16 v[42:45], v[158:161], v[186:189], v[42:45]
	v_mfma_f32_16x16x32_bf16 v[38:41], v[150:153], v[194:197], v[38:41]
	v_mfma_f32_16x16x32_bf16 v[34:37], v[158:161], v[194:197], v[34:37]
	s_add_u32 s44, s44, s21
	s_addc_u32 s45, s45, 0
	s_add_i32 s22, s22, s46
	v_lshl_add_u64 v[242:243], s[44:45], 0, v[0:1]
	s_mov_b32 m0, s22
	v_lshl_add_u64 v[244:245], s[44:45], 0, v[130:131]
	global_load_lds_dwordx4 v[242:243], off
	s_add_i32 m0, s22, 0x2000
	s_nop 0
	global_load_lds_dwordx4 v[244:245], off
	s_waitcnt vmcnt(6)
	s_barrier
	v_mfma_f32_16x16x32_bf16 v[30:33], v[220:223], v[162:165], v[30:33]
	v_mfma_f32_16x16x32_bf16 v[26:29], v[228:231], v[162:165], v[26:29]
	v_mfma_f32_16x16x32_bf16 v[22:25], v[220:223], v[170:173], v[22:25]
	v_mfma_f32_16x16x32_bf16 v[18:21], v[228:231], v[170:173], v[18:21]
	v_mfma_f32_16x16x32_bf16 v[14:17], v[220:223], v[182:185], v[14:17]
	v_mfma_f32_16x16x32_bf16 v[10:13], v[228:231], v[182:185], v[10:13]
	v_mfma_f32_16x16x32_bf16 v[6:9], v[220:223], v[190:193], v[6:9]
	v_mfma_f32_16x16x32_bf16 v[2:5], v[228:231], v[190:193], v[2:5]
	v_mfma_f32_16x16x32_bf16 v[30:33], v[224:227], v[166:169], v[30:33]
	v_mfma_f32_16x16x32_bf16 v[26:29], v[232:235], v[166:169], v[26:29]
	v_mfma_f32_16x16x32_bf16 v[22:25], v[224:227], v[174:177], v[22:25]
	v_mfma_f32_16x16x32_bf16 v[18:21], v[232:235], v[174:177], v[18:21]
	v_mfma_f32_16x16x32_bf16 v[14:17], v[224:227], v[186:189], v[14:17]
	s_barrier
	v_mfma_f32_16x16x32_bf16 v[10:13], v[232:235], v[186:189], v[10:13]
	v_mfma_f32_16x16x32_bf16 v[6:9], v[224:227], v[194:197], v[6:9]
	v_mfma_f32_16x16x32_bf16 v[2:5], v[232:235], v[194:197], v[2:5]
	s_add_i32 s22, 0, 0x18000
	v_add_u32_e32 v145, s22, v141
	ds_read_b128 v[146:149], v145
	ds_read_b128 v[150:153], v145 offset:1024
	ds_read_b128 v[154:157], v145 offset:2048
	ds_read_b128 v[158:161], v145 offset:3072
	s_add_u32 s38, s38, s21
	s_addc_u32 s39, s39, 0
	s_mov_b32 m0, s51
	v_lshl_add_u64 v[220:221], s[38:39], 0, v[0:1]
	ds_read_b128 v[162:165], v144 offset:32768
	ds_read_b128 v[166:169], v144 offset:33792
	ds_read_b128 v[170:173], v144 offset:34816
	ds_read_b128 v[174:177], v144 offset:35840
	ds_read_b128 v[182:185], v144 offset:36864
	ds_read_b128 v[186:189], v144 offset:37888
	ds_read_b128 v[190:193], v144 offset:38912
	ds_read_b128 v[194:197], v144 offset:39936
	global_load_lds_dwordx4 v[220:221], off
	v_lshl_add_u64 v[220:221], s[38:39], 0, v[130:131]
	s_mov_b32 m0, s52
	s_nop 0
	global_load_lds_dwordx4 v[220:221], off
	s_waitcnt lgkmcnt(8)
	s_barrier
	s_waitcnt lgkmcnt(0)
	v_mfma_f32_16x16x32_bf16 v[126:129], v[146:149], v[162:165], v[126:129]
	v_mfma_f32_16x16x32_bf16 v[122:125], v[154:157], v[162:165], v[122:125]
	v_mfma_f32_16x16x32_bf16 v[118:121], v[146:149], v[170:173], v[118:121]
	v_mfma_f32_16x16x32_bf16 v[114:117], v[154:157], v[170:173], v[114:117]
	v_mfma_f32_16x16x32_bf16 v[110:113], v[146:149], v[182:185], v[110:113]
	v_mfma_f32_16x16x32_bf16 v[106:109], v[154:157], v[182:185], v[106:109]
	v_mfma_f32_16x16x32_bf16 v[102:105], v[146:149], v[190:193], v[102:105]
	v_mfma_f32_16x16x32_bf16 v[98:101], v[154:157], v[190:193], v[98:101]
	v_mfma_f32_16x16x32_bf16 v[126:129], v[150:153], v[166:169], v[126:129]
	v_mfma_f32_16x16x32_bf16 v[122:125], v[158:161], v[166:169], v[122:125]
	v_mfma_f32_16x16x32_bf16 v[118:121], v[150:153], v[174:177], v[118:121]
	v_mfma_f32_16x16x32_bf16 v[114:117], v[158:161], v[174:177], v[114:117]
	v_mfma_f32_16x16x32_bf16 v[110:113], v[150:153], v[186:189], v[110:113]
	s_barrier
	v_mfma_f32_16x16x32_bf16 v[106:109], v[158:161], v[186:189], v[106:109]
	v_mfma_f32_16x16x32_bf16 v[102:105], v[150:153], v[194:197], v[102:105]
	v_mfma_f32_16x16x32_bf16 v[98:101], v[158:161], v[194:197], v[98:101]
	s_add_i32 s30, 0, 0x1c000
	s_add_i32 s22, s22, s46
	v_add_u32_e32 v145, s30, v141
	v_lshl_add_u64 v[198:199], v[198:199], 0, s[76:77]
	s_mov_b32 m0, s22
	ds_read_b128 v[220:223], v145
	ds_read_b128 v[224:227], v145 offset:1024
	ds_read_b128 v[228:231], v145 offset:2048
	ds_read_b128 v[232:235], v145 offset:3072
	global_load_lds_dwordx4 v[198:199], off
	v_lshl_add_u64 v[198:199], v[236:237], 0, s[76:77]
	s_add_i32 m0, s22, 0x2000
	s_nop 0
	global_load_lds_dwordx4 v[198:199], off
	s_barrier
	s_waitcnt lgkmcnt(0)
	v_mfma_f32_16x16x32_bf16 v[94:97], v[220:223], v[162:165], v[94:97]
	v_mfma_f32_16x16x32_bf16 v[90:93], v[228:231], v[162:165], v[90:93]
	v_mfma_f32_16x16x32_bf16 v[86:89], v[220:223], v[170:173], v[86:89]
	v_mfma_f32_16x16x32_bf16 v[82:85], v[228:231], v[170:173], v[82:85]
	v_mfma_f32_16x16x32_bf16 v[78:81], v[220:223], v[182:185], v[78:81]
	v_mfma_f32_16x16x32_bf16 v[74:77], v[228:231], v[182:185], v[74:77]
	v_mfma_f32_16x16x32_bf16 v[70:73], v[220:223], v[190:193], v[70:73]
	v_mfma_f32_16x16x32_bf16 v[66:69], v[228:231], v[190:193], v[66:69]
	v_mfma_f32_16x16x32_bf16 v[94:97], v[224:227], v[166:169], v[94:97]
	v_mfma_f32_16x16x32_bf16 v[90:93], v[232:235], v[166:169], v[90:93]
	v_mfma_f32_16x16x32_bf16 v[86:89], v[224:227], v[174:177], v[86:89]
	v_mfma_f32_16x16x32_bf16 v[82:85], v[232:235], v[174:177], v[82:85]
	v_mfma_f32_16x16x32_bf16 v[78:81], v[224:227], v[186:189], v[78:81]
	s_barrier
	v_mfma_f32_16x16x32_bf16 v[74:77], v[232:235], v[186:189], v[74:77]
	v_mfma_f32_16x16x32_bf16 v[70:73], v[224:227], v[194:197], v[70:73]
	v_mfma_f32_16x16x32_bf16 v[66:69], v[232:235], v[194:197], v[66:69]
	s_mov_b32 m0, s53
	v_lshl_add_u64 v[198:199], v[238:239], 0, s[76:77]
	ds_read_b128 v[162:165], v144 offset:49152
	ds_read_b128 v[166:169], v144 offset:50176
	ds_read_b128 v[170:173], v144 offset:51200
	ds_read_b128 v[174:177], v144 offset:52224
	ds_read_b128 v[182:185], v144 offset:53248
	ds_read_b128 v[186:189], v144 offset:54272
	ds_read_b128 v[190:193], v144 offset:55296
	ds_read_b128 v[194:197], v144 offset:56320
	global_load_lds_dwordx4 v[198:199], off
	v_lshl_add_u64 v[198:199], v[240:241], 0, s[76:77]
	s_mov_b32 m0, s54
	s_nop 0
	global_load_lds_dwordx4 v[198:199], off
	s_barrier
; __device__ __forceinline__ unsigned pk2(float lo, float hi) { unsigned r; asm volatile("v_cvt_pk_bf16_f32 %0, %1, %2" : "=v"(r) : "v"(lo), "v"(hi)); return r; }
; __device__ __forceinline__ float siluf_(float x) { return x * __builtin_amdgcn_rcpf(1.0f + __expf(-x)); }
; #define PG8_LDA(dst, b, h) do { _Pragma("unroll") for (int m = 0; m < 4; ++m) _Pragma("unroll") for (int k = 0; k < 2; ++k) dst[m][k] = *(const LAS bf16x8*)(lds + PG8_SA(b, h) + aoff + m * 2048 + k * 1024); } while (0)
;     template <int mode> __device__ __forceinline__ void run(const f32x4 (&acc)[2][2][4][2], const Unit& u, int wr, int wc, int fr, int fq, const LAS float* sc) const {
;     ...
;         if (mode == 0) {
;             const int col0 = u.pn * HALF + wc * 32 + 8 * fq;
; #pragma unroll
;             for (int ai = 0; ai < 2; ++ai)
; #pragma unroll
;                 for (int m = 0; m < 4; ++m) {
;                     const int row = row0 + ai * HALF + m * 16;
;                     const float s = sc[ai * HALF + wr * 64 + m * 16 + fr];
;                     const f32x4 g0 = acc[ai][0][m][0] * s, u0 = acc[ai][1][m][0] * s, g1 = acc[ai][0][m][1] * s, u1 = acc[ai][1][m][1] * s;
;                     u32x4 w;
;                     w.x = pk2(siluf_(g0[0]) * u0[0], siluf_(g0[1]) * u0[1]); w.y = pk2(siluf_(g0[2]) * u0[2], siluf_(g0[3]) * u0[3]);
;                     w.z = pk2(siluf_(g1[0]) * u1[0], siluf_(g1[1]) * u1[1]); w.w = pk2(siluf_(g1[2]) * u1[2], siluf_(g1[3]) * u1[3]);
;                     *(u32x4*)(ob + (size_t)row * FF + col0) = w;
; template <int MODE, class EpiT, class Sched>
; __device__ __forceinline__ void gemm_phase(LAS unsigned char* lds, const Gemm g, const Sched& S, const EpiT& E) {
;     ...
;             PG8_WAIT_V(6); PG8_BAR; PG8_MMA(1, 1, At, B1); PG8_BAR;
;             PG8_LDB(B0, 1, 0); PG8_SCHED; PG8_LDA(At, 1, 0); PG8_STAGE(PG8_SA(0, 1), a2 + hstep, voffA);
;             PG8_WAIT_L(8); PG8_BAR; PG8_WAIT_L(0); PG8_MMA(0, 0, At, B0); PG8_BAR; PG8_SCHED;
;             PG8_LDB(B1, 1, 1); PG8_STAGE(PG8_SB(1, 0), b3, voffB);
;             PG8_BAR; PG8_WAIT_L(0); PG8_MMA(0, 1, At, B1); PG8_BAR;
;             PG8_LDA(At, 1, 1); PG8_STAGE(PG8_SA(1, 0), a3, voffA);
;             PG8_BAR; PG8_WAIT_L(0); PG8_MMA(1, 0, At, B0); PG8_BAR; PG8_SCHED;
;             PG8_STAGE(PG8_SB(1, 1), b3 + hstep, voffB);
;             PG8_WAIT_V(6); PG8_BAR; PG8_MMA(1, 1, At, B1); PG8_BAR;
	s_waitcnt lgkmcnt(0)
	v_mfma_f32_16x16x32_bf16 v[62:65], v[146:149], v[162:165], v[62:65]
	v_mfma_f32_16x16x32_bf16 v[58:61], v[154:157], v[162:165], v[58:61]
	v_mfma_f32_16x16x32_bf16 v[54:57], v[146:149], v[170:173], v[54:57]
	v_mfma_f32_16x16x32_bf16 v[50:53], v[154:157], v[170:173], v[50:53]
	v_mfma_f32_16x16x32_bf16 v[46:49], v[146:149], v[182:185], v[46:49]
	v_mfma_f32_16x16x32_bf16 v[42:45], v[154:157], v[182:185], v[42:45]
	v_mfma_f32_16x16x32_bf16 v[38:41], v[146:149], v[190:193], v[38:41]
	v_mfma_f32_16x16x32_bf16 v[34:37], v[154:157], v[190:193], v[34:37]
	v_mfma_f32_16x16x32_bf16 v[62:65], v[150:153], v[166:169], v[62:65]
	v_mfma_f32_16x16x32_bf16 v[58:61], v[158:161], v[166:169], v[58:61]
	v_mfma_f32_16x16x32_bf16 v[54:57], v[150:153], v[174:177], v[54:57]
	v_mfma_f32_16x16x32_bf16 v[50:53], v[158:161], v[174:177], v[50:53]
	v_mfma_f32_16x16x32_bf16 v[46:49], v[150:153], v[186:189], v[46:49]
	s_barrier
	v_mfma_f32_16x16x32_bf16 v[42:45], v[158:161], v[186:189], v[42:45]
	v_mfma_f32_16x16x32_bf16 v[38:41], v[150:153], v[194:197], v[38:41]
	v_mfma_f32_16x16x32_bf16 v[34:37], v[158:161], v[194:197], v[34:37]
	s_add_i32 s22, s30, s46
	v_lshl_add_u64 v[146:147], v[242:243], 0, s[76:77]
	s_mov_b32 m0, s22
	s_nop 0
	global_load_lds_dwordx4 v[146:147], off
	v_lshl_add_u64 v[146:147], v[244:245], 0, s[76:77]
	s_add_i32 m0, s22, 0x2000
	s_nop 0
	global_load_lds_dwordx4 v[146:147], off
	s_waitcnt vmcnt(6)
	s_barrier
	v_mfma_f32_16x16x32_bf16 v[30:33], v[220:223], v[162:165], v[30:33]
	v_mfma_f32_16x16x32_bf16 v[26:29], v[228:231], v[162:165], v[26:29]
	v_mfma_f32_16x16x32_bf16 v[22:25], v[220:223], v[170:173], v[22:25]
	v_mfma_f32_16x16x32_bf16 v[18:21], v[228:231], v[170:173], v[18:21]
	v_mfma_f32_16x16x32_bf16 v[14:17], v[220:223], v[182:185], v[14:17]
	v_mfma_f32_16x16x32_bf16 v[10:13], v[228:231], v[182:185], v[10:13]
	v_mfma_f32_16x16x32_bf16 v[6:9], v[220:223], v[190:193], v[6:9]
	v_mfma_f32_16x16x32_bf16 v[2:5], v[228:231], v[190:193], v[2:5]
	v_mfma_f32_16x16x32_bf16 v[30:33], v[224:227], v[166:169], v[30:33]
	v_mfma_f32_16x16x32_bf16 v[26:29], v[232:235], v[166:169], v[26:29]
	v_mfma_f32_16x16x32_bf16 v[22:25], v[224:227], v[174:177], v[22:25]
	v_mfma_f32_16x16x32_bf16 v[18:21], v[232:235], v[174:177], v[18:21]
	v_mfma_f32_16x16x32_bf16 v[14:17], v[224:227], v[186:189], v[14:17]
	s_barrier
	v_mfma_f32_16x16x32_bf16 v[10:13], v[232:235], v[186:189], v[10:13]
	v_mfma_f32_16x16x32_bf16 v[6:9], v[224:227], v[194:197], v[6:9]
	v_mfma_f32_16x16x32_bf16 v[2:5], v[232:235], v[194:197], v[2:5]
	s_add_u32 s4, s4, 0x100
	s_addc_u32 s5, s5, 0
	v_lshl_add_u64 v[138:139], v[138:139], 0, s[80:81]
	v_lshl_add_u64 v[136:137], v[136:137], 0, s[80:81]
	s_cmp_ge_u32 s23, s16
	s_mov_b32 s22, s23
	s_cbranch_scc0 .LBB0_332
	v_lshl_add_u32 v145, s57, 10, v142
	ds_read_b32 v136, v145
	v_lshl_or_b32 v138, s8, 7, v143
	v_lshl_add_u32 v146, s9, 8, v140
	v_ashrrev_i32_e32 v139, 31, v138
	v_lshlrev_b64 v[138:139], 1, v[138:139]
	s_waitcnt lgkmcnt(0)
	v_pk_mul_f32 v[148:149], v[126:127], v[136:137] op_sel_hi:[1,0]
	v_pk_mul_f32 v[154:155], v[94:95], v[136:137] op_sel_hi:[1,0]
	v_mul_f32_e32 v147, 0xbfb8aa3b, v148
	v_exp_f32_e32 v147, v147
	v_pk_mul_f32 v[150:151], v[128:129], v[136:137] op_sel_hi:[1,0]
	v_pk_mul_f32 v[152:153], v[96:97], v[136:137] op_sel_hi:[1,0]
	v_pk_mul_f32 v[158:159], v[122:123], v[136:137] op_sel_hi:[1,0]
	v_add_f32_e32 v147, 1.0, v147
	v_rcp_f32_e32 v147, v147
	v_pk_mul_f32 v[156:157], v[124:125], v[136:137] op_sel_hi:[1,0]
	v_pk_mul_f32 v[160:161], v[92:93], v[136:137] op_sel_hi:[1,0]
	v_pk_mul_f32 v[136:137], v[90:91], v[136:137] op_sel_hi:[1,0]
	v_mul_f32_e32 v147, v148, v147
	v_mul_f32_e32 v148, 0xbfb8aa3b, v149
	v_exp_f32_e32 v148, v148
	v_mul_f32_e32 v147, v154, v147
	s_and_b64 vcc, exec, s[42:43]
	v_add_f32_e32 v148, 1.0, v148
	v_rcp_f32_e32 v148, v148
	s_nop 0
	v_mul_f32_e32 v148, v149, v148
	v_mul_f32_e32 v148, v155, v148
	v_cvt_pk_bf16_f32 v148, v147, v148
	v_mul_f32_e32 v147, 0xbfb8aa3b, v150
	v_mul_f32_e32 v149, 0xbfb8aa3b, v151
	v_exp_f32_e32 v147, v147
	v_exp_f32_e32 v149, v149
	v_add_f32_e32 v147, 1.0, v147
	v_add_f32_e32 v149, 1.0, v149
	v_rcp_f32_e32 v147, v147
	v_rcp_f32_e32 v149, v149
	v_mul_f32_e32 v147, v150, v147
	v_mul_f32_e32 v149, v151, v149
	v_mul_f32_e32 v147, v152, v147
	v_mul_f32_e32 v149, v153, v149
	v_cvt_pk_bf16_f32 v149, v147, v149
	v_mul_f32_e32 v147, 0xbfb8aa3b, v158
	v_exp_f32_e32 v147, v147
	s_nop 0
	v_add_f32_e32 v147, 1.0, v147
	v_rcp_f32_e32 v147, v147
	s_nop 0
	v_mul_f32_e32 v147, v158, v147
	v_mul_f32_e32 v136, v136, v147
	v_mul_f32_e32 v147, 0xbfb8aa3b, v159
	v_exp_f32_e32 v147, v147
	s_nop 0
	v_add_f32_e32 v147, 1.0, v147
	v_rcp_f32_e32 v147, v147
	s_nop 0
	v_mul_f32_e32 v147, v159, v147
	v_mul_f32_e32 v137, v137, v147
	v_cvt_pk_bf16_f32 v150, v136, v137
	v_mul_f32_e32 v136, 0xbfb8aa3b, v156
	v_mul_f32_e32 v137, 0xbfb8aa3b, v157
	v_exp_f32_e32 v136, v136
	v_exp_f32_e32 v137, v137
	v_or_b32_e32 v147, 16, v146
	v_add_f32_e32 v136, 1.0, v136
	v_add_f32_e32 v137, 1.0, v137
	v_rcp_f32_e32 v136, v136
	v_rcp_f32_e32 v137, v137
	v_mul_f32_e32 v136, v156, v136
	v_mul_f32_e32 v137, v157, v137
	v_mul_f32_e32 v136, v160, v136
	v_mul_f32_e32 v137, v161, v137
	v_cvt_pk_bf16_f32 v151, v136, v137
	v_mov_b64_e32 v[136:137], s[6:7]
	v_mad_i64_i32 v[152:153], s[4:5], v146, s33, v[136:137]
	v_lshl_add_u64 v[152:153], v[152:153], 0, v[138:139]
	global_store_dwordx4 v[152:153], v[148:151], off
	ds_read_b32 v148, v145 offset:64
	s_waitcnt lgkmcnt(0)
; __device__ __forceinline__ unsigned pk2(float lo, float hi) { unsigned r; asm volatile("v_cvt_pk_bf16_f32 %0, %1, %2" : "=v"(r) : "v"(lo), "v"(hi)); return r; }
; __device__ __forceinline__ float siluf_(float x) { return x * __builtin_amdgcn_rcpf(1.0f + __expf(-x)); }
;     template <int mode> __device__ __forceinline__ void run(const f32x4 (&acc)[2][2][4][2], const Unit& u, int wr, int wc, int fr, int fq, const LAS float* sc) const {
;     ...
; #pragma unroll
;             for (int ai = 0; ai < 2; ++ai)
; #pragma unroll
;                 for (int m = 0; m < 4; ++m) {
;                     const int row = row0 + ai * HALF + m * 16;
;                     const float s = sc[ai * HALF + wr * 64 + m * 16 + fr];
;                     const f32x4 g0 = acc[ai][0][m][0] * s, u0 = acc[ai][1][m][0] * s, g1 = acc[ai][0][m][1] * s, u1 = acc[ai][1][m][1] * s;
;                     u32x4 w;
;                     w.x = pk2(siluf_(g0[0]) * u0[0], siluf_(g0[1]) * u0[1]); w.y = pk2(siluf_(g0[2]) * u0[2], siluf_(g0[3]) * u0[3]);
;                     w.z = pk2(siluf_(g1[0]) * u1[0], siluf_(g1[1]) * u1[1]); w.w = pk2(siluf_(g1[2]) * u1[2], siluf_(g1[3]) * u1[3]);
;                     *(u32x4*)(ob + (size_t)row * FF + col0) = w;
	v_pk_mul_f32 v[152:153], v[118:119], v[148:149] op_sel_hi:[1,0]
	v_pk_mul_f32 v[150:151], v[120:121], v[148:149] op_sel_hi:[1,0]
	v_pk_mul_f32 v[154:155], v[88:89], v[148:149] op_sel_hi:[1,0]
	v_pk_mul_f32 v[156:157], v[86:87], v[148:149] op_sel_hi:[1,0]
	v_pk_mul_f32 v[158:159], v[116:117], v[148:149] op_sel_hi:[1,0]
	v_pk_mul_f32 v[160:161], v[114:115], v[148:149] op_sel_hi:[1,0]
	v_pk_mul_f32 v[162:163], v[84:85], v[148:149] op_sel_hi:[1,0]
	v_pk_mul_f32 v[164:165], v[82:83], v[148:149] op_sel_hi:[1,0]
	v_mul_f32_e32 v148, 0xbfb8aa3b, v152
	v_mul_f32_e32 v149, 0xbfb8aa3b, v153
	v_exp_f32_e32 v148, v148
	v_exp_f32_e32 v149, v149
	v_add_f32_e32 v148, 1.0, v148
	v_add_f32_e32 v149, 1.0, v149
	v_rcp_f32_e32 v148, v148
	v_rcp_f32_e32 v149, v149
	v_mul_f32_e32 v148, v152, v148
	v_mul_f32_e32 v149, v153, v149
	v_mul_f32_e32 v148, v156, v148
	v_mul_f32_e32 v149, v157, v149
	v_cvt_pk_bf16_f32 v148, v148, v149
	v_mul_f32_e32 v149, 0xbfb8aa3b, v150
	v_exp_f32_e32 v149, v149
	v_mul_f32_e32 v152, 0xbfb8aa3b, v159
	v_exp_f32_e32 v152, v152
	v_add_f32_e32 v149, 1.0, v149
	v_rcp_f32_e32 v149, v149
	v_add_f32_e32 v152, 1.0, v152
	v_rcp_f32_e32 v152, v152
	v_mul_f32_e32 v149, v150, v149
	v_mul_f32_e32 v150, 0xbfb8aa3b, v151
	v_exp_f32_e32 v150, v150
	v_mul_f32_e32 v149, v154, v149
	v_mul_f32_e32 v152, v159, v152
	v_mul_f32_e32 v152, v163, v152
	v_add_f32_e32 v150, 1.0, v150
	v_rcp_f32_e32 v150, v150
	s_nop 0
	v_mul_f32_e32 v150, v151, v150
	v_mul_f32_e32 v150, v155, v150
	v_cvt_pk_bf16_f32 v149, v149, v150
	v_mul_f32_e32 v150, 0xbfb8aa3b, v160
	v_mul_f32_e32 v151, 0xbfb8aa3b, v161
	v_exp_f32_e32 v150, v150
	v_exp_f32_e32 v151, v151
	v_add_f32_e32 v150, 1.0, v150
	v_add_f32_e32 v151, 1.0, v151
	v_rcp_f32_e32 v150, v150
	v_rcp_f32_e32 v151, v151
	v_mul_f32_e32 v150, v160, v150
	v_mul_f32_e32 v151, v161, v151
	v_mul_f32_e32 v150, v164, v150
	v_mul_f32_e32 v151, v165, v151
	v_cvt_pk_bf16_f32 v150, v150, v151
	v_mul_f32_e32 v151, 0xbfb8aa3b, v158
	v_exp_f32_e32 v151, v151
	s_nop 0
	v_add_f32_e32 v151, 1.0, v151
	v_rcp_f32_e32 v151, v151
	s_nop 0
	v_mul_f32_e32 v151, v158, v151
	v_mul_f32_e32 v151, v162, v151
	v_cvt_pk_bf16_f32 v151, v151, v152
	v_mad_i64_i32 v[152:153], s[4:5], v147, s33, v[136:137]
	v_lshl_add_u64 v[152:153], v[152:153], 0, v[138:139]
	global_store_dwordx4 v[152:153], v[148:151], off
	ds_read_b32 v148, v145 offset:128
	v_or_b32_e32 v147, 32, v146
	s_waitcnt lgkmcnt(0)
	v_pk_mul_f32 v[152:153], v[110:111], v[148:149] op_sel_hi:[1,0]
	v_pk_mul_f32 v[150:151], v[112:113], v[148:149] op_sel_hi:[1,0]
	v_pk_mul_f32 v[154:155], v[80:81], v[148:149] op_sel_hi:[1,0]
	v_pk_mul_f32 v[156:157], v[78:79], v[148:149] op_sel_hi:[1,0]
	v_pk_mul_f32 v[158:159], v[108:109], v[148:149] op_sel_hi:[1,0]
	v_pk_mul_f32 v[160:161], v[106:107], v[148:149] op_sel_hi:[1,0]
	v_pk_mul_f32 v[162:163], v[76:77], v[148:149] op_sel_hi:[1,0]
	v_pk_mul_f32 v[164:165], v[74:75], v[148:149] op_sel_hi:[1,0]
	v_mul_f32_e32 v148, 0xbfb8aa3b, v152
	v_mul_f32_e32 v149, 0xbfb8aa3b, v153
	v_exp_f32_e32 v148, v148
	v_exp_f32_e32 v149, v149
	v_add_f32_e32 v148, 1.0, v148
	v_add_f32_e32 v149, 1.0, v149
	v_rcp_f32_e32 v148, v148
	v_rcp_f32_e32 v149, v149
	v_mul_f32_e32 v148, v152, v148
	v_mul_f32_e32 v149, v153, v149
	v_mul_f32_e32 v148, v156, v148
	v_mul_f32_e32 v149, v157, v149
	v_cvt_pk_bf16_f32 v148, v148, v149
	v_mul_f32_e32 v149, 0xbfb8aa3b, v150
	v_exp_f32_e32 v149, v149
	v_mul_f32_e32 v152, 0xbfb8aa3b, v159
	v_exp_f32_e32 v152, v152
	v_add_f32_e32 v149, 1.0, v149
	v_rcp_f32_e32 v149, v149
	v_add_f32_e32 v152, 1.0, v152
	v_rcp_f32_e32 v152, v152
	v_mul_f32_e32 v149, v150, v149
	v_mul_f32_e32 v150, 0xbfb8aa3b, v151
	v_exp_f32_e32 v150, v150
	v_mul_f32_e32 v149, v154, v149
	v_mul_f32_e32 v152, v159, v152
	v_mul_f32_e32 v152, v163, v152
	v_add_f32_e32 v150, 1.0, v150
	v_rcp_f32_e32 v150, v150
	s_nop 0
	v_mul_f32_e32 v150, v151, v150
	v_mul_f32_e32 v150, v155, v150
	v_cvt_pk_bf16_f32 v149, v149, v150
	v_mul_f32_e32 v150, 0xbfb8aa3b, v160
	v_mul_f32_e32 v151, 0xbfb8aa3b, v161
	v_exp_f32_e32 v150, v150
	v_exp_f32_e32 v151, v151
	v_add_f32_e32 v150, 1.0, v150
	v_add_f32_e32 v151, 1.0, v151
	v_rcp_f32_e32 v150, v150
	v_rcp_f32_e32 v151, v151
	v_mul_f32_e32 v150, v160, v150
	v_mul_f32_e32 v151, v161, v151
	v_mul_f32_e32 v150, v164, v150
	v_mul_f32_e32 v151, v165, v151
	v_cvt_pk_bf16_f32 v150, v150, v151
	v_mul_f32_e32 v151, 0xbfb8aa3b, v158
	v_exp_f32_e32 v151, v151
	s_nop 0
	v_add_f32_e32 v151, 1.0, v151
	v_rcp_f32_e32 v151, v151
	s_nop 0
	v_mul_f32_e32 v151, v158, v151
	v_mul_f32_e32 v151, v162, v151
	v_cvt_pk_bf16_f32 v151, v151, v152
	v_mad_i64_i32 v[152:153], s[4:5], v147, s33, v[136:137]
	v_lshl_add_u64 v[152:153], v[152:153], 0, v[138:139]
	global_store_dwordx4 v[152:153], v[148:151], off
	ds_read_b32 v148, v145 offset:192
	v_or_b32_e32 v147, 48, v146
	s_waitcnt lgkmcnt(0)
; __device__ __forceinline__ unsigned pk2(float lo, float hi) { unsigned r; asm volatile("v_cvt_pk_bf16_f32 %0, %1, %2" : "=v"(r) : "v"(lo), "v"(hi)); return r; }
; __device__ __forceinline__ float siluf_(float x) { return x * __builtin_amdgcn_rcpf(1.0f + __expf(-x)); }
;     template <int mode> __device__ __forceinline__ void run(const f32x4 (&acc)[2][2][4][2], const Unit& u, int wr, int wc, int fr, int fq, const LAS float* sc) const {
;     ...
; #pragma unroll
;             for (int ai = 0; ai < 2; ++ai)
; #pragma unroll
;                 for (int m = 0; m < 4; ++m) {
;                     const int row = row0 + ai * HALF + m * 16;
;                     const float s = sc[ai * HALF + wr * 64 + m * 16 + fr];
;                     const f32x4 g0 = acc[ai][0][m][0] * s, u0 = acc[ai][1][m][0] * s, g1 = acc[ai][0][m][1] * s, u1 = acc[ai][1][m][1] * s;
;                     u32x4 w;
;                     w.x = pk2(siluf_(g0[0]) * u0[0], siluf_(g0[1]) * u0[1]); w.y = pk2(siluf_(g0[2]) * u0[2], siluf_(g0[3]) * u0[3]);
;                     w.z = pk2(siluf_(g1[0]) * u1[0], siluf_(g1[1]) * u1[1]); w.w = pk2(siluf_(g1[2]) * u1[2], siluf_(g1[3]) * u1[3]);
;                     *(u32x4*)(ob + (size_t)row * FF + col0) = w;
	v_pk_mul_f32 v[152:153], v[102:103], v[148:149] op_sel_hi:[1,0]
	v_pk_mul_f32 v[150:151], v[104:105], v[148:149] op_sel_hi:[1,0]
	v_pk_mul_f32 v[154:155], v[72:73], v[148:149] op_sel_hi:[1,0]
	v_pk_mul_f32 v[156:157], v[70:71], v[148:149] op_sel_hi:[1,0]
	v_pk_mul_f32 v[158:159], v[100:101], v[148:149] op_sel_hi:[1,0]
	v_pk_mul_f32 v[160:161], v[98:99], v[148:149] op_sel_hi:[1,0]
	v_pk_mul_f32 v[162:163], v[68:69], v[148:149] op_sel_hi:[1,0]
	v_pk_mul_f32 v[164:165], v[66:67], v[148:149] op_sel_hi:[1,0]
	v_mul_f32_e32 v148, 0xbfb8aa3b, v152
	v_mul_f32_e32 v149, 0xbfb8aa3b, v153
	v_exp_f32_e32 v148, v148
	v_exp_f32_e32 v149, v149
	v_add_f32_e32 v148, 1.0, v148
	v_add_f32_e32 v149, 1.0, v149
	v_rcp_f32_e32 v148, v148
	v_rcp_f32_e32 v149, v149
	v_mul_f32_e32 v148, v152, v148
	v_mul_f32_e32 v149, v153, v149
	v_mul_f32_e32 v148, v156, v148
	v_mul_f32_e32 v149, v157, v149
	v_cvt_pk_bf16_f32 v148, v148, v149
	v_mul_f32_e32 v149, 0xbfb8aa3b, v150
	v_exp_f32_e32 v149, v149
	v_mul_f32_e32 v152, 0xbfb8aa3b, v159
	v_exp_f32_e32 v152, v152
	v_add_f32_e32 v149, 1.0, v149
	v_rcp_f32_e32 v149, v149
	v_add_f32_e32 v152, 1.0, v152
	v_rcp_f32_e32 v152, v152
	v_mul_f32_e32 v149, v150, v149
	v_mul_f32_e32 v150, 0xbfb8aa3b, v151
	v_exp_f32_e32 v150, v150
	v_mul_f32_e32 v149, v154, v149
	v_mul_f32_e32 v152, v159, v152
	v_mul_f32_e32 v152, v163, v152
	v_add_f32_e32 v150, 1.0, v150
	v_rcp_f32_e32 v150, v150
	s_nop 0
	v_mul_f32_e32 v150, v151, v150
	v_mul_f32_e32 v150, v155, v150
	v_cvt_pk_bf16_f32 v149, v149, v150
	v_mul_f32_e32 v150, 0xbfb8aa3b, v160
	v_mul_f32_e32 v151, 0xbfb8aa3b, v161
	v_exp_f32_e32 v150, v150
	v_exp_f32_e32 v151, v151
	v_add_f32_e32 v150, 1.0, v150
	v_add_f32_e32 v151, 1.0, v151
	v_rcp_f32_e32 v150, v150
	v_rcp_f32_e32 v151, v151
	v_mul_f32_e32 v150, v160, v150
	v_mul_f32_e32 v151, v161, v151
	v_mul_f32_e32 v150, v164, v150
	v_mul_f32_e32 v151, v165, v151
	v_cvt_pk_bf16_f32 v150, v150, v151
	v_mul_f32_e32 v151, 0xbfb8aa3b, v158
	v_exp_f32_e32 v151, v151
	s_nop 0
	v_add_f32_e32 v151, 1.0, v151
	v_rcp_f32_e32 v151, v151
	s_nop 0
	v_mul_f32_e32 v151, v158, v151
	v_mul_f32_e32 v151, v162, v151
	v_cvt_pk_bf16_f32 v151, v151, v152
	v_mad_i64_i32 v[152:153], s[4:5], v147, s33, v[136:137]
	v_lshl_add_u64 v[152:153], v[152:153], 0, v[138:139]
	global_store_dwordx4 v[152:153], v[148:151], off
	ds_read_b32 v148, v145 offset:512
	v_add_u32_e32 v147, 0x80, v146
	s_waitcnt lgkmcnt(0)
	v_pk_mul_f32 v[152:153], v[62:63], v[148:149] op_sel_hi:[1,0]
	v_pk_mul_f32 v[150:151], v[64:65], v[148:149] op_sel_hi:[1,0]
	v_pk_mul_f32 v[154:155], v[32:33], v[148:149] op_sel_hi:[1,0]
	v_pk_mul_f32 v[156:157], v[30:31], v[148:149] op_sel_hi:[1,0]
	v_pk_mul_f32 v[158:159], v[60:61], v[148:149] op_sel_hi:[1,0]
	v_pk_mul_f32 v[160:161], v[58:59], v[148:149] op_sel_hi:[1,0]
	v_pk_mul_f32 v[162:163], v[28:29], v[148:149] op_sel_hi:[1,0]
	v_pk_mul_f32 v[164:165], v[26:27], v[148:149] op_sel_hi:[1,0]
	v_mul_f32_e32 v148, 0xbfb8aa3b, v152
	v_mul_f32_e32 v149, 0xbfb8aa3b, v153
	v_exp_f32_e32 v148, v148
	v_exp_f32_e32 v149, v149
	v_add_f32_e32 v148, 1.0, v148
	v_add_f32_e32 v149, 1.0, v149
	v_rcp_f32_e32 v148, v148
	v_rcp_f32_e32 v149, v149
	v_mul_f32_e32 v148, v152, v148
	v_mul_f32_e32 v149, v153, v149
	v_mul_f32_e32 v148, v156, v148
	v_mul_f32_e32 v149, v157, v149
	v_cvt_pk_bf16_f32 v148, v148, v149
	v_mul_f32_e32 v149, 0xbfb8aa3b, v150
	v_exp_f32_e32 v149, v149
	v_mul_f32_e32 v152, 0xbfb8aa3b, v159
	v_exp_f32_e32 v152, v152
	v_add_f32_e32 v149, 1.0, v149
	v_rcp_f32_e32 v149, v149
	v_add_f32_e32 v152, 1.0, v152
	v_rcp_f32_e32 v152, v152
	v_mul_f32_e32 v149, v150, v149
	v_mul_f32_e32 v150, 0xbfb8aa3b, v151
	v_exp_f32_e32 v150, v150
	v_mul_f32_e32 v149, v154, v149
	v_mul_f32_e32 v152, v159, v152
	v_mul_f32_e32 v152, v163, v152
	v_add_f32_e32 v150, 1.0, v150
	v_rcp_f32_e32 v150, v150
	s_nop 0
	v_mul_f32_e32 v150, v151, v150
	v_mul_f32_e32 v150, v155, v150
	v_cvt_pk_bf16_f32 v149, v149, v150
	v_mul_f32_e32 v150, 0xbfb8aa3b, v160
	v_mul_f32_e32 v151, 0xbfb8aa3b, v161
	v_exp_f32_e32 v150, v150
	v_exp_f32_e32 v151, v151
	v_add_f32_e32 v150, 1.0, v150
	v_add_f32_e32 v151, 1.0, v151
	v_rcp_f32_e32 v150, v150
	v_rcp_f32_e32 v151, v151
	v_mul_f32_e32 v150, v160, v150
	v_mul_f32_e32 v151, v161, v151
	v_mul_f32_e32 v150, v164, v150
	v_mul_f32_e32 v151, v165, v151
	v_cvt_pk_bf16_f32 v150, v150, v151
	v_mul_f32_e32 v151, 0xbfb8aa3b, v158
	v_exp_f32_e32 v151, v151
	s_nop 0
	v_add_f32_e32 v151, 1.0, v151
	v_rcp_f32_e32 v151, v151
	s_nop 0
	v_mul_f32_e32 v151, v158, v151
	v_mul_f32_e32 v151, v162, v151
	v_cvt_pk_bf16_f32 v151, v151, v152
	v_mad_i64_i32 v[152:153], s[4:5], v147, s33, v[136:137]
	v_lshl_add_u64 v[152:153], v[152:153], 0, v[138:139]
	global_store_dwordx4 v[152:153], v[148:151], off
	ds_read_b32 v148, v145 offset:576
	v_add_u32_e32 v147, 0x90, v146
	s_waitcnt lgkmcnt(0)
; __device__ __forceinline__ unsigned pk2(float lo, float hi) { unsigned r; asm volatile("v_cvt_pk_bf16_f32 %0, %1, %2" : "=v"(r) : "v"(lo), "v"(hi)); return r; }
; __device__ __forceinline__ float siluf_(float x) { return x * __builtin_amdgcn_rcpf(1.0f + __expf(-x)); }
;     template <int mode> __device__ __forceinline__ void run(const f32x4 (&acc)[2][2][4][2], const Unit& u, int wr, int wc, int fr, int fq, const LAS float* sc) const {
;     ...
; #pragma unroll
;             for (int ai = 0; ai < 2; ++ai)
; #pragma unroll
;                 for (int m = 0; m < 4; ++m) {
;                     const int row = row0 + ai * HALF + m * 16;
;                     const float s = sc[ai * HALF + wr * 64 + m * 16 + fr];
;                     const f32x4 g0 = acc[ai][0][m][0] * s, u0 = acc[ai][1][m][0] * s, g1 = acc[ai][0][m][1] * s, u1 = acc[ai][1][m][1] * s;
;                     u32x4 w;
;                     w.x = pk2(siluf_(g0[0]) * u0[0], siluf_(g0[1]) * u0[1]); w.y = pk2(siluf_(g0[2]) * u0[2], siluf_(g0[3]) * u0[3]);
;                     w.z = pk2(siluf_(g1[0]) * u1[0], siluf_(g1[1]) * u1[1]); w.w = pk2(siluf_(g1[2]) * u1[2], siluf_(g1[3]) * u1[3]);
;                     *(u32x4*)(ob + (size_t)row * FF + col0) = w;
	v_pk_mul_f32 v[152:153], v[54:55], v[148:149] op_sel_hi:[1,0]
	v_pk_mul_f32 v[150:151], v[56:57], v[148:149] op_sel_hi:[1,0]
	v_pk_mul_f32 v[154:155], v[24:25], v[148:149] op_sel_hi:[1,0]
	v_pk_mul_f32 v[156:157], v[22:23], v[148:149] op_sel_hi:[1,0]
	v_pk_mul_f32 v[158:159], v[52:53], v[148:149] op_sel_hi:[1,0]
	v_pk_mul_f32 v[160:161], v[50:51], v[148:149] op_sel_hi:[1,0]
	v_pk_mul_f32 v[162:163], v[20:21], v[148:149] op_sel_hi:[1,0]
	v_pk_mul_f32 v[164:165], v[18:19], v[148:149] op_sel_hi:[1,0]
	v_mul_f32_e32 v148, 0xbfb8aa3b, v152
	v_mul_f32_e32 v149, 0xbfb8aa3b, v153
	v_exp_f32_e32 v148, v148
	v_exp_f32_e32 v149, v149
	v_add_f32_e32 v148, 1.0, v148
	v_add_f32_e32 v149, 1.0, v149
	v_rcp_f32_e32 v148, v148
	v_rcp_f32_e32 v149, v149
	v_mul_f32_e32 v148, v152, v148
	v_mul_f32_e32 v149, v153, v149
	v_mul_f32_e32 v148, v156, v148
	v_mul_f32_e32 v149, v157, v149
	v_cvt_pk_bf16_f32 v148, v148, v149
	v_mul_f32_e32 v149, 0xbfb8aa3b, v150
	v_exp_f32_e32 v149, v149
	v_mul_f32_e32 v152, 0xbfb8aa3b, v159
	v_exp_f32_e32 v152, v152
	v_add_f32_e32 v149, 1.0, v149
	v_rcp_f32_e32 v149, v149
	v_add_f32_e32 v152, 1.0, v152
	v_rcp_f32_e32 v152, v152
	v_mul_f32_e32 v149, v150, v149
	v_mul_f32_e32 v150, 0xbfb8aa3b, v151
	v_exp_f32_e32 v150, v150
	v_mul_f32_e32 v149, v154, v149
	v_mul_f32_e32 v152, v159, v152
	v_mul_f32_e32 v152, v163, v152
	v_add_f32_e32 v150, 1.0, v150
	v_rcp_f32_e32 v150, v150
	s_nop 0
	v_mul_f32_e32 v150, v151, v150
	v_mul_f32_e32 v150, v155, v150
	v_cvt_pk_bf16_f32 v149, v149, v150
	v_mul_f32_e32 v150, 0xbfb8aa3b, v160
	v_mul_f32_e32 v151, 0xbfb8aa3b, v161
	v_exp_f32_e32 v150, v150
	v_exp_f32_e32 v151, v151
	v_add_f32_e32 v150, 1.0, v150
	v_add_f32_e32 v151, 1.0, v151
	v_rcp_f32_e32 v150, v150
	v_rcp_f32_e32 v151, v151
	v_mul_f32_e32 v150, v160, v150
	v_mul_f32_e32 v151, v161, v151
	v_mul_f32_e32 v150, v164, v150
	v_mul_f32_e32 v151, v165, v151
	v_cvt_pk_bf16_f32 v150, v150, v151
	v_mul_f32_e32 v151, 0xbfb8aa3b, v158
	v_exp_f32_e32 v151, v151
	s_nop 0
	v_add_f32_e32 v151, 1.0, v151
	v_rcp_f32_e32 v151, v151
	s_nop 0
	v_mul_f32_e32 v151, v158, v151
	v_mul_f32_e32 v151, v162, v151
	v_cvt_pk_bf16_f32 v151, v151, v152
	v_mad_i64_i32 v[152:153], s[4:5], v147, s33, v[136:137]
	v_lshl_add_u64 v[152:153], v[152:153], 0, v[138:139]
	global_store_dwordx4 v[152:153], v[148:151], off
	ds_read_b32 v148, v145 offset:640
	v_add_u32_e32 v147, 0xa0, v146
	s_waitcnt lgkmcnt(0)
	v_pk_mul_f32 v[152:153], v[46:47], v[148:149] op_sel_hi:[1,0]
	v_pk_mul_f32 v[150:151], v[48:49], v[148:149] op_sel_hi:[1,0]
	v_pk_mul_f32 v[154:155], v[16:17], v[148:149] op_sel_hi:[1,0]
	v_pk_mul_f32 v[156:157], v[14:15], v[148:149] op_sel_hi:[1,0]
	v_pk_mul_f32 v[158:159], v[44:45], v[148:149] op_sel_hi:[1,0]
	v_pk_mul_f32 v[160:161], v[42:43], v[148:149] op_sel_hi:[1,0]
	v_pk_mul_f32 v[162:163], v[12:13], v[148:149] op_sel_hi:[1,0]
	v_pk_mul_f32 v[164:165], v[10:11], v[148:149] op_sel_hi:[1,0]
	v_mul_f32_e32 v148, 0xbfb8aa3b, v152
	v_mul_f32_e32 v149, 0xbfb8aa3b, v153
	v_exp_f32_e32 v148, v148
	v_exp_f32_e32 v149, v149
	v_add_f32_e32 v148, 1.0, v148
	v_add_f32_e32 v149, 1.0, v149
	v_rcp_f32_e32 v148, v148
	v_rcp_f32_e32 v149, v149
	v_mul_f32_e32 v148, v152, v148
	v_mul_f32_e32 v149, v153, v149
	v_mul_f32_e32 v148, v156, v148
	v_mul_f32_e32 v149, v157, v149
	v_cvt_pk_bf16_f32 v148, v148, v149
	v_mul_f32_e32 v149, 0xbfb8aa3b, v150
	v_exp_f32_e32 v149, v149
	v_mul_f32_e32 v152, 0xbfb8aa3b, v159
	v_exp_f32_e32 v152, v152
	v_add_f32_e32 v149, 1.0, v149
	v_rcp_f32_e32 v149, v149
	v_add_f32_e32 v152, 1.0, v152
	v_rcp_f32_e32 v152, v152
	v_mul_f32_e32 v149, v150, v149
	v_mul_f32_e32 v150, 0xbfb8aa3b, v151
	v_exp_f32_e32 v150, v150
	v_mul_f32_e32 v149, v154, v149
	v_mul_f32_e32 v152, v159, v152
	v_mul_f32_e32 v152, v163, v152
	v_add_f32_e32 v150, 1.0, v150
	v_rcp_f32_e32 v150, v150
	s_nop 0
	v_mul_f32_e32 v150, v151, v150
	v_mul_f32_e32 v150, v155, v150
	v_cvt_pk_bf16_f32 v149, v149, v150
	v_mul_f32_e32 v150, 0xbfb8aa3b, v160
	v_mul_f32_e32 v151, 0xbfb8aa3b, v161
	v_exp_f32_e32 v150, v150
	v_exp_f32_e32 v151, v151
	v_add_f32_e32 v150, 1.0, v150
	v_add_f32_e32 v151, 1.0, v151
	v_rcp_f32_e32 v150, v150
	v_rcp_f32_e32 v151, v151
	v_mul_f32_e32 v150, v160, v150
	v_mul_f32_e32 v151, v161, v151
	v_mul_f32_e32 v150, v164, v150
	v_mul_f32_e32 v151, v165, v151
	v_cvt_pk_bf16_f32 v150, v150, v151
	v_mul_f32_e32 v151, 0xbfb8aa3b, v158
	v_exp_f32_e32 v151, v151
	v_add_u32_e32 v164, 0xb0, v146
	v_add_f32_e32 v151, 1.0, v151
	v_rcp_f32_e32 v151, v151
	s_nop 0
	v_mul_f32_e32 v151, v158, v151
	v_mul_f32_e32 v151, v162, v151
	v_cvt_pk_bf16_f32 v151, v151, v152
	ds_read_b32 v146, v145 offset:704
	v_mad_i64_i32 v[152:153], s[4:5], v147, s33, v[136:137]
	v_lshl_add_u64 v[152:153], v[152:153], 0, v[138:139]
	global_store_dwordx4 v[152:153], v[148:151], off
	s_waitcnt lgkmcnt(0)
; __device__ __forceinline__ unsigned pk2(float lo, float hi) { unsigned r; asm volatile("v_cvt_pk_bf16_f32 %0, %1, %2" : "=v"(r) : "v"(lo), "v"(hi)); return r; }
; __device__ __forceinline__ float siluf_(float x) { return x * __builtin_amdgcn_rcpf(1.0f + __expf(-x)); }
;     template <int mode> __device__ __forceinline__ void run(const f32x4 (&acc)[2][2][4][2], const Unit& u, int wr, int wc, int fr, int fq, const LAS float* sc) const {
;     ...
; #pragma unroll
;             for (int ai = 0; ai < 2; ++ai)
; #pragma unroll
;                 for (int m = 0; m < 4; ++m) {
;                     const int row = row0 + ai * HALF + m * 16;
;                     const float s = sc[ai * HALF + wr * 64 + m * 16 + fr];
;                     const f32x4 g0 = acc[ai][0][m][0] * s, u0 = acc[ai][1][m][0] * s, g1 = acc[ai][0][m][1] * s, u1 = acc[ai][1][m][1] * s;
;                     u32x4 w;
;                     w.x = pk2(siluf_(g0[0]) * u0[0], siluf_(g0[1]) * u0[1]); w.y = pk2(siluf_(g0[2]) * u0[2], siluf_(g0[3]) * u0[3]);
;                     w.z = pk2(siluf_(g1[0]) * u1[0], siluf_(g1[1]) * u1[1]); w.w = pk2(siluf_(g1[2]) * u1[2], siluf_(g1[3]) * u1[3]);
;                     *(u32x4*)(ob + (size_t)row * FF + col0) = w;
; template <int MODE, class EpiT, class Sched>
; __device__ __forceinline__ void gemm_phase(LAS unsigned char* lds, const Gemm g, const Sched& S, const EpiT& E) {
;     ...
;         if (!has_next) break;
; #pragma unroll
;         for (int a = 0; a < 2; ++a)
; #pragma unroll
;             for (int b = 0; b < 2; ++b)
; #pragma unroll
;                 for (int m = 0; m < 4; ++m)
; #pragma unroll
;                     for (int n = 0; n < 2; ++n) acc[a][b][m][n] = (f32x4){0.f, 0.f, 0.f, 0.f};
;         cur = nxt; cA = nA; cB = nB; ++ui;
	v_pk_mul_f32 v[152:153], v[8:9], v[146:147] op_sel_hi:[1,0]
	v_pk_mul_f32 v[154:155], v[6:7], v[146:147] op_sel_hi:[1,0]
	v_pk_mul_f32 v[150:151], v[38:39], v[146:147] op_sel_hi:[1,0]
	v_pk_mul_f32 v[148:149], v[40:41], v[146:147] op_sel_hi:[1,0]
	v_pk_mul_f32 v[156:157], v[36:37], v[146:147] op_sel_hi:[1,0]
	v_pk_mul_f32 v[158:159], v[34:35], v[146:147] op_sel_hi:[1,0]
	v_pk_mul_f32 v[160:161], v[4:5], v[146:147] op_sel_hi:[1,0]
	v_pk_mul_f32 v[162:163], v[2:3], v[146:147] op_sel_hi:[1,0]
	v_mul_f32_e32 v145, 0xbfb8aa3b, v150
	v_mul_f32_e32 v146, 0xbfb8aa3b, v151
	v_exp_f32_e32 v145, v145
	v_exp_f32_e32 v146, v146
	v_mul_f32_e32 v147, 0xbfb8aa3b, v149
	v_exp_f32_e32 v147, v147
	v_add_f32_e32 v145, 1.0, v145
	v_add_f32_e32 v146, 1.0, v146
	v_rcp_f32_e32 v145, v145
	v_rcp_f32_e32 v146, v146
	v_add_f32_e32 v147, 1.0, v147
	v_rcp_f32_e32 v147, v147
	v_mul_f32_e32 v145, v150, v145
	v_mul_f32_e32 v146, v151, v146
	v_mul_f32_e32 v145, v154, v145
	v_mul_f32_e32 v146, v155, v146
	v_cvt_pk_bf16_f32 v146, v145, v146
	v_mul_f32_e32 v145, 0xbfb8aa3b, v148
	v_exp_f32_e32 v145, v145
	v_mul_f32_e32 v147, v149, v147
	v_mul_f32_e32 v147, v153, v147
	v_mul_f32_e32 v149, 0xbfb8aa3b, v157
	v_add_f32_e32 v145, 1.0, v145
	v_rcp_f32_e32 v145, v145
	v_exp_f32_e32 v149, v149
	v_mad_i64_i32 v[136:137], s[4:5], v164, s33, v[136:137]
	v_mul_f32_e32 v145, v148, v145
	v_mul_f32_e32 v145, v152, v145
	v_cvt_pk_bf16_f32 v147, v145, v147
	v_mul_f32_e32 v145, 0xbfb8aa3b, v158
	v_mul_f32_e32 v148, 0xbfb8aa3b, v159
	v_exp_f32_e32 v145, v145
	v_exp_f32_e32 v148, v148
	v_add_f32_e32 v149, 1.0, v149
	v_rcp_f32_e32 v149, v149
	v_add_f32_e32 v145, 1.0, v145
	v_add_f32_e32 v148, 1.0, v148
	v_rcp_f32_e32 v145, v145
	v_rcp_f32_e32 v148, v148
	v_mul_f32_e32 v149, v157, v149
	v_mul_f32_e32 v149, v161, v149
	v_mul_f32_e32 v145, v158, v145
	v_mul_f32_e32 v148, v159, v148
	v_mul_f32_e32 v145, v162, v145
	v_mul_f32_e32 v148, v163, v148
	v_cvt_pk_bf16_f32 v148, v145, v148
	v_mul_f32_e32 v145, 0xbfb8aa3b, v156
	v_exp_f32_e32 v145, v145
	v_lshl_add_u64 v[136:137], v[136:137], 0, v[138:139]
	v_add_f32_e32 v145, 1.0, v145
	v_rcp_f32_e32 v145, v145
	s_nop 0
	v_mul_f32_e32 v145, v156, v145
	v_mul_f32_e32 v145, v160, v145
	v_cvt_pk_bf16_f32 v149, v145, v149
	global_store_dwordx4 v[136:137], v[146:149], off
	s_cbranch_vccnz .LBB0_324
	v_mov_b32_e32 v2, 0
	s_mov_b32 s9, s61
	s_mov_b32 s8, s60
	s_mov_b64 s[12:13], s[28:29]
	s_mov_b64 s[10:11], s[34:35]
	s_mov_b32 s57, s2
	v_mov_b32_e32 v3, v2
	v_mov_b32_e32 v4, v2
	v_mov_b32_e32 v5, v2
	v_mov_b32_e32 v6, v2
	v_mov_b32_e32 v7, v2
	v_mov_b32_e32 v8, v2
	v_mov_b32_e32 v9, v2
	v_mov_b32_e32 v10, v2
	v_mov_b32_e32 v11, v2
	v_mov_b32_e32 v12, v2
	v_mov_b32_e32 v13, v2
	v_mov_b32_e32 v14, v2
	v_mov_b32_e32 v15, v2
	v_mov_b32_e32 v16, v2
	v_mov_b32_e32 v17, v2
	v_mov_b32_e32 v18, v2
	v_mov_b32_e32 v19, v2
	v_mov_b32_e32 v20, v2
	v_mov_b32_e32 v21, v2
	v_mov_b32_e32 v22, v2
	v_mov_b32_e32 v23, v2
	v_mov_b32_e32 v24, v2
	v_mov_b32_e32 v25, v2
	v_mov_b32_e32 v26, v2
	v_mov_b32_e32 v27, v2
	v_mov_b32_e32 v28, v2
	v_mov_b32_e32 v29, v2
	v_mov_b32_e32 v30, v2
	v_mov_b32_e32 v31, v2
	v_mov_b32_e32 v32, v2
	v_mov_b32_e32 v33, v2
	v_mov_b32_e32 v34, v2
	v_mov_b32_e32 v35, v2
	v_mov_b32_e32 v36, v2
	v_mov_b32_e32 v37, v2
	v_mov_b32_e32 v38, v2
	v_mov_b32_e32 v39, v2
	v_mov_b32_e32 v40, v2
	v_mov_b32_e32 v41, v2
	v_mov_b32_e32 v42, v2
	v_mov_b32_e32 v43, v2
	v_mov_b32_e32 v44, v2
	v_mov_b32_e32 v45, v2
	v_mov_b32_e32 v46, v2
	v_mov_b32_e32 v47, v2
	v_mov_b32_e32 v48, v2
	v_mov_b32_e32 v49, v2
	v_mov_b32_e32 v50, v2
	v_mov_b32_e32 v51, v2
	v_mov_b32_e32 v52, v2
	v_mov_b32_e32 v53, v2
	v_mov_b32_e32 v54, v2
	v_mov_b32_e32 v55, v2
	v_mov_b32_e32 v56, v2
	v_mov_b32_e32 v57, v2
	v_mov_b32_e32 v58, v2
	v_mov_b32_e32 v59, v2
	v_mov_b32_e32 v60, v2
	v_mov_b32_e32 v61, v2
	v_mov_b32_e32 v62, v2
	v_mov_b32_e32 v63, v2
	v_mov_b32_e32 v64, v2
	v_mov_b32_e32 v65, v2
	v_mov_b32_e32 v66, v2
	v_mov_b32_e32 v67, v2
	v_mov_b32_e32 v68, v2
	v_mov_b32_e32 v69, v2
	v_mov_b32_e32 v70, v2
	v_mov_b32_e32 v71, v2
	v_mov_b32_e32 v72, v2
	v_mov_b32_e32 v73, v2
	v_mov_b32_e32 v74, v2
	v_mov_b32_e32 v75, v2
	v_mov_b32_e32 v76, v2
	v_mov_b32_e32 v77, v2
	v_mov_b32_e32 v78, v2
	v_mov_b32_e32 v79, v2
	v_mov_b32_e32 v80, v2
	v_mov_b32_e32 v81, v2
	v_mov_b32_e32 v82, v2
	v_mov_b32_e32 v83, v2
	v_mov_b32_e32 v84, v2
	v_mov_b32_e32 v85, v2
	v_mov_b32_e32 v86, v2
	v_mov_b32_e32 v87, v2
	v_mov_b32_e32 v88, v2
	v_mov_b32_e32 v89, v2
	v_mov_b32_e32 v90, v2
	v_mov_b32_e32 v91, v2
	v_mov_b32_e32 v92, v2
	v_mov_b32_e32 v93, v2
	v_mov_b32_e32 v94, v2
	v_mov_b32_e32 v95, v2
	v_mov_b32_e32 v96, v2
	v_mov_b32_e32 v97, v2
	v_mov_b32_e32 v98, v2
	v_mov_b32_e32 v99, v2
	v_mov_b32_e32 v100, v2
	v_mov_b32_e32 v101, v2
	v_mov_b32_e32 v102, v2
	v_mov_b32_e32 v103, v2
	v_mov_b32_e32 v104, v2
	v_mov_b32_e32 v105, v2
	v_mov_b32_e32 v106, v2
	v_mov_b32_e32 v107, v2
	v_mov_b32_e32 v108, v2
	v_mov_b32_e32 v109, v2
	v_mov_b32_e32 v110, v2
	v_mov_b32_e32 v111, v2
	v_mov_b32_e32 v112, v2
	v_mov_b32_e32 v113, v2
	v_mov_b32_e32 v114, v2
	v_mov_b32_e32 v115, v2
	v_mov_b32_e32 v116, v2
	v_mov_b32_e32 v117, v2
	v_mov_b32_e32 v118, v2
	v_mov_b32_e32 v119, v2
	v_mov_b32_e32 v120, v2
	v_mov_b32_e32 v121, v2
	v_mov_b32_e32 v122, v2
	v_mov_b32_e32 v123, v2
	v_mov_b32_e32 v124, v2
	v_mov_b32_e32 v125, v2
	v_mov_b32_e32 v126, v2
	v_mov_b32_e32 v127, v2
	v_mov_b32_e32 v128, v2
	v_mov_b32_e32 v129, v2
	s_branch .LBB0_324
